# weight-prep tile loops: 32 loads in flight instead of load-wait-write serialisation (16 simple instances); scan wave 7 prefetch deepened
# speedup vs baseline: 1.0267x; 1.0267x over previous
; #define LAS __attribute__((address_space(3)))
; template <class Fn>
; __device__ __forceinline__ void prep_mat(bf16_t* dst, int NR, int KC, int ldd, const Fn f, int& gw, int NGW, LAS float* scr, int lane) {
;     const int nnb = NR / 32, ntile = nnb * (KC / 64);
;     const int gw0 = gw; gw = (gw0 + NGW - ntile % NGW) % NGW;
;     for (int it = gw0; it < ntile; it += NGW) {
;         const int nb = it % nnb, kb = it / nnb, n0 = 32 * nb, k0 = 64 * kb;
; #pragma unroll 4
;         for (int i = 0; i < 32; ++i) { const int kk = 2 * i + (lane >> 5); scr[kk * 33 + (lane & 31)] = f(n0 + (lane & 31), k0 + kk); }
; __device__ __forceinline__ void prep_hybrid(const float* w_in, const float* w_out, const float* pool_w, const float* pool_scale, bf16_t* WIN, bf16_t* WOUT, int gw, int NGW, LAS float* scr, int lane) {
;     prep_mat(WIN, NPROJ, D, D, [=](int n, int k) -> float {
;         const int src = n < 1024 ? headperm(n) : (n < 2048 ? n : n + 8);
;         return w_in[(size_t)k * INC + src]; }, gw, NGW, scr, lane);
.LBB0_35:
	v_lshl_add_u64 v[24:25], v[10:11], 0, s[8:9]
	global_load_dword v40, v[24:25], off
	v_lshl_add_u64 v[24:25], v[8:9], 0, s[8:9]
	global_load_dword v41, v[24:25], off
	v_lshl_add_u64 v[24:25], v[6:7], 0, s[8:9]
	s_add_u32 s8, s8, 0x14100
	s_addc_u32 s9, s9, 0
	s_cmp_eq_u32 s8, 0xa0800
	global_load_dword v42, v[24:25], off
	v_mad_i64_i32 v[24:25], s[38:39], v22, s31, v[4:5]
	v_add_u32_e32 v22, 8, v22
	global_load_dword v43, v[24:25], off
	v_lshl_add_u64 v[24:25], v[10:11], 0, s[8:9]
	global_load_dword v44, v[24:25], off
	v_lshl_add_u64 v[24:25], v[8:9], 0, s[8:9]
	global_load_dword v45, v[24:25], off
	v_lshl_add_u64 v[24:25], v[6:7], 0, s[8:9]
	s_add_u32 s8, s8, 0x14100
	s_addc_u32 s9, s9, 0
	s_cmp_eq_u32 s8, 0xa0800
	global_load_dword v46, v[24:25], off
	v_mad_i64_i32 v[24:25], s[38:39], v22, s31, v[4:5]
	v_add_u32_e32 v22, 8, v22
	global_load_dword v47, v[24:25], off
	v_lshl_add_u64 v[24:25], v[10:11], 0, s[8:9]
	global_load_dword v48, v[24:25], off
	v_lshl_add_u64 v[24:25], v[8:9], 0, s[8:9]
	global_load_dword v49, v[24:25], off
	v_lshl_add_u64 v[24:25], v[6:7], 0, s[8:9]
	s_add_u32 s8, s8, 0x14100
	s_addc_u32 s9, s9, 0
	s_cmp_eq_u32 s8, 0xa0800
	global_load_dword v50, v[24:25], off
	v_mad_i64_i32 v[24:25], s[38:39], v22, s31, v[4:5]
	v_add_u32_e32 v22, 8, v22
	global_load_dword v51, v[24:25], off
	v_lshl_add_u64 v[24:25], v[10:11], 0, s[8:9]
	global_load_dword v52, v[24:25], off
	v_lshl_add_u64 v[24:25], v[8:9], 0, s[8:9]
	global_load_dword v53, v[24:25], off
	v_lshl_add_u64 v[24:25], v[6:7], 0, s[8:9]
	s_add_u32 s8, s8, 0x14100
	s_addc_u32 s9, s9, 0
	s_cmp_eq_u32 s8, 0xa0800
	global_load_dword v54, v[24:25], off
	v_mad_i64_i32 v[24:25], s[38:39], v22, s31, v[4:5]
	v_add_u32_e32 v22, 8, v22
	global_load_dword v55, v[24:25], off
	v_lshl_add_u64 v[24:25], v[10:11], 0, s[8:9]
	global_load_dword v56, v[24:25], off
	v_lshl_add_u64 v[24:25], v[8:9], 0, s[8:9]
	global_load_dword v57, v[24:25], off
	v_lshl_add_u64 v[24:25], v[6:7], 0, s[8:9]
	s_add_u32 s8, s8, 0x14100
	s_addc_u32 s9, s9, 0
	s_cmp_eq_u32 s8, 0xa0800
	global_load_dword v58, v[24:25], off
	v_mad_i64_i32 v[24:25], s[38:39], v22, s31, v[4:5]
	v_add_u32_e32 v22, 8, v22
	global_load_dword v59, v[24:25], off
	v_lshl_add_u64 v[24:25], v[10:11], 0, s[8:9]
	global_load_dword v60, v[24:25], off
	v_lshl_add_u64 v[24:25], v[8:9], 0, s[8:9]
	global_load_dword v61, v[24:25], off
	v_lshl_add_u64 v[24:25], v[6:7], 0, s[8:9]
	s_add_u32 s8, s8, 0x14100
	s_addc_u32 s9, s9, 0
	s_cmp_eq_u32 s8, 0xa0800
	global_load_dword v62, v[24:25], off
	v_mad_i64_i32 v[24:25], s[38:39], v22, s31, v[4:5]
	v_add_u32_e32 v22, 8, v22
	global_load_dword v63, v[24:25], off
	v_lshl_add_u64 v[24:25], v[10:11], 0, s[8:9]
	global_load_dword v64, v[24:25], off
	v_lshl_add_u64 v[24:25], v[8:9], 0, s[8:9]
	global_load_dword v66, v[24:25], off
	v_lshl_add_u64 v[24:25], v[6:7], 0, s[8:9]
	s_add_u32 s8, s8, 0x14100
	s_addc_u32 s9, s9, 0
	s_cmp_eq_u32 s8, 0xa0800
	global_load_dword v67, v[24:25], off
	v_mad_i64_i32 v[24:25], s[38:39], v22, s31, v[4:5]
	v_add_u32_e32 v22, 8, v22
	global_load_dword v68, v[24:25], off
	v_lshl_add_u64 v[24:25], v[10:11], 0, s[8:9]
	global_load_dword v69, v[24:25], off
	v_lshl_add_u64 v[24:25], v[8:9], 0, s[8:9]
	global_load_dword v70, v[24:25], off
	v_lshl_add_u64 v[24:25], v[6:7], 0, s[8:9]
	s_add_u32 s8, s8, 0x14100
	s_addc_u32 s9, s9, 0
	s_cmp_eq_u32 s8, 0xa0800
	global_load_dword v71, v[24:25], off
	v_mad_i64_i32 v[24:25], s[38:39], v22, s31, v[4:5]
	v_add_u32_e32 v22, 8, v22
	global_load_dword v72, v[24:25], off
	s_waitcnt vmcnt(31)
	ds_write_b32 v23, v40
	s_waitcnt vmcnt(30)
	ds_write_b32 v23, v41 offset:264
	s_waitcnt vmcnt(29)
	ds_write_b32 v23, v42 offset:528
	s_waitcnt vmcnt(28)
	ds_write_b32 v23, v43 offset:792
	s_waitcnt vmcnt(27)
	ds_write_b32 v23, v44 offset:1056
	s_waitcnt vmcnt(26)
	ds_write_b32 v23, v45 offset:1320
	s_waitcnt vmcnt(25)
; #define LAS __attribute__((address_space(3)))
; #define GAS __attribute__((address_space(1)))
; __device__ __forceinline__ unsigned cvt_pk_bf16(float lo, float hi) { const f32x2 v = {lo, hi}; return __builtin_bit_cast(unsigned, __builtin_convertvector(v, b16x2_t)); }
; #define LDS_WAIT() asm volatile("s_waitcnt lgkmcnt(0)" ::: "memory")
; template <class Fn>
; __device__ __forceinline__ void prep_mat(bf16_t* dst, int NR, int KC, int ldd, const Fn f, int& gw, int NGW, LAS float* scr, int lane) {
;     ...
;         for (int i = 0; i < 32; ++i) { const int kk = 2 * i + (lane >> 5); scr[kk * 33 + (lane & 31)] = f(n0 + (lane & 31), k0 + kk); }
;         LDS_WAIT(); asm volatile("" ::: "memory");
;         const int c = lane & 7;
; #pragma unroll
;         for (int j = 0; j < 4; ++j) { const int n = (lane >> 3) + 8 * j; const LAS float* s = scr + (8 * c) * 33 + n;
;             u32x4 o; o.x = cvt_pk_bf16(s[0 * 33], s[1 * 33]); o.y = cvt_pk_bf16(s[2 * 33], s[3 * 33]); o.z = cvt_pk_bf16(s[4 * 33], s[5 * 33]); o.w = cvt_pk_bf16(s[6 * 33], s[7 * 33]);
;             *(GAS u32x4*)(dst + (size_t)(n0 + n) * ldd + k0 + 8 * c) = o; }
;         LDS_WAIT(); asm volatile("" ::: "memory");
;     }
	ds_write_b32 v23, v46 offset:1584
	s_waitcnt vmcnt(24)
	ds_write_b32 v23, v47 offset:1848
	s_waitcnt vmcnt(23)
	ds_write_b32 v23, v48 offset:2112
	s_waitcnt vmcnt(22)
	ds_write_b32 v23, v49 offset:2376
	s_waitcnt vmcnt(21)
	ds_write_b32 v23, v50 offset:2640
	s_waitcnt vmcnt(20)
	ds_write_b32 v23, v51 offset:2904
	s_waitcnt vmcnt(19)
	ds_write_b32 v23, v52 offset:3168
	s_waitcnt vmcnt(18)
	ds_write_b32 v23, v53 offset:3432
	s_waitcnt vmcnt(17)
	ds_write_b32 v23, v54 offset:3696
	s_waitcnt vmcnt(16)
	ds_write_b32 v23, v55 offset:3960
	s_waitcnt vmcnt(15)
	ds_write_b32 v23, v56 offset:4224
	s_waitcnt vmcnt(14)
	ds_write_b32 v23, v57 offset:4488
	s_waitcnt vmcnt(13)
	ds_write_b32 v23, v58 offset:4752
	s_waitcnt vmcnt(12)
	ds_write_b32 v23, v59 offset:5016
	s_waitcnt vmcnt(11)
	ds_write_b32 v23, v60 offset:5280
	s_waitcnt vmcnt(10)
	ds_write_b32 v23, v61 offset:5544
	s_waitcnt vmcnt(9)
	ds_write_b32 v23, v62 offset:5808
	s_waitcnt vmcnt(8)
	ds_write_b32 v23, v63 offset:6072
	s_waitcnt vmcnt(7)
	ds_write_b32 v23, v64 offset:6336
	s_waitcnt vmcnt(6)
	ds_write_b32 v23, v66 offset:6600
	s_waitcnt vmcnt(5)
	ds_write_b32 v23, v67 offset:6864
	s_waitcnt vmcnt(4)
	ds_write_b32 v23, v68 offset:7128
	s_waitcnt vmcnt(3)
	ds_write_b32 v23, v69 offset:7392
	s_waitcnt vmcnt(2)
	ds_write_b32 v23, v70 offset:7656
	s_waitcnt vmcnt(1)
	ds_write_b32 v23, v71 offset:7920
	s_waitcnt vmcnt(0)
	ds_write_b32 v23, v72 offset:8184
	v_add_u32_e32 v23, 0x2100, v23
	s_waitcnt lgkmcnt(0)
	ds_read2_b32 v[8:9], v12 offset0:33 offset1:41
	ds_read2_b32 v[10:11], v12 offset1:8
	ds_read2_b32 v[22:23], v12 offset0:66 offset1:74
	ds_read2_b32 v[24:25], v12 offset0:99 offset1:107
	ds_read2_b32 v[26:27], v12 offset0:132 offset1:140
	ds_read2_b32 v[28:29], v12 offset0:165 offset1:173
	ds_read2_b32 v[30:31], v12 offset0:198 offset1:206
	ds_read2_b32 v[32:33], v12 offset0:231 offset1:239
	v_add_u32_e32 v36, s35, v15
	v_ashrrev_i32_e32 v37, 31, v36
	v_lshl_add_u64 v[34:35], s[6:7], 1, v[2:3]
	v_lshlrev_b64 v[38:39], 11, v[36:37]
	s_waitcnt lgkmcnt(6)
	v_cvt_pk_bf16_f32 v4, v10, v8
	s_waitcnt lgkmcnt(4)
	v_cvt_pk_bf16_f32 v5, v22, v24
	s_waitcnt lgkmcnt(2)
	v_cvt_pk_bf16_f32 v6, v26, v28
	s_waitcnt lgkmcnt(0)
	v_cvt_pk_bf16_f32 v7, v30, v32
	v_lshl_add_u64 v[38:39], v[34:35], 0, v[38:39]
	v_add_u32_e32 v8, 8, v36
	global_store_dwordx4 v[38:39], v[4:7], off
	s_add_i32 s34, s34, s18
	s_cmpk_gt_i32 s34, 0x4ff
	v_cvt_pk_bf16_f32 v4, v11, v9
	v_ashrrev_i32_e32 v9, 31, v8
	v_cvt_pk_bf16_f32 v5, v23, v25
	v_cvt_pk_bf16_f32 v6, v27, v29
	v_cvt_pk_bf16_f32 v7, v31, v33
	v_lshlrev_b64 v[8:9], 11, v[8:9]
	ds_read2_b32 v[10:11], v12 offset0:49 offset1:57
	ds_read2_b32 v[22:23], v12 offset0:16 offset1:24
	ds_read2_b32 v[24:25], v12 offset0:82 offset1:90
	ds_read2_b32 v[26:27], v12 offset0:115 offset1:123
	ds_read2_b32 v[28:29], v12 offset0:148 offset1:156
	ds_read2_b32 v[30:31], v12 offset0:181 offset1:189
	ds_read2_b32 v[32:33], v12 offset0:214 offset1:222
	ds_read2_b32 v[38:39], v12 offset0:247 offset1:255
	v_lshl_add_u64 v[8:9], v[34:35], 0, v[8:9]
	global_store_dwordx4 v[8:9], v[4:7], off
	v_add_u32_e32 v8, 16, v36
	v_ashrrev_i32_e32 v9, 31, v8
	v_lshlrev_b64 v[8:9], 11, v[8:9]
	s_waitcnt lgkmcnt(6)
	v_cvt_pk_bf16_f32 v4, v22, v10
	s_waitcnt lgkmcnt(4)
	v_cvt_pk_bf16_f32 v5, v24, v26
	s_waitcnt lgkmcnt(2)
	v_cvt_pk_bf16_f32 v6, v28, v30
	s_waitcnt lgkmcnt(0)
	v_cvt_pk_bf16_f32 v7, v32, v38
	v_lshl_add_u64 v[8:9], v[34:35], 0, v[8:9]
	global_store_dwordx4 v[8:9], v[4:7], off
	v_add_u32_e32 v8, 24, v36
	v_ashrrev_i32_e32 v9, 31, v8
	v_lshlrev_b64 v[8:9], 11, v[8:9]
	v_cvt_pk_bf16_f32 v4, v23, v11
	v_cvt_pk_bf16_f32 v5, v25, v27
	v_cvt_pk_bf16_f32 v6, v29, v31
	v_cvt_pk_bf16_f32 v7, v33, v39
	v_lshl_add_u64 v[8:9], v[34:35], 0, v[8:9]
	global_store_dwordx4 v[8:9], v[4:7], off
	s_waitcnt lgkmcnt(0)
	s_cbranch_scc0 .LBB0_34

; #define LAS __attribute__((address_space(3)))
; template <class Fn>
; __device__ __forceinline__ void prep_mat(bf16_t* dst, int NR, int KC, int ldd, const Fn f, int& gw, int NGW, LAS float* scr, int lane) {
;     const int nnb = NR / 32, ntile = nnb * (KC / 64);
;     const int gw0 = gw; gw = (gw0 + NGW - ntile % NGW) % NGW;
;     for (int it = gw0; it < ntile; it += NGW) {
;         const int nb = it % nnb, kb = it / nnb, n0 = 32 * nb, k0 = 64 * kb;
; #pragma unroll 4
;         for (int i = 0; i < 32; ++i) { const int kk = 2 * i + (lane >> 5); scr[kk * 33 + (lane & 31)] = f(n0 + (lane & 31), k0 + kk); }
; __device__ __forceinline__ void prep_hybrid(const float* w_in, const float* w_out, const float* pool_w, const float* pool_scale, bf16_t* WIN, bf16_t* WOUT, int gw, int NGW, LAS float* scr, int lane) {
;     ...
;     prep_mat(WOUT, D, 512, D, [=](int n, int k) -> float { return w_out[(size_t)k * D + n]; }, gw, NGW, scr, lane);
.LBB0_40:
	v_lshl_add_u64 v[24:25], v[12:13], 0, s[8:9]
	global_load_dword v73, v[24:25], off
	v_lshl_add_u64 v[24:25], v[10:11], 0, s[8:9]
	global_load_dword v74, v[24:25], off
	v_lshl_add_u64 v[24:25], v[8:9], 0, s[8:9]
	s_add_u32 s8, s8, 0x8000
	s_addc_u32 s9, s9, 0
	s_cmp_eq_u32 s8, 0x40000
	global_load_dword v75, v[24:25], off
	v_ashrrev_i32_e32 v7, 31, v6
	v_lshlrev_b64 v[24:25], 12, v[6:7]
	v_lshl_add_u64 v[24:25], v[4:5], 0, v[24:25]
	v_add_u32_e32 v6, 8, v6
	global_load_dword v76, v[24:25], off
	v_lshl_add_u64 v[24:25], v[12:13], 0, s[8:9]
	global_load_dword v77, v[24:25], off
	v_lshl_add_u64 v[24:25], v[10:11], 0, s[8:9]
	global_load_dword v78, v[24:25], off
	v_lshl_add_u64 v[24:25], v[8:9], 0, s[8:9]
	s_add_u32 s8, s8, 0x8000
	s_addc_u32 s9, s9, 0
	s_cmp_eq_u32 s8, 0x40000
	global_load_dword v79, v[24:25], off
	v_ashrrev_i32_e32 v7, 31, v6
	v_lshlrev_b64 v[24:25], 12, v[6:7]
	v_lshl_add_u64 v[24:25], v[4:5], 0, v[24:25]
	v_add_u32_e32 v6, 8, v6
	global_load_dword v80, v[24:25], off
	v_lshl_add_u64 v[24:25], v[12:13], 0, s[8:9]
	global_load_dword v81, v[24:25], off
	v_lshl_add_u64 v[24:25], v[10:11], 0, s[8:9]
	global_load_dword v82, v[24:25], off
	v_lshl_add_u64 v[24:25], v[8:9], 0, s[8:9]
	s_add_u32 s8, s8, 0x8000
	s_addc_u32 s9, s9, 0
	s_cmp_eq_u32 s8, 0x40000
	global_load_dword v83, v[24:25], off
	v_ashrrev_i32_e32 v7, 31, v6
	v_lshlrev_b64 v[24:25], 12, v[6:7]
	v_lshl_add_u64 v[24:25], v[4:5], 0, v[24:25]
	v_add_u32_e32 v6, 8, v6
	global_load_dword v84, v[24:25], off
	v_lshl_add_u64 v[24:25], v[12:13], 0, s[8:9]
	global_load_dword v85, v[24:25], off
	v_lshl_add_u64 v[24:25], v[10:11], 0, s[8:9]
	global_load_dword v86, v[24:25], off
	v_lshl_add_u64 v[24:25], v[8:9], 0, s[8:9]
	s_add_u32 s8, s8, 0x8000
	s_addc_u32 s9, s9, 0
	s_cmp_eq_u32 s8, 0x40000
	global_load_dword v87, v[24:25], off
	v_ashrrev_i32_e32 v7, 31, v6
	v_lshlrev_b64 v[24:25], 12, v[6:7]
	v_lshl_add_u64 v[24:25], v[4:5], 0, v[24:25]
	v_add_u32_e32 v6, 8, v6
	global_load_dword v90, v[24:25], off
	v_lshl_add_u64 v[24:25], v[12:13], 0, s[8:9]
	global_load_dword v91, v[24:25], off
	v_lshl_add_u64 v[24:25], v[10:11], 0, s[8:9]
	global_load_dword v92, v[24:25], off
	v_lshl_add_u64 v[24:25], v[8:9], 0, s[8:9]
	s_add_u32 s8, s8, 0x8000
	s_addc_u32 s9, s9, 0
	s_cmp_eq_u32 s8, 0x40000
	global_load_dword v93, v[24:25], off
	v_ashrrev_i32_e32 v7, 31, v6
	v_lshlrev_b64 v[24:25], 12, v[6:7]
	v_lshl_add_u64 v[24:25], v[4:5], 0, v[24:25]
	v_add_u32_e32 v6, 8, v6
	global_load_dword v94, v[24:25], off
	v_lshl_add_u64 v[24:25], v[12:13], 0, s[8:9]
	global_load_dword v95, v[24:25], off
	v_lshl_add_u64 v[24:25], v[10:11], 0, s[8:9]
	global_load_dword v96, v[24:25], off
	v_lshl_add_u64 v[24:25], v[8:9], 0, s[8:9]
	s_add_u32 s8, s8, 0x8000
	s_addc_u32 s9, s9, 0
	s_cmp_eq_u32 s8, 0x40000
	global_load_dword v97, v[24:25], off
	v_ashrrev_i32_e32 v7, 31, v6
	v_lshlrev_b64 v[24:25], 12, v[6:7]
	v_lshl_add_u64 v[24:25], v[4:5], 0, v[24:25]
	v_add_u32_e32 v6, 8, v6
	global_load_dword v98, v[24:25], off
	v_lshl_add_u64 v[24:25], v[12:13], 0, s[8:9]
	global_load_dword v99, v[24:25], off
	v_lshl_add_u64 v[24:25], v[10:11], 0, s[8:9]
	global_load_dword v100, v[24:25], off
	v_lshl_add_u64 v[24:25], v[8:9], 0, s[8:9]
	s_add_u32 s8, s8, 0x8000
	s_addc_u32 s9, s9, 0
	s_cmp_eq_u32 s8, 0x40000
	global_load_dword v101, v[24:25], off
	v_ashrrev_i32_e32 v7, 31, v6
	v_lshlrev_b64 v[24:25], 12, v[6:7]
	v_lshl_add_u64 v[24:25], v[4:5], 0, v[24:25]
	v_add_u32_e32 v6, 8, v6
	global_load_dword v102, v[24:25], off
	v_lshl_add_u64 v[24:25], v[12:13], 0, s[8:9]
	global_load_dword v103, v[24:25], off
	v_lshl_add_u64 v[24:25], v[10:11], 0, s[8:9]
	global_load_dword v104, v[24:25], off
	v_lshl_add_u64 v[24:25], v[8:9], 0, s[8:9]
	s_add_u32 s8, s8, 0x8000
	s_addc_u32 s9, s9, 0
	s_cmp_eq_u32 s8, 0x40000
	global_load_dword v105, v[24:25], off
	v_ashrrev_i32_e32 v7, 31, v6
	v_lshlrev_b64 v[24:25], 12, v[6:7]
	v_lshl_add_u64 v[24:25], v[4:5], 0, v[24:25]
	v_add_u32_e32 v6, 8, v6
	global_load_dword v106, v[24:25], off
	s_waitcnt vmcnt(31)
	ds_write_b32 v23, v73
	s_waitcnt vmcnt(30)
; #define LAS __attribute__((address_space(3)))
; #define GAS __attribute__((address_space(1)))
; __device__ __forceinline__ unsigned cvt_pk_bf16(float lo, float hi) { const f32x2 v = {lo, hi}; return __builtin_bit_cast(unsigned, __builtin_convertvector(v, b16x2_t)); }
; #define LDS_WAIT() asm volatile("s_waitcnt lgkmcnt(0)" ::: "memory")
; template <class Fn>
; __device__ __forceinline__ void prep_mat(bf16_t* dst, int NR, int KC, int ldd, const Fn f, int& gw, int NGW, LAS float* scr, int lane) {
;     ...
;         for (int i = 0; i < 32; ++i) { const int kk = 2 * i + (lane >> 5); scr[kk * 33 + (lane & 31)] = f(n0 + (lane & 31), k0 + kk); }
;         LDS_WAIT(); asm volatile("" ::: "memory");
;         const int c = lane & 7;
; #pragma unroll
;         for (int j = 0; j < 4; ++j) { const int n = (lane >> 3) + 8 * j; const LAS float* s = scr + (8 * c) * 33 + n;
;             u32x4 o; o.x = cvt_pk_bf16(s[0 * 33], s[1 * 33]); o.y = cvt_pk_bf16(s[2 * 33], s[3 * 33]); o.z = cvt_pk_bf16(s[4 * 33], s[5 * 33]); o.w = cvt_pk_bf16(s[6 * 33], s[7 * 33]);
;             *(GAS u32x4*)(dst + (size_t)(n0 + n) * ldd + k0 + 8 * c) = o; }
;         LDS_WAIT(); asm volatile("" ::: "memory");
;     }
	ds_write_b32 v23, v74 offset:264
	s_waitcnt vmcnt(29)
	ds_write_b32 v23, v75 offset:528
	s_waitcnt vmcnt(28)
	ds_write_b32 v23, v76 offset:792
	s_waitcnt vmcnt(27)
	ds_write_b32 v23, v77 offset:1056
	s_waitcnt vmcnt(26)
	ds_write_b32 v23, v78 offset:1320
	s_waitcnt vmcnt(25)
	ds_write_b32 v23, v79 offset:1584
	s_waitcnt vmcnt(24)
	ds_write_b32 v23, v80 offset:1848
	s_waitcnt vmcnt(23)
	ds_write_b32 v23, v81 offset:2112
	s_waitcnt vmcnt(22)
	ds_write_b32 v23, v82 offset:2376
	s_waitcnt vmcnt(21)
	ds_write_b32 v23, v83 offset:2640
	s_waitcnt vmcnt(20)
	ds_write_b32 v23, v84 offset:2904
	s_waitcnt vmcnt(19)
	ds_write_b32 v23, v85 offset:3168
	s_waitcnt vmcnt(18)
	ds_write_b32 v23, v86 offset:3432
	s_waitcnt vmcnt(17)
	ds_write_b32 v23, v87 offset:3696
	s_waitcnt vmcnt(16)
	ds_write_b32 v23, v90 offset:3960
	s_waitcnt vmcnt(15)
	ds_write_b32 v23, v91 offset:4224
	s_waitcnt vmcnt(14)
	ds_write_b32 v23, v92 offset:4488
	s_waitcnt vmcnt(13)
	ds_write_b32 v23, v93 offset:4752
	s_waitcnt vmcnt(12)
	ds_write_b32 v23, v94 offset:5016
	s_waitcnt vmcnt(11)
	ds_write_b32 v23, v95 offset:5280
	s_waitcnt vmcnt(10)
	ds_write_b32 v23, v96 offset:5544
	s_waitcnt vmcnt(9)
	ds_write_b32 v23, v97 offset:5808
	s_waitcnt vmcnt(8)
	ds_write_b32 v23, v98 offset:6072
	s_waitcnt vmcnt(7)
	ds_write_b32 v23, v99 offset:6336
	s_waitcnt vmcnt(6)
	ds_write_b32 v23, v100 offset:6600
	s_waitcnt vmcnt(5)
	ds_write_b32 v23, v101 offset:6864
	s_waitcnt vmcnt(4)
	ds_write_b32 v23, v102 offset:7128
	s_waitcnt vmcnt(3)
	ds_write_b32 v23, v103 offset:7392
	s_waitcnt vmcnt(2)
	ds_write_b32 v23, v104 offset:7656
	s_waitcnt vmcnt(1)
	ds_write_b32 v23, v105 offset:7920
	s_waitcnt vmcnt(0)
	ds_write_b32 v23, v106 offset:8184
	v_add_u32_e32 v23, 0x2100, v23
	s_waitcnt lgkmcnt(0)
	ds_read2_b32 v[8:9], v17 offset0:33 offset1:41
	ds_read2_b32 v[10:11], v17 offset1:8
	ds_read2_b32 v[12:13], v17 offset0:66 offset1:74
	ds_read2_b32 v[24:25], v17 offset0:99 offset1:107
	ds_read2_b32 v[26:27], v17 offset0:132 offset1:140
	ds_read2_b32 v[28:29], v17 offset0:165 offset1:173
	ds_read2_b32 v[30:31], v17 offset0:198 offset1:206
	ds_read2_b32 v[32:33], v17 offset0:231 offset1:239
	v_add_u32_e32 v36, s11, v15
	v_ashrrev_i32_e32 v37, 31, v36
	v_lshl_add_u64 v[34:35], s[6:7], 1, v[2:3]
	v_lshlrev_b64 v[38:39], 11, v[36:37]
	s_waitcnt lgkmcnt(6)
	v_cvt_pk_bf16_f32 v4, v10, v8
	s_waitcnt lgkmcnt(4)
	v_cvt_pk_bf16_f32 v5, v12, v24
	s_waitcnt lgkmcnt(2)
	v_cvt_pk_bf16_f32 v6, v26, v28
	s_waitcnt lgkmcnt(0)
	v_cvt_pk_bf16_f32 v7, v30, v32
	v_lshl_add_u64 v[38:39], v[34:35], 0, v[38:39]
	v_add_u32_e32 v8, 8, v36
	global_store_dwordx4 v[38:39], v[4:7], off
	s_add_i32 s25, s25, s18
	s_cmpk_gt_i32 s25, 0xff
	v_cvt_pk_bf16_f32 v4, v11, v9
	v_ashrrev_i32_e32 v9, 31, v8
	v_cvt_pk_bf16_f32 v5, v13, v25
	v_cvt_pk_bf16_f32 v6, v27, v29
	v_cvt_pk_bf16_f32 v7, v31, v33
	v_lshlrev_b64 v[8:9], 11, v[8:9]
	ds_read2_b32 v[10:11], v17 offset0:49 offset1:57
	ds_read2_b32 v[12:13], v17 offset0:16 offset1:24
	ds_read2_b32 v[24:25], v17 offset0:82 offset1:90
	ds_read2_b32 v[26:27], v17 offset0:115 offset1:123
	ds_read2_b32 v[28:29], v17 offset0:148 offset1:156
	ds_read2_b32 v[30:31], v17 offset0:181 offset1:189
	ds_read2_b32 v[32:33], v17 offset0:214 offset1:222
	ds_read2_b32 v[38:39], v17 offset0:247 offset1:255
	v_lshl_add_u64 v[8:9], v[34:35], 0, v[8:9]
	global_store_dwordx4 v[8:9], v[4:7], off
	v_add_u32_e32 v8, 16, v36
	v_ashrrev_i32_e32 v9, 31, v8
	v_lshlrev_b64 v[8:9], 11, v[8:9]
	s_waitcnt lgkmcnt(6)
	v_cvt_pk_bf16_f32 v4, v12, v10
	s_waitcnt lgkmcnt(4)
	v_cvt_pk_bf16_f32 v5, v24, v26
	s_waitcnt lgkmcnt(2)
	v_cvt_pk_bf16_f32 v6, v28, v30
	s_waitcnt lgkmcnt(0)
	v_cvt_pk_bf16_f32 v7, v32, v38
	v_lshl_add_u64 v[8:9], v[34:35], 0, v[8:9]
	global_store_dwordx4 v[8:9], v[4:7], off
	v_add_u32_e32 v8, 24, v36
	v_ashrrev_i32_e32 v9, 31, v8
	v_lshlrev_b64 v[8:9], 11, v[8:9]
	v_cvt_pk_bf16_f32 v4, v13, v11
	v_cvt_pk_bf16_f32 v5, v25, v27
	v_cvt_pk_bf16_f32 v6, v29, v31
	v_cvt_pk_bf16_f32 v7, v33, v39
	v_lshl_add_u64 v[8:9], v[34:35], 0, v[8:9]
	global_store_dwordx4 v[8:9], v[4:7], off
	s_waitcnt lgkmcnt(0)
	s_cbranch_scc0 .LBB0_39

; #define LAS __attribute__((address_space(3)))
; template <class Fn>
; __device__ __forceinline__ void prep_mat(bf16_t* dst, int NR, int KC, int ldd, const Fn f, int& gw, int NGW, LAS float* scr, int lane) {
;     const int nnb = NR / 32, ntile = nnb * (KC / 64);
;     const int gw0 = gw; gw = (gw0 + NGW - ntile % NGW) % NGW;
;     for (int it = gw0; it < ntile; it += NGW) {
;         const int nb = it % nnb, kb = it / nnb, n0 = 32 * nb, k0 = 64 * kb;
; #pragma unroll 4
;         for (int i = 0; i < 32; ++i) { const int kk = 2 * i + (lane >> 5); scr[kk * 33 + (lane & 31)] = f(n0 + (lane & 31), k0 + kk); }
; __device__ __forceinline__ void prep_ffn(const float* wg, const float* wu, const float* wd, bf16_t* WGU, bf16_t* WD, int gw, int NGW, LAS float* scr, int lane) {
;     prep_mat(WGU, 2 * F, D, D, [=](int n, int k) -> float {
;         const int pn = n >> 8, p = n & 255, f = pn * 128 + (p & 127);
;         const float* src = (p >> 7) ? wu : wg; return src[(size_t)k * F + f]; }, gw, NGW, scr, lane);
.LBB0_409:
	v_lshl_add_u64 v[22:23], v[10:11], 0, s[8:9]
	global_load_dword v40, v[22:23], off
	v_lshl_add_u64 v[22:23], v[8:9], 0, s[8:9]
	global_load_dword v41, v[22:23], off
	v_lshl_add_u64 v[22:23], v[6:7], 0, s[8:9]
	global_load_dword v42, v[22:23], off
	v_lshl_add_u64 v[22:23], v[4:5], 0, s[8:9]
	s_add_u32 s8, s8, 0x16000
	s_addc_u32 s9, s9, 0
	s_cmp_eq_u32 s8, 0xb0000
	global_load_dword v43, v[22:23], off
	v_lshl_add_u64 v[22:23], v[10:11], 0, s[8:9]
	global_load_dword v44, v[22:23], off
	v_lshl_add_u64 v[22:23], v[8:9], 0, s[8:9]
	global_load_dword v45, v[22:23], off
	v_lshl_add_u64 v[22:23], v[6:7], 0, s[8:9]
	global_load_dword v46, v[22:23], off
	v_lshl_add_u64 v[22:23], v[4:5], 0, s[8:9]
	s_add_u32 s8, s8, 0x16000
	s_addc_u32 s9, s9, 0
	s_cmp_eq_u32 s8, 0xb0000
	global_load_dword v47, v[22:23], off
	v_lshl_add_u64 v[22:23], v[10:11], 0, s[8:9]
	global_load_dword v48, v[22:23], off
	v_lshl_add_u64 v[22:23], v[8:9], 0, s[8:9]
	global_load_dword v49, v[22:23], off
	v_lshl_add_u64 v[22:23], v[6:7], 0, s[8:9]
	global_load_dword v50, v[22:23], off
	v_lshl_add_u64 v[22:23], v[4:5], 0, s[8:9]
	s_add_u32 s8, s8, 0x16000
	s_addc_u32 s9, s9, 0
	s_cmp_eq_u32 s8, 0xb0000
	global_load_dword v51, v[22:23], off
	v_lshl_add_u64 v[22:23], v[10:11], 0, s[8:9]
	global_load_dword v52, v[22:23], off
	v_lshl_add_u64 v[22:23], v[8:9], 0, s[8:9]
	global_load_dword v53, v[22:23], off
	v_lshl_add_u64 v[22:23], v[6:7], 0, s[8:9]
	global_load_dword v54, v[22:23], off
	v_lshl_add_u64 v[22:23], v[4:5], 0, s[8:9]
	s_add_u32 s8, s8, 0x16000
	s_addc_u32 s9, s9, 0
	s_cmp_eq_u32 s8, 0xb0000
	global_load_dword v55, v[22:23], off
	v_lshl_add_u64 v[22:23], v[10:11], 0, s[8:9]
	global_load_dword v56, v[22:23], off
	v_lshl_add_u64 v[22:23], v[8:9], 0, s[8:9]
	global_load_dword v57, v[22:23], off
	v_lshl_add_u64 v[22:23], v[6:7], 0, s[8:9]
	global_load_dword v58, v[22:23], off
	v_lshl_add_u64 v[22:23], v[4:5], 0, s[8:9]
	s_add_u32 s8, s8, 0x16000
	s_addc_u32 s9, s9, 0
	s_cmp_eq_u32 s8, 0xb0000
	global_load_dword v59, v[22:23], off
	v_lshl_add_u64 v[22:23], v[10:11], 0, s[8:9]
	global_load_dword v60, v[22:23], off
	v_lshl_add_u64 v[22:23], v[8:9], 0, s[8:9]
	global_load_dword v61, v[22:23], off
	v_lshl_add_u64 v[22:23], v[6:7], 0, s[8:9]
	global_load_dword v62, v[22:23], off
	v_lshl_add_u64 v[22:23], v[4:5], 0, s[8:9]
	s_add_u32 s8, s8, 0x16000
	s_addc_u32 s9, s9, 0
	s_cmp_eq_u32 s8, 0xb0000
	global_load_dword v63, v[22:23], off
	v_lshl_add_u64 v[22:23], v[10:11], 0, s[8:9]
	global_load_dword v64, v[22:23], off
	v_lshl_add_u64 v[22:23], v[8:9], 0, s[8:9]
	global_load_dword v65, v[22:23], off
	v_lshl_add_u64 v[22:23], v[6:7], 0, s[8:9]
	global_load_dword v66, v[22:23], off
	v_lshl_add_u64 v[22:23], v[4:5], 0, s[8:9]
	s_add_u32 s8, s8, 0x16000
	s_addc_u32 s9, s9, 0
	s_cmp_eq_u32 s8, 0xb0000
	global_load_dword v67, v[22:23], off
	v_lshl_add_u64 v[22:23], v[10:11], 0, s[8:9]
	global_load_dword v68, v[22:23], off
	v_lshl_add_u64 v[22:23], v[8:9], 0, s[8:9]
	global_load_dword v69, v[22:23], off
	v_lshl_add_u64 v[22:23], v[6:7], 0, s[8:9]
	global_load_dword v70, v[22:23], off
	v_lshl_add_u64 v[22:23], v[4:5], 0, s[8:9]
	s_add_u32 s8, s8, 0x16000
	s_addc_u32 s9, s9, 0
	s_cmp_eq_u32 s8, 0xb0000
	global_load_dword v71, v[22:23], off
	s_waitcnt vmcnt(31)
	ds_write_b32 v21, v40
	s_waitcnt vmcnt(30)
	ds_write_b32 v21, v41 offset:264
	s_waitcnt vmcnt(29)
	ds_write_b32 v21, v42 offset:528
	s_waitcnt vmcnt(28)
	ds_write_b32 v21, v43 offset:792
	s_waitcnt vmcnt(27)
	ds_write_b32 v21, v44 offset:1056
	s_waitcnt vmcnt(26)
	ds_write_b32 v21, v45 offset:1320
	s_waitcnt vmcnt(25)
	ds_write_b32 v21, v46 offset:1584
	s_waitcnt vmcnt(24)
	ds_write_b32 v21, v47 offset:1848
	s_waitcnt vmcnt(23)
; #define LAS __attribute__((address_space(3)))
; #define GAS __attribute__((address_space(1)))
; __device__ __forceinline__ unsigned cvt_pk_bf16(float lo, float hi) { const f32x2 v = {lo, hi}; return __builtin_bit_cast(unsigned, __builtin_convertvector(v, b16x2_t)); }
; #define LDS_WAIT() asm volatile("s_waitcnt lgkmcnt(0)" ::: "memory")
; template <class Fn>
; __device__ __forceinline__ void prep_mat(bf16_t* dst, int NR, int KC, int ldd, const Fn f, int& gw, int NGW, LAS float* scr, int lane) {
;     ...
;         for (int i = 0; i < 32; ++i) { const int kk = 2 * i + (lane >> 5); scr[kk * 33 + (lane & 31)] = f(n0 + (lane & 31), k0 + kk); }
;         LDS_WAIT(); asm volatile("" ::: "memory");
;         const int c = lane & 7;
; #pragma unroll
;         for (int j = 0; j < 4; ++j) { const int n = (lane >> 3) + 8 * j; const LAS float* s = scr + (8 * c) * 33 + n;
;             u32x4 o; o.x = cvt_pk_bf16(s[0 * 33], s[1 * 33]); o.y = cvt_pk_bf16(s[2 * 33], s[3 * 33]); o.z = cvt_pk_bf16(s[4 * 33], s[5 * 33]); o.w = cvt_pk_bf16(s[6 * 33], s[7 * 33]);
;             *(GAS u32x4*)(dst + (size_t)(n0 + n) * ldd + k0 + 8 * c) = o; }
;         LDS_WAIT(); asm volatile("" ::: "memory");
;     }
	ds_write_b32 v21, v48 offset:2112
	s_waitcnt vmcnt(22)
	ds_write_b32 v21, v49 offset:2376
	s_waitcnt vmcnt(21)
	ds_write_b32 v21, v50 offset:2640
	s_waitcnt vmcnt(20)
	ds_write_b32 v21, v51 offset:2904
	s_waitcnt vmcnt(19)
	ds_write_b32 v21, v52 offset:3168
	s_waitcnt vmcnt(18)
	ds_write_b32 v21, v53 offset:3432
	s_waitcnt vmcnt(17)
	ds_write_b32 v21, v54 offset:3696
	s_waitcnt vmcnt(16)
	ds_write_b32 v21, v55 offset:3960
	s_waitcnt vmcnt(15)
	ds_write_b32 v21, v56 offset:4224
	s_waitcnt vmcnt(14)
	ds_write_b32 v21, v57 offset:4488
	s_waitcnt vmcnt(13)
	ds_write_b32 v21, v58 offset:4752
	s_waitcnt vmcnt(12)
	ds_write_b32 v21, v59 offset:5016
	s_waitcnt vmcnt(11)
	ds_write_b32 v21, v60 offset:5280
	s_waitcnt vmcnt(10)
	ds_write_b32 v21, v61 offset:5544
	s_waitcnt vmcnt(9)
	ds_write_b32 v21, v62 offset:5808
	s_waitcnt vmcnt(8)
	ds_write_b32 v21, v63 offset:6072
	s_waitcnt vmcnt(7)
	ds_write_b32 v21, v64 offset:6336
	s_waitcnt vmcnt(6)
	ds_write_b32 v21, v65 offset:6600
	s_waitcnt vmcnt(5)
	ds_write_b32 v21, v66 offset:6864
	s_waitcnt vmcnt(4)
	ds_write_b32 v21, v67 offset:7128
	s_waitcnt vmcnt(3)
	ds_write_b32 v21, v68 offset:7392
	s_waitcnt vmcnt(2)
	ds_write_b32 v21, v69 offset:7656
	s_waitcnt vmcnt(1)
	ds_write_b32 v21, v70 offset:7920
	s_waitcnt vmcnt(0)
	ds_write_b32 v21, v71 offset:8184
	v_add_u32_e32 v21, 0x2100, v21
	s_waitcnt lgkmcnt(0)
	ds_read2_b32 v[8:9], v13 offset0:33 offset1:41
	ds_read2_b32 v[10:11], v13 offset1:8
	ds_read2_b32 v[22:23], v13 offset0:66 offset1:74
	ds_read2_b32 v[24:25], v13 offset0:99 offset1:107
	ds_read2_b32 v[26:27], v13 offset0:132 offset1:140
	ds_read2_b32 v[28:29], v13 offset0:165 offset1:173
	ds_read2_b32 v[30:31], v13 offset0:198 offset1:206
	ds_read2_b32 v[32:33], v13 offset0:231 offset1:239
	v_add_u32_e32 v36, s28, v17
	v_ashrrev_i32_e32 v37, 31, v36
	v_lshl_add_u64 v[34:35], s[6:7], 1, v[2:3]
	v_lshlrev_b64 v[38:39], 11, v[36:37]
	s_waitcnt lgkmcnt(6)
	v_cvt_pk_bf16_f32 v4, v10, v8
	s_waitcnt lgkmcnt(4)
	v_cvt_pk_bf16_f32 v5, v22, v24
	s_waitcnt lgkmcnt(2)
	v_cvt_pk_bf16_f32 v6, v26, v28
	s_waitcnt lgkmcnt(0)
	v_cvt_pk_bf16_f32 v7, v30, v32
	v_lshl_add_u64 v[38:39], v[34:35], 0, v[38:39]
	v_add_u32_e32 v8, 8, v36
	global_store_dwordx4 v[38:39], v[4:7], off
	s_add_i32 s27, s27, s12
	s_cmpk_gt_i32 s27, 0xaff
	v_cvt_pk_bf16_f32 v4, v11, v9
	v_ashrrev_i32_e32 v9, 31, v8
	v_cvt_pk_bf16_f32 v5, v23, v25
	v_cvt_pk_bf16_f32 v6, v27, v29
	v_cvt_pk_bf16_f32 v7, v31, v33
	v_lshlrev_b64 v[8:9], 11, v[8:9]
	ds_read2_b32 v[10:11], v13 offset0:49 offset1:57
	ds_read2_b32 v[22:23], v13 offset0:16 offset1:24
	ds_read2_b32 v[24:25], v13 offset0:82 offset1:90
	ds_read2_b32 v[26:27], v13 offset0:115 offset1:123
	ds_read2_b32 v[28:29], v13 offset0:148 offset1:156
	ds_read2_b32 v[30:31], v13 offset0:181 offset1:189
	ds_read2_b32 v[32:33], v13 offset0:214 offset1:222
	ds_read2_b32 v[38:39], v13 offset0:247 offset1:255
	v_lshl_add_u64 v[8:9], v[34:35], 0, v[8:9]
	global_store_dwordx4 v[8:9], v[4:7], off
	v_add_u32_e32 v8, 16, v36
	v_ashrrev_i32_e32 v9, 31, v8
	v_lshlrev_b64 v[8:9], 11, v[8:9]
	s_waitcnt lgkmcnt(6)
	v_cvt_pk_bf16_f32 v4, v22, v10
	s_waitcnt lgkmcnt(4)
	v_cvt_pk_bf16_f32 v5, v24, v26
	s_waitcnt lgkmcnt(2)
	v_cvt_pk_bf16_f32 v6, v28, v30
	s_waitcnt lgkmcnt(0)
	v_cvt_pk_bf16_f32 v7, v32, v38
	v_lshl_add_u64 v[8:9], v[34:35], 0, v[8:9]
	global_store_dwordx4 v[8:9], v[4:7], off
	v_add_u32_e32 v8, 24, v36
	v_ashrrev_i32_e32 v9, 31, v8
	v_lshlrev_b64 v[8:9], 11, v[8:9]
	v_cvt_pk_bf16_f32 v4, v23, v11
	v_cvt_pk_bf16_f32 v5, v25, v27
	v_cvt_pk_bf16_f32 v6, v29, v31
	v_cvt_pk_bf16_f32 v7, v33, v39
	v_lshl_add_u64 v[8:9], v[34:35], 0, v[8:9]
	global_store_dwordx4 v[8:9], v[4:7], off
	s_waitcnt lgkmcnt(0)
	s_cbranch_scc0 .LBB0_408

; #define LAS __attribute__((address_space(3)))
; template <class Fn>
; __device__ __forceinline__ void prep_mat(bf16_t* dst, int NR, int KC, int ldd, const Fn f, int& gw, int NGW, LAS float* scr, int lane) {
;     const int nnb = NR / 32, ntile = nnb * (KC / 64);
;     const int gw0 = gw; gw = (gw0 + NGW - ntile % NGW) % NGW;
;     for (int it = gw0; it < ntile; it += NGW) {
;         const int nb = it % nnb, kb = it / nnb, n0 = 32 * nb, k0 = 64 * kb;
; #pragma unroll 4
;         for (int i = 0; i < 32; ++i) { const int kk = 2 * i + (lane >> 5); scr[kk * 33 + (lane & 31)] = f(n0 + (lane & 31), k0 + kk); }
; __device__ __forceinline__ void prep_ffn(const float* wg, const float* wu, const float* wd, bf16_t* WGU, bf16_t* WD, int gw, int NGW, LAS float* scr, int lane) {
;     ...
;     prep_mat(WD, D, F, F, [=](int n, int k) -> float { return wd[(size_t)k * D + n]; }, gw, NGW, scr, lane);
.LBB0_416:
	v_lshl_add_u64 v[24:25], v[12:13], 0, s[6:7]
	global_load_dword v72, v[24:25], off
	v_lshl_add_u64 v[24:25], v[10:11], 0, s[6:7]
	global_load_dword v73, v[24:25], off
	v_lshl_add_u64 v[24:25], v[8:9], 0, s[6:7]
	s_add_u32 s6, s6, 0x8000
	s_addc_u32 s7, s7, 0
	s_cmp_eq_u32 s6, 0x40000
	global_load_dword v74, v[24:25], off
	v_ashrrev_i32_e32 v7, 31, v6
	v_lshlrev_b64 v[24:25], 12, v[6:7]
	v_lshl_add_u64 v[24:25], v[4:5], 0, v[24:25]
	v_add_u32_e32 v6, 8, v6
	global_load_dword v75, v[24:25], off
	v_lshl_add_u64 v[24:25], v[12:13], 0, s[6:7]
	global_load_dword v76, v[24:25], off
	v_lshl_add_u64 v[24:25], v[10:11], 0, s[6:7]
	global_load_dword v77, v[24:25], off
	v_lshl_add_u64 v[24:25], v[8:9], 0, s[6:7]
	s_add_u32 s6, s6, 0x8000
	s_addc_u32 s7, s7, 0
	s_cmp_eq_u32 s6, 0x40000
	global_load_dword v78, v[24:25], off
	v_ashrrev_i32_e32 v7, 31, v6
	v_lshlrev_b64 v[24:25], 12, v[6:7]
	v_lshl_add_u64 v[24:25], v[4:5], 0, v[24:25]
	v_add_u32_e32 v6, 8, v6
	global_load_dword v79, v[24:25], off
	v_lshl_add_u64 v[24:25], v[12:13], 0, s[6:7]
	global_load_dword v80, v[24:25], off
	v_lshl_add_u64 v[24:25], v[10:11], 0, s[6:7]
	global_load_dword v81, v[24:25], off
	v_lshl_add_u64 v[24:25], v[8:9], 0, s[6:7]
	s_add_u32 s6, s6, 0x8000
	s_addc_u32 s7, s7, 0
	s_cmp_eq_u32 s6, 0x40000
	global_load_dword v82, v[24:25], off
	v_ashrrev_i32_e32 v7, 31, v6
	v_lshlrev_b64 v[24:25], 12, v[6:7]
	v_lshl_add_u64 v[24:25], v[4:5], 0, v[24:25]
	v_add_u32_e32 v6, 8, v6
	global_load_dword v83, v[24:25], off
	v_lshl_add_u64 v[24:25], v[12:13], 0, s[6:7]
	global_load_dword v84, v[24:25], off
	v_lshl_add_u64 v[24:25], v[10:11], 0, s[6:7]
	global_load_dword v85, v[24:25], off
	v_lshl_add_u64 v[24:25], v[8:9], 0, s[6:7]
	s_add_u32 s6, s6, 0x8000
	s_addc_u32 s7, s7, 0
	s_cmp_eq_u32 s6, 0x40000
	global_load_dword v86, v[24:25], off
	v_ashrrev_i32_e32 v7, 31, v6
	v_lshlrev_b64 v[24:25], 12, v[6:7]
	v_lshl_add_u64 v[24:25], v[4:5], 0, v[24:25]
	v_add_u32_e32 v6, 8, v6
	global_load_dword v87, v[24:25], off
	v_lshl_add_u64 v[24:25], v[12:13], 0, s[6:7]
	global_load_dword v88, v[24:25], off
	v_lshl_add_u64 v[24:25], v[10:11], 0, s[6:7]
	global_load_dword v89, v[24:25], off
	v_lshl_add_u64 v[24:25], v[8:9], 0, s[6:7]
	s_add_u32 s6, s6, 0x8000
	s_addc_u32 s7, s7, 0
	s_cmp_eq_u32 s6, 0x40000
	global_load_dword v90, v[24:25], off
	v_ashrrev_i32_e32 v7, 31, v6
	v_lshlrev_b64 v[24:25], 12, v[6:7]
	v_lshl_add_u64 v[24:25], v[4:5], 0, v[24:25]
	v_add_u32_e32 v6, 8, v6
	global_load_dword v91, v[24:25], off
	v_lshl_add_u64 v[24:25], v[12:13], 0, s[6:7]
	global_load_dword v92, v[24:25], off
	v_lshl_add_u64 v[24:25], v[10:11], 0, s[6:7]
	global_load_dword v93, v[24:25], off
	v_lshl_add_u64 v[24:25], v[8:9], 0, s[6:7]
	s_add_u32 s6, s6, 0x8000
	s_addc_u32 s7, s7, 0
	s_cmp_eq_u32 s6, 0x40000
	global_load_dword v94, v[24:25], off
	v_ashrrev_i32_e32 v7, 31, v6
	v_lshlrev_b64 v[24:25], 12, v[6:7]
	v_lshl_add_u64 v[24:25], v[4:5], 0, v[24:25]
	v_add_u32_e32 v6, 8, v6
	global_load_dword v95, v[24:25], off
	v_lshl_add_u64 v[24:25], v[12:13], 0, s[6:7]
	global_load_dword v96, v[24:25], off
	v_lshl_add_u64 v[24:25], v[10:11], 0, s[6:7]
	global_load_dword v97, v[24:25], off
	v_lshl_add_u64 v[24:25], v[8:9], 0, s[6:7]
	s_add_u32 s6, s6, 0x8000
	s_addc_u32 s7, s7, 0
	s_cmp_eq_u32 s6, 0x40000
	global_load_dword v98, v[24:25], off
	v_ashrrev_i32_e32 v7, 31, v6
	v_lshlrev_b64 v[24:25], 12, v[6:7]
	v_lshl_add_u64 v[24:25], v[4:5], 0, v[24:25]
	v_add_u32_e32 v6, 8, v6
	global_load_dword v99, v[24:25], off
	v_lshl_add_u64 v[24:25], v[12:13], 0, s[6:7]
	global_load_dword v100, v[24:25], off
	v_lshl_add_u64 v[24:25], v[10:11], 0, s[6:7]
	global_load_dword v101, v[24:25], off
	v_lshl_add_u64 v[24:25], v[8:9], 0, s[6:7]
	s_add_u32 s6, s6, 0x8000
	s_addc_u32 s7, s7, 0
	s_cmp_eq_u32 s6, 0x40000
	global_load_dword v102, v[24:25], off
	v_ashrrev_i32_e32 v7, 31, v6
	v_lshlrev_b64 v[24:25], 12, v[6:7]
	v_lshl_add_u64 v[24:25], v[4:5], 0, v[24:25]
	v_add_u32_e32 v6, 8, v6
	global_load_dword v103, v[24:25], off
	s_waitcnt vmcnt(31)
; #define LAS __attribute__((address_space(3)))
; #define GAS __attribute__((address_space(1)))
; __device__ __forceinline__ unsigned cvt_pk_bf16(float lo, float hi) { const f32x2 v = {lo, hi}; return __builtin_bit_cast(unsigned, __builtin_convertvector(v, b16x2_t)); }
; #define LDS_WAIT() asm volatile("s_waitcnt lgkmcnt(0)" ::: "memory")
; template <class Fn>
; __device__ __forceinline__ void prep_mat(bf16_t* dst, int NR, int KC, int ldd, const Fn f, int& gw, int NGW, LAS float* scr, int lane) {
;     ...
;         for (int i = 0; i < 32; ++i) { const int kk = 2 * i + (lane >> 5); scr[kk * 33 + (lane & 31)] = f(n0 + (lane & 31), k0 + kk); }
;         LDS_WAIT(); asm volatile("" ::: "memory");
;         const int c = lane & 7;
; #pragma unroll
;         for (int j = 0; j < 4; ++j) { const int n = (lane >> 3) + 8 * j; const LAS float* s = scr + (8 * c) * 33 + n;
;             u32x4 o; o.x = cvt_pk_bf16(s[0 * 33], s[1 * 33]); o.y = cvt_pk_bf16(s[2 * 33], s[3 * 33]); o.z = cvt_pk_bf16(s[4 * 33], s[5 * 33]); o.w = cvt_pk_bf16(s[6 * 33], s[7 * 33]);
;             *(GAS u32x4*)(dst + (size_t)(n0 + n) * ldd + k0 + 8 * c) = o; }
;         LDS_WAIT(); asm volatile("" ::: "memory");
;     }
	ds_write_b32 v22, v72
	s_waitcnt vmcnt(30)
	ds_write_b32 v22, v73 offset:264
	s_waitcnt vmcnt(29)
	ds_write_b32 v22, v74 offset:528
	s_waitcnt vmcnt(28)
	ds_write_b32 v22, v75 offset:792
	s_waitcnt vmcnt(27)
	ds_write_b32 v22, v76 offset:1056
	s_waitcnt vmcnt(26)
	ds_write_b32 v22, v77 offset:1320
	s_waitcnt vmcnt(25)
	ds_write_b32 v22, v78 offset:1584
	s_waitcnt vmcnt(24)
	ds_write_b32 v22, v79 offset:1848
	s_waitcnt vmcnt(23)
	ds_write_b32 v22, v80 offset:2112
	s_waitcnt vmcnt(22)
	ds_write_b32 v22, v81 offset:2376
	s_waitcnt vmcnt(21)
	ds_write_b32 v22, v82 offset:2640
	s_waitcnt vmcnt(20)
	ds_write_b32 v22, v83 offset:2904
	s_waitcnt vmcnt(19)
	ds_write_b32 v22, v84 offset:3168
	s_waitcnt vmcnt(18)
	ds_write_b32 v22, v85 offset:3432
	s_waitcnt vmcnt(17)
	ds_write_b32 v22, v86 offset:3696
	s_waitcnt vmcnt(16)
	ds_write_b32 v22, v87 offset:3960
	s_waitcnt vmcnt(15)
	ds_write_b32 v22, v88 offset:4224
	s_waitcnt vmcnt(14)
	ds_write_b32 v22, v89 offset:4488
	s_waitcnt vmcnt(13)
	ds_write_b32 v22, v90 offset:4752
	s_waitcnt vmcnt(12)
	ds_write_b32 v22, v91 offset:5016
	s_waitcnt vmcnt(11)
	ds_write_b32 v22, v92 offset:5280
	s_waitcnt vmcnt(10)
	ds_write_b32 v22, v93 offset:5544
	s_waitcnt vmcnt(9)
	ds_write_b32 v22, v94 offset:5808
	s_waitcnt vmcnt(8)
	ds_write_b32 v22, v95 offset:6072
	s_waitcnt vmcnt(7)
	ds_write_b32 v22, v96 offset:6336
	s_waitcnt vmcnt(6)
	ds_write_b32 v22, v97 offset:6600
	s_waitcnt vmcnt(5)
	ds_write_b32 v22, v98 offset:6864
	s_waitcnt vmcnt(4)
	ds_write_b32 v22, v99 offset:7128
	s_waitcnt vmcnt(3)
	ds_write_b32 v22, v100 offset:7392
	s_waitcnt vmcnt(2)
	ds_write_b32 v22, v101 offset:7656
	s_waitcnt vmcnt(1)
	ds_write_b32 v22, v102 offset:7920
	s_waitcnt vmcnt(0)
	ds_write_b32 v22, v103 offset:8184
	v_add_u32_e32 v22, 0x2100, v22
	s_waitcnt lgkmcnt(0)
	ds_read2_b32 v[8:9], v16 offset0:33 offset1:41
	ds_read2_b32 v[10:11], v16 offset1:8
	ds_read2_b32 v[12:13], v16 offset0:66 offset1:74
	ds_read2_b32 v[22:23], v16 offset0:99 offset1:107
	ds_read2_b32 v[24:25], v16 offset0:132 offset1:140
	ds_read2_b32 v[26:27], v16 offset0:165 offset1:173
	ds_read2_b32 v[28:29], v16 offset0:198 offset1:206
	ds_read2_b32 v[30:31], v16 offset0:231 offset1:239
	v_lshl_add_u64 v[32:33], s[4:5], 1, v[2:3]
	v_add_u32_e32 v36, s13, v17
	s_waitcnt lgkmcnt(6)
	v_cvt_pk_bf16_f32 v4, v10, v8
	s_waitcnt lgkmcnt(4)
	v_cvt_pk_bf16_f32 v5, v12, v22
	s_waitcnt lgkmcnt(2)
	v_cvt_pk_bf16_f32 v6, v24, v26
	s_waitcnt lgkmcnt(0)
	v_cvt_pk_bf16_f32 v7, v28, v30
	v_mad_i64_i32 v[34:35], s[4:5], v36, s9, v[32:33]
	global_store_dwordx4 v[34:35], v[4:7], off
	v_add_u32_e32 v8, 8, v36
	s_add_i32 s8, s8, s12
	v_cvt_pk_bf16_f32 v4, v11, v9
	v_cvt_pk_bf16_f32 v5, v13, v23
	v_cvt_pk_bf16_f32 v6, v25, v27
	v_cvt_pk_bf16_f32 v7, v29, v31
	ds_read2_b32 v[10:11], v16 offset0:49 offset1:57
	ds_read2_b32 v[12:13], v16 offset0:16 offset1:24
	ds_read2_b32 v[22:23], v16 offset0:82 offset1:90
	ds_read2_b32 v[24:25], v16 offset0:115 offset1:123
	ds_read2_b32 v[26:27], v16 offset0:148 offset1:156
	ds_read2_b32 v[28:29], v16 offset0:181 offset1:189
	ds_read2_b32 v[30:31], v16 offset0:214 offset1:222
	ds_read2_b32 v[34:35], v16 offset0:247 offset1:255
	v_mad_i64_i32 v[8:9], s[4:5], v8, s9, v[32:33]
	global_store_dwordx4 v[8:9], v[4:7], off
	v_add_u32_e32 v8, 16, v36
	v_mad_i64_i32 v[8:9], s[4:5], v8, s9, v[32:33]
	s_waitcnt lgkmcnt(6)
	v_cvt_pk_bf16_f32 v4, v12, v10
	s_waitcnt lgkmcnt(4)
	v_cvt_pk_bf16_f32 v5, v22, v24
	s_waitcnt lgkmcnt(2)
	v_cvt_pk_bf16_f32 v6, v26, v28
	s_waitcnt lgkmcnt(0)
	v_cvt_pk_bf16_f32 v7, v30, v34
	global_store_dwordx4 v[8:9], v[4:7], off
	v_add_u32_e32 v8, 24, v36
	v_mad_i64_i32 v[8:9], s[4:5], v8, s9, v[32:33]
	v_cvt_pk_bf16_f32 v4, v13, v11
	v_cvt_pk_bf16_f32 v5, v23, v25
	v_cvt_pk_bf16_f32 v6, v27, v29
	v_cvt_pk_bf16_f32 v7, v31, v35
	global_store_dwordx4 v[8:9], v[4:7], off
	s_waitcnt lgkmcnt(0)
	s_cmpk_gt_i32 s8, 0x57f
	s_cbranch_scc0 .LBB0_415
	v_mov_b32_e32 v16, v15

; #define LAS __attribute__((address_space(3)))
; template <class Fn>
; __device__ __forceinline__ void prep_mat(bf16_t* dst, int NR, int KC, int ldd, const Fn f, int& gw, int NGW, LAS float* scr, int lane) {
;     const int nnb = NR / 32, ntile = nnb * (KC / 64);
;     const int gw0 = gw; gw = (gw0 + NGW - ntile % NGW) % NGW;
;     for (int it = gw0; it < ntile; it += NGW) {
;         const int nb = it % nnb, kb = it / nnb, n0 = 32 * nb, k0 = 64 * kb;
; #pragma unroll 4
;         for (int i = 0; i < 32; ++i) { const int kk = 2 * i + (lane >> 5); scr[kk * 33 + (lane & 31)] = f(n0 + (lane & 31), k0 + kk); }
; __device__ __forceinline__ void prep_rwkv(const LAS unsigned* PL, int idx, bf16_t* WR2, bf16_t* WR3, bf16_t* WG, bf16_t* WO, int gw, int NGW, LAS float* scr, int lane) {
;     ...
;             prep_mat(WR2, 2048, 1024, 1024, [=](int n, int k) -> float { const float* W = (n >> 10) ? w_k : w_r; return W[(size_t)k * D + (n & 1023)]; }, gw, NGW, scr, lane);
.LBB0_615:
	v_lshl_add_u64 v[26:27], v[14:15], 0, s[16:17]
	global_load_dword v40, v[26:27], off
	v_lshl_add_u64 v[26:27], v[12:13], 0, s[16:17]
	global_load_dword v41, v[26:27], off
	v_lshl_add_u64 v[26:27], v[10:11], 0, s[16:17]
	s_add_u32 s16, s16, 0x8000
	s_addc_u32 s17, s17, 0
	s_cmp_eq_u32 s16, 0x40000
	global_load_dword v42, v[26:27], off
	v_ashrrev_i32_e32 v9, 31, v8
	v_lshlrev_b64 v[26:27], 12, v[8:9]
	v_lshl_add_u64 v[26:27], v[6:7], 0, v[26:27]
	v_add_u32_e32 v8, 8, v8
	global_load_dword v43, v[26:27], off
	v_lshl_add_u64 v[26:27], v[14:15], 0, s[16:17]
	global_load_dword v44, v[26:27], off
	v_lshl_add_u64 v[26:27], v[12:13], 0, s[16:17]
	global_load_dword v45, v[26:27], off
	v_lshl_add_u64 v[26:27], v[10:11], 0, s[16:17]
	s_add_u32 s16, s16, 0x8000
	s_addc_u32 s17, s17, 0
	s_cmp_eq_u32 s16, 0x40000
	global_load_dword v46, v[26:27], off
	v_ashrrev_i32_e32 v9, 31, v8
	v_lshlrev_b64 v[26:27], 12, v[8:9]
	v_lshl_add_u64 v[26:27], v[6:7], 0, v[26:27]
	v_add_u32_e32 v8, 8, v8
	global_load_dword v47, v[26:27], off
	v_lshl_add_u64 v[26:27], v[14:15], 0, s[16:17]
	global_load_dword v48, v[26:27], off
	v_lshl_add_u64 v[26:27], v[12:13], 0, s[16:17]
	global_load_dword v49, v[26:27], off
	v_lshl_add_u64 v[26:27], v[10:11], 0, s[16:17]
	s_add_u32 s16, s16, 0x8000
	s_addc_u32 s17, s17, 0
	s_cmp_eq_u32 s16, 0x40000
	global_load_dword v50, v[26:27], off
	v_ashrrev_i32_e32 v9, 31, v8
	v_lshlrev_b64 v[26:27], 12, v[8:9]
	v_lshl_add_u64 v[26:27], v[6:7], 0, v[26:27]
	v_add_u32_e32 v8, 8, v8
	global_load_dword v51, v[26:27], off
	v_lshl_add_u64 v[26:27], v[14:15], 0, s[16:17]
	global_load_dword v52, v[26:27], off
	v_lshl_add_u64 v[26:27], v[12:13], 0, s[16:17]
	global_load_dword v53, v[26:27], off
	v_lshl_add_u64 v[26:27], v[10:11], 0, s[16:17]
	s_add_u32 s16, s16, 0x8000
	s_addc_u32 s17, s17, 0
	s_cmp_eq_u32 s16, 0x40000
	global_load_dword v54, v[26:27], off
	v_ashrrev_i32_e32 v9, 31, v8
	v_lshlrev_b64 v[26:27], 12, v[8:9]
	v_lshl_add_u64 v[26:27], v[6:7], 0, v[26:27]
	v_add_u32_e32 v8, 8, v8
	global_load_dword v55, v[26:27], off
	v_lshl_add_u64 v[26:27], v[14:15], 0, s[16:17]
	global_load_dword v56, v[26:27], off
	v_lshl_add_u64 v[26:27], v[12:13], 0, s[16:17]
	global_load_dword v57, v[26:27], off
	v_lshl_add_u64 v[26:27], v[10:11], 0, s[16:17]
	s_add_u32 s16, s16, 0x8000
	s_addc_u32 s17, s17, 0
	s_cmp_eq_u32 s16, 0x40000
	global_load_dword v58, v[26:27], off
	v_ashrrev_i32_e32 v9, 31, v8
	v_lshlrev_b64 v[26:27], 12, v[8:9]
	v_lshl_add_u64 v[26:27], v[6:7], 0, v[26:27]
	v_add_u32_e32 v8, 8, v8
	global_load_dword v59, v[26:27], off
	v_lshl_add_u64 v[26:27], v[14:15], 0, s[16:17]
	global_load_dword v60, v[26:27], off
	v_lshl_add_u64 v[26:27], v[12:13], 0, s[16:17]
	global_load_dword v61, v[26:27], off
	v_lshl_add_u64 v[26:27], v[10:11], 0, s[16:17]
	s_add_u32 s16, s16, 0x8000
	s_addc_u32 s17, s17, 0
	s_cmp_eq_u32 s16, 0x40000
	global_load_dword v62, v[26:27], off
	v_ashrrev_i32_e32 v9, 31, v8
	v_lshlrev_b64 v[26:27], 12, v[8:9]
	v_lshl_add_u64 v[26:27], v[6:7], 0, v[26:27]
	v_add_u32_e32 v8, 8, v8
	global_load_dword v113, v[26:27], off
	v_lshl_add_u64 v[26:27], v[14:15], 0, s[16:17]
	global_load_dword v130, v[26:27], off
	v_lshl_add_u64 v[26:27], v[12:13], 0, s[16:17]
	global_load_dword v132, v[26:27], off
	v_lshl_add_u64 v[26:27], v[10:11], 0, s[16:17]
	s_add_u32 s16, s16, 0x8000
	s_addc_u32 s17, s17, 0
	s_cmp_eq_u32 s16, 0x40000
	global_load_dword v134, v[26:27], off
	v_ashrrev_i32_e32 v9, 31, v8
	v_lshlrev_b64 v[26:27], 12, v[8:9]
	v_lshl_add_u64 v[26:27], v[6:7], 0, v[26:27]
	v_add_u32_e32 v8, 8, v8
	global_load_dword v136, v[26:27], off
	v_lshl_add_u64 v[26:27], v[14:15], 0, s[16:17]
	global_load_dword v138, v[26:27], off
	v_lshl_add_u64 v[26:27], v[12:13], 0, s[16:17]
	global_load_dword v140, v[26:27], off
	v_lshl_add_u64 v[26:27], v[10:11], 0, s[16:17]
	s_add_u32 s16, s16, 0x8000
	s_addc_u32 s17, s17, 0
	s_cmp_eq_u32 s16, 0x40000
	global_load_dword v142, v[26:27], off
	v_ashrrev_i32_e32 v9, 31, v8
	v_lshlrev_b64 v[26:27], 12, v[8:9]
	v_lshl_add_u64 v[26:27], v[6:7], 0, v[26:27]
	v_add_u32_e32 v8, 8, v8
	global_load_dword v144, v[26:27], off
	s_waitcnt vmcnt(31)
; #define LAS __attribute__((address_space(3)))
; #define GAS __attribute__((address_space(1)))
; __device__ __forceinline__ unsigned cvt_pk_bf16(float lo, float hi) { const f32x2 v = {lo, hi}; return __builtin_bit_cast(unsigned, __builtin_convertvector(v, b16x2_t)); }
; #define LDS_WAIT() asm volatile("s_waitcnt lgkmcnt(0)" ::: "memory")
; template <class Fn>
; __device__ __forceinline__ void prep_mat(bf16_t* dst, int NR, int KC, int ldd, const Fn f, int& gw, int NGW, LAS float* scr, int lane) {
;     ...
;         for (int i = 0; i < 32; ++i) { const int kk = 2 * i + (lane >> 5); scr[kk * 33 + (lane & 31)] = f(n0 + (lane & 31), k0 + kk); }
;         LDS_WAIT(); asm volatile("" ::: "memory");
;         const int c = lane & 7;
; #pragma unroll
;         for (int j = 0; j < 4; ++j) { const int n = (lane >> 3) + 8 * j; const LAS float* s = scr + (8 * c) * 33 + n;
;             u32x4 o; o.x = cvt_pk_bf16(s[0 * 33], s[1 * 33]); o.y = cvt_pk_bf16(s[2 * 33], s[3 * 33]); o.z = cvt_pk_bf16(s[4 * 33], s[5 * 33]); o.w = cvt_pk_bf16(s[6 * 33], s[7 * 33]);
;             *(GAS u32x4*)(dst + (size_t)(n0 + n) * ldd + k0 + 8 * c) = o; }
;         LDS_WAIT(); asm volatile("" ::: "memory");
;     }
	ds_write_b32 v2, v40
	s_waitcnt vmcnt(30)
	ds_write_b32 v2, v41 offset:264
	s_waitcnt vmcnt(29)
	ds_write_b32 v2, v42 offset:528
	s_waitcnt vmcnt(28)
	ds_write_b32 v2, v43 offset:792
	s_waitcnt vmcnt(27)
	ds_write_b32 v2, v44 offset:1056
	s_waitcnt vmcnt(26)
	ds_write_b32 v2, v45 offset:1320
	s_waitcnt vmcnt(25)
	ds_write_b32 v2, v46 offset:1584
	s_waitcnt vmcnt(24)
	ds_write_b32 v2, v47 offset:1848
	s_waitcnt vmcnt(23)
	ds_write_b32 v2, v48 offset:2112
	s_waitcnt vmcnt(22)
	ds_write_b32 v2, v49 offset:2376
	s_waitcnt vmcnt(21)
	ds_write_b32 v2, v50 offset:2640
	s_waitcnt vmcnt(20)
	ds_write_b32 v2, v51 offset:2904
	s_waitcnt vmcnt(19)
	ds_write_b32 v2, v52 offset:3168
	s_waitcnt vmcnt(18)
	ds_write_b32 v2, v53 offset:3432
	s_waitcnt vmcnt(17)
	ds_write_b32 v2, v54 offset:3696
	s_waitcnt vmcnt(16)
	ds_write_b32 v2, v55 offset:3960
	s_waitcnt vmcnt(15)
	ds_write_b32 v2, v56 offset:4224
	s_waitcnt vmcnt(14)
	ds_write_b32 v2, v57 offset:4488
	s_waitcnt vmcnt(13)
	ds_write_b32 v2, v58 offset:4752
	s_waitcnt vmcnt(12)
	ds_write_b32 v2, v59 offset:5016
	s_waitcnt vmcnt(11)
	ds_write_b32 v2, v60 offset:5280
	s_waitcnt vmcnt(10)
	ds_write_b32 v2, v61 offset:5544
	s_waitcnt vmcnt(9)
	ds_write_b32 v2, v62 offset:5808
	s_waitcnt vmcnt(8)
	ds_write_b32 v2, v113 offset:6072
	s_waitcnt vmcnt(7)
	ds_write_b32 v2, v130 offset:6336
	s_waitcnt vmcnt(6)
	ds_write_b32 v2, v132 offset:6600
	s_waitcnt vmcnt(5)
	ds_write_b32 v2, v134 offset:6864
	s_waitcnt vmcnt(4)
	ds_write_b32 v2, v136 offset:7128
	s_waitcnt vmcnt(3)
	ds_write_b32 v2, v138 offset:7392
	s_waitcnt vmcnt(2)
	ds_write_b32 v2, v140 offset:7656
	s_waitcnt vmcnt(1)
	ds_write_b32 v2, v142 offset:7920
	s_waitcnt vmcnt(0)
	ds_write_b32 v2, v144 offset:8184
	v_add_u32_e32 v2, 0x2100, v2
	s_waitcnt lgkmcnt(0)
	ds_read2_b32 v[10:11], v20 offset0:33 offset1:41
	ds_read2_b32 v[12:13], v20 offset1:8
	ds_read2_b32 v[14:15], v20 offset0:66 offset1:74
	ds_read2_b32 v[26:27], v20 offset0:99 offset1:107
	ds_read2_b32 v[28:29], v20 offset0:132 offset1:140
	ds_read2_b32 v[30:31], v20 offset0:165 offset1:173
	ds_read2_b32 v[32:33], v20 offset0:198 offset1:206
	ds_read2_b32 v[34:35], v20 offset0:231 offset1:239
	v_add_u32_e32 v38, s29, v18
	v_ashrrev_i32_e32 v39, 31, v38
	v_lshl_add_u64 v[36:37], s[14:15], 1, v[4:5]
	v_lshlrev_b64 v[40:41], 11, v[38:39]
	s_waitcnt lgkmcnt(6)
	v_cvt_pk_bf16_f32 v6, v12, v10
	s_waitcnt lgkmcnt(4)
	v_cvt_pk_bf16_f32 v7, v14, v26
	s_waitcnt lgkmcnt(2)
	v_cvt_pk_bf16_f32 v8, v28, v30
	s_waitcnt lgkmcnt(0)
	v_cvt_pk_bf16_f32 v9, v32, v34
	v_lshl_add_u64 v[40:41], v[36:37], 0, v[40:41]
	v_add_u32_e32 v10, 8, v38
	global_store_dwordx4 v[40:41], v[6:9], off
	s_add_i32 s28, s28, s43
	s_cmpk_gt_i32 s28, 0x3ff
	v_cvt_pk_bf16_f32 v6, v13, v11
	v_ashrrev_i32_e32 v11, 31, v10
	v_cvt_pk_bf16_f32 v7, v15, v27
	v_cvt_pk_bf16_f32 v8, v29, v31
	v_cvt_pk_bf16_f32 v9, v33, v35
	v_lshlrev_b64 v[10:11], 11, v[10:11]
	ds_read2_b32 v[12:13], v20 offset0:49 offset1:57
	ds_read2_b32 v[14:15], v20 offset0:16 offset1:24
	ds_read2_b32 v[26:27], v20 offset0:82 offset1:90
	ds_read2_b32 v[28:29], v20 offset0:115 offset1:123
	ds_read2_b32 v[30:31], v20 offset0:148 offset1:156
	ds_read2_b32 v[32:33], v20 offset0:181 offset1:189
	ds_read2_b32 v[34:35], v20 offset0:214 offset1:222
	ds_read2_b32 v[40:41], v20 offset0:247 offset1:255
	v_lshl_add_u64 v[10:11], v[36:37], 0, v[10:11]
	global_store_dwordx4 v[10:11], v[6:9], off
	v_add_u32_e32 v10, 16, v38
	v_ashrrev_i32_e32 v11, 31, v10
	v_lshlrev_b64 v[10:11], 11, v[10:11]
	s_waitcnt lgkmcnt(6)
	v_cvt_pk_bf16_f32 v6, v14, v12
	s_waitcnt lgkmcnt(4)
	v_cvt_pk_bf16_f32 v7, v26, v28
	s_waitcnt lgkmcnt(2)
	v_cvt_pk_bf16_f32 v8, v30, v32
	s_waitcnt lgkmcnt(0)
	v_cvt_pk_bf16_f32 v9, v34, v40
	v_lshl_add_u64 v[10:11], v[36:37], 0, v[10:11]
	global_store_dwordx4 v[10:11], v[6:9], off
	v_add_u32_e32 v10, 24, v38
	v_ashrrev_i32_e32 v11, 31, v10
	v_lshlrev_b64 v[10:11], 11, v[10:11]
	v_cvt_pk_bf16_f32 v6, v15, v13
	v_cvt_pk_bf16_f32 v7, v27, v29
	v_cvt_pk_bf16_f32 v8, v31, v33
	v_cvt_pk_bf16_f32 v9, v35, v41
	v_lshl_add_u64 v[10:11], v[36:37], 0, v[10:11]
	global_store_dwordx4 v[10:11], v[6:9], off
	s_waitcnt lgkmcnt(0)
	s_cbranch_scc0 .LBB0_614

; #define LAS __attribute__((address_space(3)))
; template <class Fn>
; __device__ __forceinline__ void prep_mat(bf16_t* dst, int NR, int KC, int ldd, const Fn f, int& gw, int NGW, LAS float* scr, int lane) {
;     const int nnb = NR / 32, ntile = nnb * (KC / 64);
;     const int gw0 = gw; gw = (gw0 + NGW - ntile % NGW) % NGW;
;     for (int it = gw0; it < ntile; it += NGW) {
;         const int nb = it % nnb, kb = it / nnb, n0 = 32 * nb, k0 = 64 * kb;
; #pragma unroll 4
;         for (int i = 0; i < 32; ++i) { const int kk = 2 * i + (lane >> 5); scr[kk * 33 + (lane & 31)] = f(n0 + (lane & 31), k0 + kk); }
; __device__ __forceinline__ void prep_rwkv(const LAS unsigned* PL, int idx, bf16_t* WR2, bf16_t* WR3, bf16_t* WG, bf16_t* WO, int gw, int NGW, LAS float* scr, int lane) {
;     ...
;         prep_mat(WO, D, D, D, [=](int n, int k) -> float { return w_o[(size_t)k * D + n]; }, gw, NGW, scr, lane);
.LBB0_754:
	v_lshl_add_u64 v[24:25], v[12:13], 0, s[6:7]
	global_load_dword v156, v[24:25], off
	v_lshl_add_u64 v[24:25], v[10:11], 0, s[6:7]
	global_load_dword v157, v[24:25], off
	v_lshl_add_u64 v[24:25], v[8:9], 0, s[6:7]
	s_add_u32 s6, s6, 0x8000
	s_addc_u32 s7, s7, 0
	s_cmp_eq_u32 s6, 0x40000
	global_load_dword v158, v[24:25], off
	v_ashrrev_i32_e32 v7, 31, v6
	v_lshlrev_b64 v[24:25], 12, v[6:7]
	v_lshl_add_u64 v[24:25], v[4:5], 0, v[24:25]
	v_add_u32_e32 v6, 8, v6
	global_load_dword v159, v[24:25], off
	v_lshl_add_u64 v[24:25], v[12:13], 0, s[6:7]
	global_load_dword v160, v[24:25], off
	v_lshl_add_u64 v[24:25], v[10:11], 0, s[6:7]
	global_load_dword v161, v[24:25], off
	v_lshl_add_u64 v[24:25], v[8:9], 0, s[6:7]
	s_add_u32 s6, s6, 0x8000
	s_addc_u32 s7, s7, 0
	s_cmp_eq_u32 s6, 0x40000
	global_load_dword v162, v[24:25], off
	v_ashrrev_i32_e32 v7, 31, v6
	v_lshlrev_b64 v[24:25], 12, v[6:7]
	v_lshl_add_u64 v[24:25], v[4:5], 0, v[24:25]
	v_add_u32_e32 v6, 8, v6
	global_load_dword v163, v[24:25], off
	v_lshl_add_u64 v[24:25], v[12:13], 0, s[6:7]
	global_load_dword v164, v[24:25], off
	v_lshl_add_u64 v[24:25], v[10:11], 0, s[6:7]
	global_load_dword v165, v[24:25], off
	v_lshl_add_u64 v[24:25], v[8:9], 0, s[6:7]
	s_add_u32 s6, s6, 0x8000
	s_addc_u32 s7, s7, 0
	s_cmp_eq_u32 s6, 0x40000
	global_load_dword v166, v[24:25], off
	v_ashrrev_i32_e32 v7, 31, v6
	v_lshlrev_b64 v[24:25], 12, v[6:7]
	v_lshl_add_u64 v[24:25], v[4:5], 0, v[24:25]
	v_add_u32_e32 v6, 8, v6
	global_load_dword v167, v[24:25], off
	v_lshl_add_u64 v[24:25], v[12:13], 0, s[6:7]
	global_load_dword v168, v[24:25], off
	v_lshl_add_u64 v[24:25], v[10:11], 0, s[6:7]
	global_load_dword v169, v[24:25], off
	v_lshl_add_u64 v[24:25], v[8:9], 0, s[6:7]
	s_add_u32 s6, s6, 0x8000
	s_addc_u32 s7, s7, 0
	s_cmp_eq_u32 s6, 0x40000
	global_load_dword v170, v[24:25], off
	v_ashrrev_i32_e32 v7, 31, v6
	v_lshlrev_b64 v[24:25], 12, v[6:7]
	v_lshl_add_u64 v[24:25], v[4:5], 0, v[24:25]
	v_add_u32_e32 v6, 8, v6
	global_load_dword v171, v[24:25], off
	v_lshl_add_u64 v[24:25], v[12:13], 0, s[6:7]
	global_load_dword v172, v[24:25], off
	v_lshl_add_u64 v[24:25], v[10:11], 0, s[6:7]
	global_load_dword v173, v[24:25], off
	v_lshl_add_u64 v[24:25], v[8:9], 0, s[6:7]
	s_add_u32 s6, s6, 0x8000
	s_addc_u32 s7, s7, 0
	s_cmp_eq_u32 s6, 0x40000
	global_load_dword v174, v[24:25], off
	v_ashrrev_i32_e32 v7, 31, v6
	v_lshlrev_b64 v[24:25], 12, v[6:7]
	v_lshl_add_u64 v[24:25], v[4:5], 0, v[24:25]
	v_add_u32_e32 v6, 8, v6
	global_load_dword v175, v[24:25], off
	v_lshl_add_u64 v[24:25], v[12:13], 0, s[6:7]
	global_load_dword v182, v[24:25], off
	v_lshl_add_u64 v[24:25], v[10:11], 0, s[6:7]
	global_load_dword v183, v[24:25], off
	v_lshl_add_u64 v[24:25], v[8:9], 0, s[6:7]
	s_add_u32 s6, s6, 0x8000
	s_addc_u32 s7, s7, 0
	s_cmp_eq_u32 s6, 0x40000
	global_load_dword v184, v[24:25], off
	v_ashrrev_i32_e32 v7, 31, v6
	v_lshlrev_b64 v[24:25], 12, v[6:7]
	v_lshl_add_u64 v[24:25], v[4:5], 0, v[24:25]
	v_add_u32_e32 v6, 8, v6
	global_load_dword v185, v[24:25], off
	v_lshl_add_u64 v[24:25], v[12:13], 0, s[6:7]
	global_load_dword v186, v[24:25], off
	v_lshl_add_u64 v[24:25], v[10:11], 0, s[6:7]
	global_load_dword v187, v[24:25], off
	v_lshl_add_u64 v[24:25], v[8:9], 0, s[6:7]
	s_add_u32 s6, s6, 0x8000
	s_addc_u32 s7, s7, 0
	s_cmp_eq_u32 s6, 0x40000
	global_load_dword v188, v[24:25], off
	v_ashrrev_i32_e32 v7, 31, v6
	v_lshlrev_b64 v[24:25], 12, v[6:7]
	v_lshl_add_u64 v[24:25], v[4:5], 0, v[24:25]
	v_add_u32_e32 v6, 8, v6
	global_load_dword v189, v[24:25], off
	v_lshl_add_u64 v[24:25], v[12:13], 0, s[6:7]
	global_load_dword v190, v[24:25], off
	v_lshl_add_u64 v[24:25], v[10:11], 0, s[6:7]
	global_load_dword v191, v[24:25], off
	v_lshl_add_u64 v[24:25], v[8:9], 0, s[6:7]
	s_add_u32 s6, s6, 0x8000
	s_addc_u32 s7, s7, 0
	s_cmp_eq_u32 s6, 0x40000
	global_load_dword v192, v[24:25], off
	v_ashrrev_i32_e32 v7, 31, v6
	v_lshlrev_b64 v[24:25], 12, v[6:7]
	v_lshl_add_u64 v[24:25], v[4:5], 0, v[24:25]
	v_add_u32_e32 v6, 8, v6
	global_load_dword v193, v[24:25], off
	s_waitcnt vmcnt(31)
	ds_write_b32 v22, v156
	s_waitcnt vmcnt(30)
	ds_write_b32 v22, v157 offset:264
	s_waitcnt vmcnt(29)
; #define LAS __attribute__((address_space(3)))
; #define GAS __attribute__((address_space(1)))
; __device__ __forceinline__ unsigned cvt_pk_bf16(float lo, float hi) { const f32x2 v = {lo, hi}; return __builtin_bit_cast(unsigned, __builtin_convertvector(v, b16x2_t)); }
; #define LDS_WAIT() asm volatile("s_waitcnt lgkmcnt(0)" ::: "memory")
; template <class Fn>
; __device__ __forceinline__ void prep_mat(bf16_t* dst, int NR, int KC, int ldd, const Fn f, int& gw, int NGW, LAS float* scr, int lane) {
;     ...
;         for (int i = 0; i < 32; ++i) { const int kk = 2 * i + (lane >> 5); scr[kk * 33 + (lane & 31)] = f(n0 + (lane & 31), k0 + kk); }
;         LDS_WAIT(); asm volatile("" ::: "memory");
;         const int c = lane & 7;
; #pragma unroll
;         for (int j = 0; j < 4; ++j) { const int n = (lane >> 3) + 8 * j; const LAS float* s = scr + (8 * c) * 33 + n;
;             u32x4 o; o.x = cvt_pk_bf16(s[0 * 33], s[1 * 33]); o.y = cvt_pk_bf16(s[2 * 33], s[3 * 33]); o.z = cvt_pk_bf16(s[4 * 33], s[5 * 33]); o.w = cvt_pk_bf16(s[6 * 33], s[7 * 33]);
;             *(GAS u32x4*)(dst + (size_t)(n0 + n) * ldd + k0 + 8 * c) = o; }
;         LDS_WAIT(); asm volatile("" ::: "memory");
;     }
	ds_write_b32 v22, v158 offset:528
	s_waitcnt vmcnt(28)
	ds_write_b32 v22, v159 offset:792
	s_waitcnt vmcnt(27)
	ds_write_b32 v22, v160 offset:1056
	s_waitcnt vmcnt(26)
	ds_write_b32 v22, v161 offset:1320
	s_waitcnt vmcnt(25)
	ds_write_b32 v22, v162 offset:1584
	s_waitcnt vmcnt(24)
	ds_write_b32 v22, v163 offset:1848
	s_waitcnt vmcnt(23)
	ds_write_b32 v22, v164 offset:2112
	s_waitcnt vmcnt(22)
	ds_write_b32 v22, v165 offset:2376
	s_waitcnt vmcnt(21)
	ds_write_b32 v22, v166 offset:2640
	s_waitcnt vmcnt(20)
	ds_write_b32 v22, v167 offset:2904
	s_waitcnt vmcnt(19)
	ds_write_b32 v22, v168 offset:3168
	s_waitcnt vmcnt(18)
	ds_write_b32 v22, v169 offset:3432
	s_waitcnt vmcnt(17)
	ds_write_b32 v22, v170 offset:3696
	s_waitcnt vmcnt(16)
	ds_write_b32 v22, v171 offset:3960
	s_waitcnt vmcnt(15)
	ds_write_b32 v22, v172 offset:4224
	s_waitcnt vmcnt(14)
	ds_write_b32 v22, v173 offset:4488
	s_waitcnt vmcnt(13)
	ds_write_b32 v22, v174 offset:4752
	s_waitcnt vmcnt(12)
	ds_write_b32 v22, v175 offset:5016
	s_waitcnt vmcnt(11)
	ds_write_b32 v22, v182 offset:5280
	s_waitcnt vmcnt(10)
	ds_write_b32 v22, v183 offset:5544
	s_waitcnt vmcnt(9)
	ds_write_b32 v22, v184 offset:5808
	s_waitcnt vmcnt(8)
	ds_write_b32 v22, v185 offset:6072
	s_waitcnt vmcnt(7)
	ds_write_b32 v22, v186 offset:6336
	s_waitcnt vmcnt(6)
	ds_write_b32 v22, v187 offset:6600
	s_waitcnt vmcnt(5)
	ds_write_b32 v22, v188 offset:6864
	s_waitcnt vmcnt(4)
	ds_write_b32 v22, v189 offset:7128
	s_waitcnt vmcnt(3)
	ds_write_b32 v22, v190 offset:7392
	s_waitcnt vmcnt(2)
	ds_write_b32 v22, v191 offset:7656
	s_waitcnt vmcnt(1)
	ds_write_b32 v22, v192 offset:7920
	s_waitcnt vmcnt(0)
	ds_write_b32 v22, v193 offset:8184
	v_add_u32_e32 v22, 0x2100, v22
	s_waitcnt lgkmcnt(0)
	ds_read2_b32 v[8:9], v14 offset0:33 offset1:41
	ds_read2_b32 v[10:11], v14 offset1:8
	ds_read2_b32 v[12:13], v14 offset0:66 offset1:74
	ds_read2_b32 v[22:23], v14 offset0:99 offset1:107
	ds_read2_b32 v[24:25], v14 offset0:132 offset1:140
	ds_read2_b32 v[26:27], v14 offset0:165 offset1:173
	ds_read2_b32 v[28:29], v14 offset0:198 offset1:206
	ds_read2_b32 v[30:31], v14 offset0:231 offset1:239
	v_add_u32_e32 v34, s11, v18
	v_ashrrev_i32_e32 v35, 31, v34
	v_lshl_add_u64 v[32:33], s[4:5], 1, v[2:3]
	v_lshlrev_b64 v[36:37], 11, v[34:35]
	s_waitcnt lgkmcnt(6)
	v_cvt_pk_bf16_f32 v4, v10, v8
	s_waitcnt lgkmcnt(4)
	v_cvt_pk_bf16_f32 v5, v12, v22
	s_waitcnt lgkmcnt(2)
	v_cvt_pk_bf16_f32 v6, v24, v26
	s_waitcnt lgkmcnt(0)
	v_cvt_pk_bf16_f32 v7, v28, v30
	v_lshl_add_u64 v[36:37], v[32:33], 0, v[36:37]
	v_add_u32_e32 v8, 8, v34
	global_store_dwordx4 v[36:37], v[4:7], off
	s_add_i32 s10, s10, s43
	s_cmpk_gt_i32 s10, 0x1ff
	v_cvt_pk_bf16_f32 v4, v11, v9
	v_ashrrev_i32_e32 v9, 31, v8
	v_cvt_pk_bf16_f32 v5, v13, v23
	v_cvt_pk_bf16_f32 v6, v25, v27
	v_cvt_pk_bf16_f32 v7, v29, v31
	v_lshlrev_b64 v[8:9], 11, v[8:9]
	ds_read2_b32 v[10:11], v14 offset0:49 offset1:57
	ds_read2_b32 v[12:13], v14 offset0:16 offset1:24
	ds_read2_b32 v[22:23], v14 offset0:82 offset1:90
	ds_read2_b32 v[24:25], v14 offset0:115 offset1:123
	ds_read2_b32 v[26:27], v14 offset0:148 offset1:156
	ds_read2_b32 v[28:29], v14 offset0:181 offset1:189
	ds_read2_b32 v[30:31], v14 offset0:214 offset1:222
	ds_read2_b32 v[36:37], v14 offset0:247 offset1:255
	v_lshl_add_u64 v[8:9], v[32:33], 0, v[8:9]
	global_store_dwordx4 v[8:9], v[4:7], off
	v_add_u32_e32 v8, 16, v34
	v_ashrrev_i32_e32 v9, 31, v8
	v_lshlrev_b64 v[8:9], 11, v[8:9]
	s_waitcnt lgkmcnt(6)
	v_cvt_pk_bf16_f32 v4, v12, v10
	s_waitcnt lgkmcnt(4)
	v_cvt_pk_bf16_f32 v5, v22, v24
	s_waitcnt lgkmcnt(2)
	v_cvt_pk_bf16_f32 v6, v26, v28
	s_waitcnt lgkmcnt(0)
	v_cvt_pk_bf16_f32 v7, v30, v36
	v_lshl_add_u64 v[8:9], v[32:33], 0, v[8:9]
	global_store_dwordx4 v[8:9], v[4:7], off
	v_add_u32_e32 v8, 24, v34
	v_ashrrev_i32_e32 v9, 31, v8
	v_lshlrev_b64 v[8:9], 11, v[8:9]
	v_cvt_pk_bf16_f32 v4, v13, v11
	v_cvt_pk_bf16_f32 v5, v23, v25
	v_cvt_pk_bf16_f32 v6, v27, v29
	v_cvt_pk_bf16_f32 v7, v31, v37
	v_lshl_add_u64 v[8:9], v[32:33], 0, v[8:9]
	global_store_dwordx4 v[8:9], v[4:7], off
	s_waitcnt lgkmcnt(0)
	s_cbranch_scc0 .LBB0_753
	v_mov_b32_e32 v48, v17

; #define GAS __attribute__((address_space(1)))
; __device__ __forceinline__ void scan_phase2(LAS unsigned char* lds, const int wid, const bf16_t* R, const bf16_t* K, const bf16_t* V, const bf16_t* W, const bf16_t* A,
;                                             const float* k_k, const float* k_a, const float* r_k, bf16_t* Y, float* BON) {
;     ...
;             const int j = lane >> 2, v8 = (lane & 3) * 8;
;             const size_t gv = (tokb + j) * D + h * 64 + half * 32 + v8;
;             u32x4 vr = *(const GAS u32x4*)(V + gv);
;             const bf16_t* Wl = W + tokb * D + h * 64 + lane;
;             bf16_t ewl[16];
; #pragma unroll
;             for (int i = 0; i < 16; ++i) ewl[i] = Wl[(size_t)(CL + i) * D];
.LBB0_1244:
	s_andn2_b64 vcc, exec, s[54:55]
	s_cbranch_vccnz .LBB0_1253
	v_lshl_add_u64 v[0:1], s[20:21], 0, v[36:37]
	v_lshlrev_b64 v[0:1], 11, v[0:1]
	v_lshl_add_u64 v[0:1], s[28:29], 0, v[0:1]
	s_lshl_b32 s30, s86, 6
	v_lshl_add_u64 v[0:1], v[0:1], 0, s[30:31]
	s_lshl_b32 s30, s85, 7
	s_lshl_b64 s[20:21], s[24:25], 23
	s_add_u32 s0, s42, s20
	s_addc_u32 s1, s43, s21
	s_add_u32 s54, s0, s30
	s_addc_u32 s55, s1, 0
	v_lshl_add_u64 v[4:5], v[16:17], 1, s[54:55]
	v_add_co_u32_e32 v6, vcc, s76, v4
	v_mov_b32_e32 v45, v25
	s_nop 0
	v_addc_co_u32_e32 v7, vcc, 0, v5, vcc
	v_add_co_u32_e32 v12, vcc, s77, v4
	v_lshl_add_u64 v[0:1], v[0:1], 0, v[44:45]
	s_nop 0
	v_addc_co_u32_e32 v13, vcc, 0, v5, vcc
	v_add_co_u32_e32 v14, vcc, s78, v4
	v_lshl_add_u64 v[0:1], v[0:1], 0, s[30:31]
	s_nop 0
	v_addc_co_u32_e32 v15, vcc, 0, v5, vcc
	v_add_co_u32_e32 v46, vcc, s79, v4
	global_load_dwordx4 v[0:3], v[0:1], off
	s_nop 0
	v_addc_co_u32_e32 v47, vcc, 0, v5, vcc
	global_load_ushort v8, v[6:7], off
	global_load_ushort v9, v[6:7], off offset:2048
	global_load_ushort v10, v[12:13], off
	global_load_ushort v11, v[12:13], off offset:2048
	s_nop 0
	global_load_ushort v12, v[14:15], off
	global_load_ushort v13, v[14:15], off offset:2048
	s_nop 0
	global_load_ushort v14, v[46:47], off
	global_load_ushort v15, v[46:47], off offset:2048
	v_add_co_u32_e32 v6, vcc, s80, v4
	s_or_b64 s[20:21], s[20:21], s[52:53]
	s_nop 0
	v_addc_co_u32_e32 v7, vcc, 0, v5, vcc
	v_add_co_u32_e32 v48, vcc, s81, v4
	s_mov_b32 s30, 0
	s_nop 0
	v_addc_co_u32_e32 v49, vcc, 0, v5, vcc
	v_add_co_u32_e32 v50, vcc, s82, v4
	s_movk_i32 s54, 0x1000
	s_nop 0
	v_addc_co_u32_e32 v51, vcc, 0, v5, vcc
	v_add_co_u32_e32 v4, vcc, 0xf000, v4
	s_nop 1
	v_addc_co_u32_e32 v5, vcc, 0, v5, vcc
	global_load_ushort v45, v[6:7], off
	global_load_ushort v46, v[6:7], off offset:2048
	global_load_ushort v47, v[48:49], off
	s_nop 0
	global_load_ushort v48, v[48:49], off offset:2048
	s_nop 0
	global_load_ushort v49, v[50:51], off
	s_nop 0
	global_load_ushort v50, v[50:51], off offset:2048
	s_nop 0
	global_load_ushort v51, v[4:5], off
	global_load_ushort v52, v[4:5], off offset:2048
	v_cndmask_b32_e64 v4, 0, 1, s[44:45]
	v_lshlrev_b32_e32 v24, 6, v4
	v_lshl_add_u64 v[6:7], s[20:21], 0, v[24:25]
	v_lshl_add_u64 v[4:5], v[40:41], 0, s[20:21]
	v_lshl_add_u64 v[6:7], v[42:43], 0, v[6:7]
	s_nop 0
	v_readfirstlane_b32 s88, v4
	v_readfirstlane_b32 s89, v5
	s_nop 3
	v_subrev_u32_e32 v149, s88, v4
	s_add_u32 s88, s88, 0x15800000
	s_addc_u32 s89, s89, 0
	s_add_u32 s56, s88, 0x10000
	s_addc_u32 s57, s89, 0
	global_load_ushort v150, v149, s[56:57]
	global_load_ushort v151, v149, s[56:57] offset:2048
	s_add_u32 s56, s56, 0x1000
	s_addc_u32 s57, s57, 0
	global_load_ushort v152, v149, s[56:57]
	global_load_ushort v153, v149, s[56:57] offset:2048
	s_add_u32 s56, s56, 0x1000
	s_addc_u32 s57, s57, 0
	global_load_ushort v154, v149, s[56:57]
	global_load_ushort v155, v149, s[56:57] offset:2048
	s_add_u32 s56, s56, 0x1000
	s_addc_u32 s57, s57, 0
	global_load_ushort v156, v149, s[56:57]
	global_load_ushort v157, v149, s[56:57] offset:2048
	s_add_u32 s56, s56, 0x1000
	s_addc_u32 s57, s57, 0
	global_load_ushort v158, v149, s[56:57]
	global_load_ushort v159, v149, s[56:57] offset:2048
	s_add_u32 s56, s56, 0x1000
	s_addc_u32 s57, s57, 0
	global_load_ushort v160, v149, s[56:57]
	global_load_ushort v161, v149, s[56:57] offset:2048
	s_add_u32 s56, s56, 0x1000
	s_addc_u32 s57, s57, 0
	global_load_ushort v162, v149, s[56:57]
	global_load_ushort v163, v149, s[56:57] offset:2048
	s_add_u32 s56, s56, 0x1000
	s_addc_u32 s57, s57, 0
	global_load_ushort v164, v149, s[56:57]
	global_load_ushort v165, v149, s[56:57] offset:2048
	s_mov_b64 s[20:21], 0
	s_branch .LBB0_1247

; #define LAS __attribute__((address_space(3)))
; __device__ __forceinline__ void scan_phase2(LAS unsigned char* lds, const int wid, const bf16_t* R, const bf16_t* K, const bf16_t* V, const bf16_t* W, const bf16_t* A,
;                                             const float* k_k, const float* k_a, const float* r_k, bf16_t* Y, float* BON) {
;     ...
;             for (int it = 0; it < NCH + 2; ++it) {
;                 if (it < NCH) {
;                     LAS unsigned char* vt = lds + L_P + (it % 3) * P_SIZE + P_VT + (v8 * 20 + j) * 2;
.LBB0_1247:
	s_cmpk_gt_u32 s30, 0xff
	s_cbranch_scc1 .LBB0_1246
	s_mul_i32 s0, s30, 0xab
	s_bfe_u32 s0, s0, 0x70009
	s_mul_i32 s0, s0, 3
	s_sub_i32 s0, s30, s0
	s_and_b32 s0, s0, 0xff
	s_mulk_i32 s0, 0x3e00
	v_add_u32_e32 v24, s0, v115
	s_cmpk_gt_u32 s30, 0xfd
	s_cbranch_scc1 .Lw7a_w0
	s_waitcnt vmcnt(16)
	s_branch .Lw7a_vt

; #define LAS __attribute__((address_space(3)))
; #define GAS __attribute__((address_space(1)))
; #define SC2_BAR() do { asm volatile("s_waitcnt lgkmcnt(0)" ::: "memory"); __builtin_amdgcn_s_barrier(); asm volatile("" ::: "memory"); } while (0)
; __device__ __forceinline__ void scan_phase2(LAS unsigned char* lds, const int wid, const bf16_t* R, const bf16_t* K, const bf16_t* V, const bf16_t* W, const bf16_t* A,
;                                             const float* k_k, const float* k_a, const float* r_k, bf16_t* Y, float* BON) {
;     ...
;             for (int it = 0; it < NCH + 2; ++it) {
;                 if (it < NCH) {
;                     LAS unsigned char* vt = lds + L_P + (it % 3) * P_SIZE + P_VT + (v8 * 20 + j) * 2;
;                     *(LAS bf16_t*)(vt + 0 * 40) = (bf16_t)(vr.x & 0xffff); *(LAS bf16_t*)(vt + 1 * 40) = (bf16_t)(vr.x >> 16);
;                     *(LAS bf16_t*)(vt + 2 * 40) = (bf16_t)(vr.y & 0xffff); *(LAS bf16_t*)(vt + 3 * 40) = (bf16_t)(vr.y >> 16);
;                     *(LAS bf16_t*)(vt + 4 * 40) = (bf16_t)(vr.z & 0xffff); *(LAS bf16_t*)(vt + 5 * 40) = (bf16_t)(vr.z >> 16);
;                     *(LAS bf16_t*)(vt + 6 * 40) = (bf16_t)(vr.w & 0xffff); *(LAS bf16_t*)(vt + 7 * 40) = (bf16_t)(vr.w >> 16);
;                 }
;                 if (it + 1 < NCH) {
;                     LAS float* CEn = (LAS float*)(lds + L_CE + ((it + 1) & 1) * 4096);
;                     float c = 0.f;
; #pragma unroll
;                     for (int i = 0; i < 16; ++i) { c += __uint_as_float((unsigned)ewl[i] << 16); CEn[i * 64 + lane] = c; }
;                     vr = *(const GAS u32x4*)(V + gv + (size_t)(it + 1) * CL * D);
;                 }
;                 if (it + 2 < NCH) {
; #pragma unroll
;                     for (int i = 0; i < 16; ++i) ewl[i] = Wl[(size_t)((it + 2) * CL + i) * D];
;                 }
;                 SC2_BAR();
;             }
.Lw7a_vt:
	ds_write_b16 v24, v0 offset:14336
	ds_write_b16_d16_hi v24, v0 offset:14376
	ds_write_b16 v24, v1 offset:14416
	ds_write_b16_d16_hi v24, v1 offset:14456
	ds_write_b16 v24, v2 offset:14496
	ds_write_b16_d16_hi v24, v2 offset:14536
	ds_write_b16 v24, v3 offset:14576
	ds_write_b16_d16_hi v24, v3 offset:14616
	s_cmpk_gt_u32 s30, 0xfe
	s_cbranch_scc1 .LBB0_1246
	v_lshl_add_u64 v[0:1], v[6:7], 0, s[20:21]
	global_load_dwordx4 v[0:3], v[0:1], off
	s_and_b32 s0, s54, 0x1000
	v_add_u32_e32 v24, s0, v68
	s_add_u32 s56, s88, s20
	s_addc_u32 s57, s89, s21
	s_add_u32 s56, s56, 0x18000
	s_addc_u32 s57, s57, 0
	s_bitcmp1_b32 s30, 0
	s_cbranch_scc1 .Lw7a_odd
	v_lshlrev_b32_e32 v53, 16, v8
	v_add_f32_e32 v53, 0, v53
	v_lshlrev_b32_e32 v54, 16, v9
	v_add_f32_e32 v54, v53, v54
	ds_write2st64_b32 v24, v53, v54 offset0:229 offset1:230
	v_lshlrev_b32_e32 v53, 16, v10
	v_add_f32_e32 v53, v54, v53
	v_lshlrev_b32_e32 v54, 16, v11
	v_add_f32_e32 v54, v53, v54
	ds_write2st64_b32 v24, v53, v54 offset0:231 offset1:232
	v_lshlrev_b32_e32 v53, 16, v12
	v_add_f32_e32 v53, v54, v53
	v_lshlrev_b32_e32 v54, 16, v13
	v_add_f32_e32 v54, v53, v54
	ds_write2st64_b32 v24, v53, v54 offset0:233 offset1:234
	v_lshlrev_b32_e32 v53, 16, v14
	v_add_f32_e32 v53, v54, v53
	v_lshlrev_b32_e32 v54, 16, v15
	v_add_f32_e32 v54, v53, v54
	ds_write2st64_b32 v24, v53, v54 offset0:235 offset1:236
	v_lshlrev_b32_e32 v53, 16, v45
	v_add_f32_e32 v53, v54, v53
	v_lshlrev_b32_e32 v54, 16, v46
	v_add_f32_e32 v54, v53, v54
	ds_write2st64_b32 v24, v53, v54 offset0:237 offset1:238
	v_lshlrev_b32_e32 v53, 16, v47
	v_add_f32_e32 v53, v54, v53
	v_lshlrev_b32_e32 v54, 16, v48
	v_add_f32_e32 v54, v53, v54
	ds_write2st64_b32 v24, v53, v54 offset0:239 offset1:240
	v_lshlrev_b32_e32 v53, 16, v49
	v_add_f32_e32 v53, v54, v53
	v_lshlrev_b32_e32 v54, 16, v50
	v_add_f32_e32 v54, v53, v54
	ds_write2st64_b32 v24, v53, v54 offset0:241 offset1:242
	v_lshlrev_b32_e32 v53, 16, v51
	v_add_f32_e32 v53, v54, v53
	v_lshlrev_b32_e32 v54, 16, v52
	v_add_f32_e32 v54, v53, v54
	ds_write2st64_b32 v24, v53, v54 offset0:243 offset1:244
	s_cmpk_gt_u32 s30, 0xfc
	s_cbranch_scc1 .LBB0_1246
	global_load_ushort v8, v149, s[56:57]
	global_load_ushort v9, v149, s[56:57] offset:2048
	s_add_u32 s56, s56, 0x1000
	s_addc_u32 s57, s57, 0
	global_load_ushort v10, v149, s[56:57]
	global_load_ushort v11, v149, s[56:57] offset:2048
	s_add_u32 s56, s56, 0x1000
	s_addc_u32 s57, s57, 0
	global_load_ushort v12, v149, s[56:57]
	global_load_ushort v13, v149, s[56:57] offset:2048
	s_add_u32 s56, s56, 0x1000
	s_addc_u32 s57, s57, 0
	global_load_ushort v14, v149, s[56:57]
	global_load_ushort v15, v149, s[56:57] offset:2048
	s_add_u32 s56, s56, 0x1000
	s_addc_u32 s57, s57, 0
	global_load_ushort v45, v149, s[56:57]
	global_load_ushort v46, v149, s[56:57] offset:2048
	s_add_u32 s56, s56, 0x1000
	s_addc_u32 s57, s57, 0
	global_load_ushort v47, v149, s[56:57]
	global_load_ushort v48, v149, s[56:57] offset:2048
	s_add_u32 s56, s56, 0x1000
	s_addc_u32 s57, s57, 0
	global_load_ushort v49, v149, s[56:57]
	global_load_ushort v50, v149, s[56:57] offset:2048
	s_add_u32 s56, s56, 0x1000
	s_addc_u32 s57, s57, 0
	global_load_ushort v51, v149, s[56:57]
	global_load_ushort v52, v149, s[56:57] offset:2048
	s_branch .LBB0_1246
.Lw7a_odd:
	v_lshlrev_b32_e32 v53, 16, v150
	v_add_f32_e32 v53, 0, v53
	v_lshlrev_b32_e32 v54, 16, v151
	v_add_f32_e32 v54, v53, v54
	ds_write2st64_b32 v24, v53, v54 offset0:229 offset1:230
	v_lshlrev_b32_e32 v53, 16, v152
	v_add_f32_e32 v53, v54, v53
	v_lshlrev_b32_e32 v54, 16, v153
	v_add_f32_e32 v54, v53, v54
	ds_write2st64_b32 v24, v53, v54 offset0:231 offset1:232
	v_lshlrev_b32_e32 v53, 16, v154
	v_add_f32_e32 v53, v54, v53
	v_lshlrev_b32_e32 v54, 16, v155
	v_add_f32_e32 v54, v53, v54
	ds_write2st64_b32 v24, v53, v54 offset0:233 offset1:234
	v_lshlrev_b32_e32 v53, 16, v156
	v_add_f32_e32 v53, v54, v53
	v_lshlrev_b32_e32 v54, 16, v157
	v_add_f32_e32 v54, v53, v54
	ds_write2st64_b32 v24, v53, v54 offset0:235 offset1:236
	v_lshlrev_b32_e32 v53, 16, v158
	v_add_f32_e32 v53, v54, v53
	v_lshlrev_b32_e32 v54, 16, v159
	v_add_f32_e32 v54, v53, v54
	ds_write2st64_b32 v24, v53, v54 offset0:237 offset1:238
	v_lshlrev_b32_e32 v53, 16, v160
	v_add_f32_e32 v53, v54, v53
	v_lshlrev_b32_e32 v54, 16, v161
	v_add_f32_e32 v54, v53, v54
	ds_write2st64_b32 v24, v53, v54 offset0:239 offset1:240
	v_lshlrev_b32_e32 v53, 16, v162
	v_add_f32_e32 v53, v54, v53
	v_lshlrev_b32_e32 v54, 16, v163
	v_add_f32_e32 v54, v53, v54
	ds_write2st64_b32 v24, v53, v54 offset0:241 offset1:242
	v_lshlrev_b32_e32 v53, 16, v164
	v_add_f32_e32 v53, v54, v53
	v_lshlrev_b32_e32 v54, 16, v165
	v_add_f32_e32 v54, v53, v54
	ds_write2st64_b32 v24, v53, v54 offset0:243 offset1:244
	s_cmpk_gt_u32 s30, 0xfc
	s_cbranch_scc1 .LBB0_1246
	global_load_ushort v150, v149, s[56:57]
	global_load_ushort v151, v149, s[56:57] offset:2048
	s_add_u32 s56, s56, 0x1000
	s_addc_u32 s57, s57, 0
	global_load_ushort v152, v149, s[56:57]
	global_load_ushort v153, v149, s[56:57] offset:2048
	s_add_u32 s56, s56, 0x1000
	s_addc_u32 s57, s57, 0
	global_load_ushort v154, v149, s[56:57]
	global_load_ushort v155, v149, s[56:57] offset:2048
	s_add_u32 s56, s56, 0x1000
	s_addc_u32 s57, s57, 0
	global_load_ushort v156, v149, s[56:57]
	global_load_ushort v157, v149, s[56:57] offset:2048
	s_add_u32 s56, s56, 0x1000
	s_addc_u32 s57, s57, 0
	global_load_ushort v158, v149, s[56:57]
	global_load_ushort v159, v149, s[56:57] offset:2048
	s_add_u32 s56, s56, 0x1000
	s_addc_u32 s57, s57, 0
	global_load_ushort v160, v149, s[56:57]
	global_load_ushort v161, v149, s[56:57] offset:2048
	s_add_u32 s56, s56, 0x1000
	s_addc_u32 s57, s57, 0
	global_load_ushort v162, v149, s[56:57]
	global_load_ushort v163, v149, s[56:57] offset:2048
	s_add_u32 s56, s56, 0x1000
	s_addc_u32 s57, s57, 0
	global_load_ushort v164, v149, s[56:57]
	global_load_ushort v165, v149, s[56:57] offset:2048
	s_branch .LBB0_1246

; #define LAS __attribute__((address_space(3)))
; template <class Fn>
; __device__ __forceinline__ void prep_mat(bf16_t* dst, int NR, int KC, int ldd, const Fn f, int& gw, int NGW, LAS float* scr, int lane) {
;     const int nnb = NR / 32, ntile = nnb * (KC / 64);
;     const int gw0 = gw; gw = (gw0 + NGW - ntile % NGW) % NGW;
;     for (int it = gw0; it < ntile; it += NGW) {
;         const int nb = it % nnb, kb = it / nnb, n0 = 32 * nb, k0 = 64 * kb;
; #pragma unroll 4
;         for (int i = 0; i < 32; ++i) { const int kk = 2 * i + (lane >> 5); scr[kk * 33 + (lane & 31)] = f(n0 + (lane & 31), k0 + kk); }
; __device__ __forceinline__ void prep_ffn(const float* wg, const float* wu, const float* wd, bf16_t* WGU, bf16_t* WD, int gw, int NGW, LAS float* scr, int lane) {
;     prep_mat(WGU, 2 * F, D, D, [=](int n, int k) -> float {
;         const int pn = n >> 8, p = n & 255, f = pn * 128 + (p & 127);
;         const float* src = (p >> 7) ? wu : wg; return src[(size_t)k * F + f]; }, gw, NGW, scr, lane);
.LBB0_1458:
	v_lshl_add_u64 v[22:23], v[10:11], 0, s[6:7]
	global_load_dword v40, v[22:23], off
	v_lshl_add_u64 v[22:23], v[8:9], 0, s[6:7]
	global_load_dword v41, v[22:23], off
	v_lshl_add_u64 v[22:23], v[6:7], 0, s[6:7]
	global_load_dword v42, v[22:23], off
	v_lshl_add_u64 v[22:23], v[4:5], 0, s[6:7]
	s_add_u32 s6, s6, 0x16000
	s_addc_u32 s7, s7, 0
	s_cmp_eq_u32 s6, 0xb0000
	global_load_dword v43, v[22:23], off
	v_lshl_add_u64 v[22:23], v[10:11], 0, s[6:7]
	global_load_dword v44, v[22:23], off
	v_lshl_add_u64 v[22:23], v[8:9], 0, s[6:7]
	global_load_dword v45, v[22:23], off
	v_lshl_add_u64 v[22:23], v[6:7], 0, s[6:7]
	global_load_dword v46, v[22:23], off
	v_lshl_add_u64 v[22:23], v[4:5], 0, s[6:7]
	s_add_u32 s6, s6, 0x16000
	s_addc_u32 s7, s7, 0
	s_cmp_eq_u32 s6, 0xb0000
	global_load_dword v47, v[22:23], off
	v_lshl_add_u64 v[22:23], v[10:11], 0, s[6:7]
	global_load_dword v48, v[22:23], off
	v_lshl_add_u64 v[22:23], v[8:9], 0, s[6:7]
	global_load_dword v49, v[22:23], off
	v_lshl_add_u64 v[22:23], v[6:7], 0, s[6:7]
	global_load_dword v50, v[22:23], off
	v_lshl_add_u64 v[22:23], v[4:5], 0, s[6:7]
	s_add_u32 s6, s6, 0x16000
	s_addc_u32 s7, s7, 0
	s_cmp_eq_u32 s6, 0xb0000
	global_load_dword v51, v[22:23], off
	v_lshl_add_u64 v[22:23], v[10:11], 0, s[6:7]
	global_load_dword v52, v[22:23], off
	v_lshl_add_u64 v[22:23], v[8:9], 0, s[6:7]
	global_load_dword v53, v[22:23], off
	v_lshl_add_u64 v[22:23], v[6:7], 0, s[6:7]
	global_load_dword v54, v[22:23], off
	v_lshl_add_u64 v[22:23], v[4:5], 0, s[6:7]
	s_add_u32 s6, s6, 0x16000
	s_addc_u32 s7, s7, 0
	s_cmp_eq_u32 s6, 0xb0000
	global_load_dword v55, v[22:23], off
	v_lshl_add_u64 v[22:23], v[10:11], 0, s[6:7]
	global_load_dword v56, v[22:23], off
	v_lshl_add_u64 v[22:23], v[8:9], 0, s[6:7]
	global_load_dword v57, v[22:23], off
	v_lshl_add_u64 v[22:23], v[6:7], 0, s[6:7]
	global_load_dword v58, v[22:23], off
	v_lshl_add_u64 v[22:23], v[4:5], 0, s[6:7]
	s_add_u32 s6, s6, 0x16000
	s_addc_u32 s7, s7, 0
	s_cmp_eq_u32 s6, 0xb0000
	global_load_dword v59, v[22:23], off
	v_lshl_add_u64 v[22:23], v[10:11], 0, s[6:7]
	global_load_dword v60, v[22:23], off
	v_lshl_add_u64 v[22:23], v[8:9], 0, s[6:7]
	global_load_dword v61, v[22:23], off
	v_lshl_add_u64 v[22:23], v[6:7], 0, s[6:7]
	global_load_dword v62, v[22:23], off
	v_lshl_add_u64 v[22:23], v[4:5], 0, s[6:7]
	s_add_u32 s6, s6, 0x16000
	s_addc_u32 s7, s7, 0
	s_cmp_eq_u32 s6, 0xb0000
	global_load_dword v63, v[22:23], off
	v_lshl_add_u64 v[22:23], v[10:11], 0, s[6:7]
	global_load_dword v64, v[22:23], off
	v_lshl_add_u64 v[22:23], v[8:9], 0, s[6:7]
	global_load_dword v65, v[22:23], off
	v_lshl_add_u64 v[22:23], v[6:7], 0, s[6:7]
	global_load_dword v66, v[22:23], off
	v_lshl_add_u64 v[22:23], v[4:5], 0, s[6:7]
	s_add_u32 s6, s6, 0x16000
	s_addc_u32 s7, s7, 0
	s_cmp_eq_u32 s6, 0xb0000
	global_load_dword v67, v[22:23], off
	v_lshl_add_u64 v[22:23], v[10:11], 0, s[6:7]
	global_load_dword v68, v[22:23], off
	v_lshl_add_u64 v[22:23], v[8:9], 0, s[6:7]
	global_load_dword v69, v[22:23], off
	v_lshl_add_u64 v[22:23], v[6:7], 0, s[6:7]
	global_load_dword v70, v[22:23], off
	v_lshl_add_u64 v[22:23], v[4:5], 0, s[6:7]
	s_add_u32 s6, s6, 0x16000
	s_addc_u32 s7, s7, 0
	s_cmp_eq_u32 s6, 0xb0000
	global_load_dword v71, v[22:23], off
	s_waitcnt vmcnt(31)
	ds_write_b32 v21, v40
	s_waitcnt vmcnt(30)
	ds_write_b32 v21, v41 offset:264
	s_waitcnt vmcnt(29)
	ds_write_b32 v21, v42 offset:528
	s_waitcnt vmcnt(28)
	ds_write_b32 v21, v43 offset:792
	s_waitcnt vmcnt(27)
	ds_write_b32 v21, v44 offset:1056
	s_waitcnt vmcnt(26)
	ds_write_b32 v21, v45 offset:1320
	s_waitcnt vmcnt(25)
	ds_write_b32 v21, v46 offset:1584
	s_waitcnt vmcnt(24)
	ds_write_b32 v21, v47 offset:1848
	s_waitcnt vmcnt(23)
; #define LAS __attribute__((address_space(3)))
; #define GAS __attribute__((address_space(1)))
; __device__ __forceinline__ unsigned cvt_pk_bf16(float lo, float hi) { const f32x2 v = {lo, hi}; return __builtin_bit_cast(unsigned, __builtin_convertvector(v, b16x2_t)); }
; #define LDS_WAIT() asm volatile("s_waitcnt lgkmcnt(0)" ::: "memory")
; template <class Fn>
; __device__ __forceinline__ void prep_mat(bf16_t* dst, int NR, int KC, int ldd, const Fn f, int& gw, int NGW, LAS float* scr, int lane) {
;     ...
;         for (int i = 0; i < 32; ++i) { const int kk = 2 * i + (lane >> 5); scr[kk * 33 + (lane & 31)] = f(n0 + (lane & 31), k0 + kk); }
;         LDS_WAIT(); asm volatile("" ::: "memory");
;         const int c = lane & 7;
; #pragma unroll
;         for (int j = 0; j < 4; ++j) { const int n = (lane >> 3) + 8 * j; const LAS float* s = scr + (8 * c) * 33 + n;
;             u32x4 o; o.x = cvt_pk_bf16(s[0 * 33], s[1 * 33]); o.y = cvt_pk_bf16(s[2 * 33], s[3 * 33]); o.z = cvt_pk_bf16(s[4 * 33], s[5 * 33]); o.w = cvt_pk_bf16(s[6 * 33], s[7 * 33]);
;             *(GAS u32x4*)(dst + (size_t)(n0 + n) * ldd + k0 + 8 * c) = o; }
;         LDS_WAIT(); asm volatile("" ::: "memory");
;     }
	ds_write_b32 v21, v48 offset:2112
	s_waitcnt vmcnt(22)
	ds_write_b32 v21, v49 offset:2376
	s_waitcnt vmcnt(21)
	ds_write_b32 v21, v50 offset:2640
	s_waitcnt vmcnt(20)
	ds_write_b32 v21, v51 offset:2904
	s_waitcnt vmcnt(19)
	ds_write_b32 v21, v52 offset:3168
	s_waitcnt vmcnt(18)
	ds_write_b32 v21, v53 offset:3432
	s_waitcnt vmcnt(17)
	ds_write_b32 v21, v54 offset:3696
	s_waitcnt vmcnt(16)
	ds_write_b32 v21, v55 offset:3960
	s_waitcnt vmcnt(15)
	ds_write_b32 v21, v56 offset:4224
	s_waitcnt vmcnt(14)
	ds_write_b32 v21, v57 offset:4488
	s_waitcnt vmcnt(13)
	ds_write_b32 v21, v58 offset:4752
	s_waitcnt vmcnt(12)
	ds_write_b32 v21, v59 offset:5016
	s_waitcnt vmcnt(11)
	ds_write_b32 v21, v60 offset:5280
	s_waitcnt vmcnt(10)
	ds_write_b32 v21, v61 offset:5544
	s_waitcnt vmcnt(9)
	ds_write_b32 v21, v62 offset:5808
	s_waitcnt vmcnt(8)
	ds_write_b32 v21, v63 offset:6072
	s_waitcnt vmcnt(7)
	ds_write_b32 v21, v64 offset:6336
	s_waitcnt vmcnt(6)
	ds_write_b32 v21, v65 offset:6600
	s_waitcnt vmcnt(5)
	ds_write_b32 v21, v66 offset:6864
	s_waitcnt vmcnt(4)
	ds_write_b32 v21, v67 offset:7128
	s_waitcnt vmcnt(3)
	ds_write_b32 v21, v68 offset:7392
	s_waitcnt vmcnt(2)
	ds_write_b32 v21, v69 offset:7656
	s_waitcnt vmcnt(1)
	ds_write_b32 v21, v70 offset:7920
	s_waitcnt vmcnt(0)
	ds_write_b32 v21, v71 offset:8184
	v_add_u32_e32 v21, 0x2100, v21
	s_waitcnt lgkmcnt(0)
	ds_read2_b32 v[8:9], v13 offset0:33 offset1:41
	ds_read2_b32 v[10:11], v13 offset1:8
	ds_read2_b32 v[22:23], v13 offset0:66 offset1:74
	ds_read2_b32 v[24:25], v13 offset0:99 offset1:107
	ds_read2_b32 v[26:27], v13 offset0:132 offset1:140
	ds_read2_b32 v[28:29], v13 offset0:165 offset1:173
	ds_read2_b32 v[30:31], v13 offset0:198 offset1:206
	ds_read2_b32 v[32:33], v13 offset0:231 offset1:239
	v_add_u32_e32 v36, s28, v17
	v_ashrrev_i32_e32 v37, 31, v36
	v_lshl_add_u64 v[34:35], s[4:5], 1, v[2:3]
	v_lshlrev_b64 v[38:39], 11, v[36:37]
	s_waitcnt lgkmcnt(6)
	v_cvt_pk_bf16_f32 v4, v10, v8
	s_waitcnt lgkmcnt(4)
	v_cvt_pk_bf16_f32 v5, v22, v24
	s_waitcnt lgkmcnt(2)
	v_cvt_pk_bf16_f32 v6, v26, v28
	s_waitcnt lgkmcnt(0)
	v_cvt_pk_bf16_f32 v7, v30, v32
	v_lshl_add_u64 v[38:39], v[34:35], 0, v[38:39]
	v_add_u32_e32 v8, 8, v36
	global_store_dwordx4 v[38:39], v[4:7], off
	s_add_i32 s27, s27, s10
	s_cmpk_gt_i32 s27, 0xaff
	v_cvt_pk_bf16_f32 v4, v11, v9
	v_ashrrev_i32_e32 v9, 31, v8
	v_cvt_pk_bf16_f32 v5, v23, v25
	v_cvt_pk_bf16_f32 v6, v27, v29
	v_cvt_pk_bf16_f32 v7, v31, v33
	v_lshlrev_b64 v[8:9], 11, v[8:9]
	ds_read2_b32 v[10:11], v13 offset0:49 offset1:57
	ds_read2_b32 v[22:23], v13 offset0:16 offset1:24
	ds_read2_b32 v[24:25], v13 offset0:82 offset1:90
	ds_read2_b32 v[26:27], v13 offset0:115 offset1:123
	ds_read2_b32 v[28:29], v13 offset0:148 offset1:156
	ds_read2_b32 v[30:31], v13 offset0:181 offset1:189
	ds_read2_b32 v[32:33], v13 offset0:214 offset1:222
	ds_read2_b32 v[38:39], v13 offset0:247 offset1:255
	v_lshl_add_u64 v[8:9], v[34:35], 0, v[8:9]
	global_store_dwordx4 v[8:9], v[4:7], off
	v_add_u32_e32 v8, 16, v36
	v_ashrrev_i32_e32 v9, 31, v8
	v_lshlrev_b64 v[8:9], 11, v[8:9]
	s_waitcnt lgkmcnt(6)
	v_cvt_pk_bf16_f32 v4, v22, v10
	s_waitcnt lgkmcnt(4)
	v_cvt_pk_bf16_f32 v5, v24, v26
	s_waitcnt lgkmcnt(2)
	v_cvt_pk_bf16_f32 v6, v28, v30
	s_waitcnt lgkmcnt(0)
	v_cvt_pk_bf16_f32 v7, v32, v38
	v_lshl_add_u64 v[8:9], v[34:35], 0, v[8:9]
	global_store_dwordx4 v[8:9], v[4:7], off
	v_add_u32_e32 v8, 24, v36
	v_ashrrev_i32_e32 v9, 31, v8
	v_lshlrev_b64 v[8:9], 11, v[8:9]
	v_cvt_pk_bf16_f32 v4, v23, v11
	v_cvt_pk_bf16_f32 v5, v25, v27
	v_cvt_pk_bf16_f32 v6, v29, v31
	v_cvt_pk_bf16_f32 v7, v33, v39
	v_lshl_add_u64 v[8:9], v[34:35], 0, v[8:9]
	global_store_dwordx4 v[8:9], v[4:7], off
	s_waitcnt lgkmcnt(0)
	s_cbranch_scc0 .LBB0_1457

; #define LAS __attribute__((address_space(3)))
; template <class Fn>
; __device__ __forceinline__ void prep_mat(bf16_t* dst, int NR, int KC, int ldd, const Fn f, int& gw, int NGW, LAS float* scr, int lane) {
;     const int nnb = NR / 32, ntile = nnb * (KC / 64);
;     const int gw0 = gw; gw = (gw0 + NGW - ntile % NGW) % NGW;
;     for (int it = gw0; it < ntile; it += NGW) {
;         const int nb = it % nnb, kb = it / nnb, n0 = 32 * nb, k0 = 64 * kb;
; #pragma unroll 4
;         for (int i = 0; i < 32; ++i) { const int kk = 2 * i + (lane >> 5); scr[kk * 33 + (lane & 31)] = f(n0 + (lane & 31), k0 + kk); }
; __device__ __forceinline__ void prep_ffn(const float* wg, const float* wu, const float* wd, bf16_t* WGU, bf16_t* WD, int gw, int NGW, LAS float* scr, int lane) {
;     ...
;     prep_mat(WD, D, F, F, [=](int n, int k) -> float { return wd[(size_t)k * D + n]; }, gw, NGW, scr, lane);
.LBB0_1465:
	v_lshl_add_u64 v[24:25], v[12:13], 0, s[6:7]
	global_load_dword v72, v[24:25], off
	v_lshl_add_u64 v[24:25], v[10:11], 0, s[6:7]
	global_load_dword v73, v[24:25], off
	v_lshl_add_u64 v[24:25], v[8:9], 0, s[6:7]
	s_add_u32 s6, s6, 0x8000
	s_addc_u32 s7, s7, 0
	s_cmp_eq_u32 s6, 0x40000
	global_load_dword v74, v[24:25], off
	v_ashrrev_i32_e32 v7, 31, v6
	v_lshlrev_b64 v[24:25], 12, v[6:7]
	v_lshl_add_u64 v[24:25], v[4:5], 0, v[24:25]
	v_add_u32_e32 v6, 8, v6
	global_load_dword v75, v[24:25], off
	v_lshl_add_u64 v[24:25], v[12:13], 0, s[6:7]
	global_load_dword v76, v[24:25], off
	v_lshl_add_u64 v[24:25], v[10:11], 0, s[6:7]
	global_load_dword v77, v[24:25], off
	v_lshl_add_u64 v[24:25], v[8:9], 0, s[6:7]
	s_add_u32 s6, s6, 0x8000
	s_addc_u32 s7, s7, 0
	s_cmp_eq_u32 s6, 0x40000
	global_load_dword v78, v[24:25], off
	v_ashrrev_i32_e32 v7, 31, v6
	v_lshlrev_b64 v[24:25], 12, v[6:7]
	v_lshl_add_u64 v[24:25], v[4:5], 0, v[24:25]
	v_add_u32_e32 v6, 8, v6
	global_load_dword v79, v[24:25], off
	v_lshl_add_u64 v[24:25], v[12:13], 0, s[6:7]
	global_load_dword v80, v[24:25], off
	v_lshl_add_u64 v[24:25], v[10:11], 0, s[6:7]
	global_load_dword v81, v[24:25], off
	v_lshl_add_u64 v[24:25], v[8:9], 0, s[6:7]
	s_add_u32 s6, s6, 0x8000
	s_addc_u32 s7, s7, 0
	s_cmp_eq_u32 s6, 0x40000
	global_load_dword v82, v[24:25], off
	v_ashrrev_i32_e32 v7, 31, v6
	v_lshlrev_b64 v[24:25], 12, v[6:7]
	v_lshl_add_u64 v[24:25], v[4:5], 0, v[24:25]
	v_add_u32_e32 v6, 8, v6
	global_load_dword v83, v[24:25], off
	v_lshl_add_u64 v[24:25], v[12:13], 0, s[6:7]
	global_load_dword v84, v[24:25], off
	v_lshl_add_u64 v[24:25], v[10:11], 0, s[6:7]
	global_load_dword v85, v[24:25], off
	v_lshl_add_u64 v[24:25], v[8:9], 0, s[6:7]
	s_add_u32 s6, s6, 0x8000
	s_addc_u32 s7, s7, 0
	s_cmp_eq_u32 s6, 0x40000
	global_load_dword v86, v[24:25], off
	v_ashrrev_i32_e32 v7, 31, v6
	v_lshlrev_b64 v[24:25], 12, v[6:7]
	v_lshl_add_u64 v[24:25], v[4:5], 0, v[24:25]
	v_add_u32_e32 v6, 8, v6
	global_load_dword v87, v[24:25], off
	v_lshl_add_u64 v[24:25], v[12:13], 0, s[6:7]
	global_load_dword v88, v[24:25], off
	v_lshl_add_u64 v[24:25], v[10:11], 0, s[6:7]
	global_load_dword v89, v[24:25], off
	v_lshl_add_u64 v[24:25], v[8:9], 0, s[6:7]
	s_add_u32 s6, s6, 0x8000
	s_addc_u32 s7, s7, 0
	s_cmp_eq_u32 s6, 0x40000
	global_load_dword v90, v[24:25], off
	v_ashrrev_i32_e32 v7, 31, v6
	v_lshlrev_b64 v[24:25], 12, v[6:7]
	v_lshl_add_u64 v[24:25], v[4:5], 0, v[24:25]
	v_add_u32_e32 v6, 8, v6
	global_load_dword v91, v[24:25], off
	v_lshl_add_u64 v[24:25], v[12:13], 0, s[6:7]
	global_load_dword v92, v[24:25], off
	v_lshl_add_u64 v[24:25], v[10:11], 0, s[6:7]
	global_load_dword v93, v[24:25], off
	v_lshl_add_u64 v[24:25], v[8:9], 0, s[6:7]
	s_add_u32 s6, s6, 0x8000
	s_addc_u32 s7, s7, 0
	s_cmp_eq_u32 s6, 0x40000
	global_load_dword v94, v[24:25], off
	v_ashrrev_i32_e32 v7, 31, v6
	v_lshlrev_b64 v[24:25], 12, v[6:7]
	v_lshl_add_u64 v[24:25], v[4:5], 0, v[24:25]
	v_add_u32_e32 v6, 8, v6
	global_load_dword v95, v[24:25], off
	v_lshl_add_u64 v[24:25], v[12:13], 0, s[6:7]
	global_load_dword v96, v[24:25], off
	v_lshl_add_u64 v[24:25], v[10:11], 0, s[6:7]
	global_load_dword v97, v[24:25], off
	v_lshl_add_u64 v[24:25], v[8:9], 0, s[6:7]
	s_add_u32 s6, s6, 0x8000
	s_addc_u32 s7, s7, 0
	s_cmp_eq_u32 s6, 0x40000
	global_load_dword v98, v[24:25], off
	v_ashrrev_i32_e32 v7, 31, v6
	v_lshlrev_b64 v[24:25], 12, v[6:7]
	v_lshl_add_u64 v[24:25], v[4:5], 0, v[24:25]
	v_add_u32_e32 v6, 8, v6
	global_load_dword v99, v[24:25], off
	v_lshl_add_u64 v[24:25], v[12:13], 0, s[6:7]
	global_load_dword v100, v[24:25], off
	v_lshl_add_u64 v[24:25], v[10:11], 0, s[6:7]
	global_load_dword v101, v[24:25], off
	v_lshl_add_u64 v[24:25], v[8:9], 0, s[6:7]
	s_add_u32 s6, s6, 0x8000
	s_addc_u32 s7, s7, 0
	s_cmp_eq_u32 s6, 0x40000
	global_load_dword v102, v[24:25], off
	v_ashrrev_i32_e32 v7, 31, v6
	v_lshlrev_b64 v[24:25], 12, v[6:7]
	v_lshl_add_u64 v[24:25], v[4:5], 0, v[24:25]
	v_add_u32_e32 v6, 8, v6
	global_load_dword v103, v[24:25], off
	s_waitcnt vmcnt(31)
; #define LAS __attribute__((address_space(3)))
; #define GAS __attribute__((address_space(1)))
; __device__ __forceinline__ unsigned cvt_pk_bf16(float lo, float hi) { const f32x2 v = {lo, hi}; return __builtin_bit_cast(unsigned, __builtin_convertvector(v, b16x2_t)); }
; #define LDS_WAIT() asm volatile("s_waitcnt lgkmcnt(0)" ::: "memory")
; template <class Fn>
; __device__ __forceinline__ void prep_mat(bf16_t* dst, int NR, int KC, int ldd, const Fn f, int& gw, int NGW, LAS float* scr, int lane) {
;     ...
;         for (int i = 0; i < 32; ++i) { const int kk = 2 * i + (lane >> 5); scr[kk * 33 + (lane & 31)] = f(n0 + (lane & 31), k0 + kk); }
;         LDS_WAIT(); asm volatile("" ::: "memory");
;         const int c = lane & 7;
; #pragma unroll
;         for (int j = 0; j < 4; ++j) { const int n = (lane >> 3) + 8 * j; const LAS float* s = scr + (8 * c) * 33 + n;
;             u32x4 o; o.x = cvt_pk_bf16(s[0 * 33], s[1 * 33]); o.y = cvt_pk_bf16(s[2 * 33], s[3 * 33]); o.z = cvt_pk_bf16(s[4 * 33], s[5 * 33]); o.w = cvt_pk_bf16(s[6 * 33], s[7 * 33]);
;             *(GAS u32x4*)(dst + (size_t)(n0 + n) * ldd + k0 + 8 * c) = o; }
;         LDS_WAIT(); asm volatile("" ::: "memory");
;     }
	ds_write_b32 v22, v72
	s_waitcnt vmcnt(30)
	ds_write_b32 v22, v73 offset:264
	s_waitcnt vmcnt(29)
	ds_write_b32 v22, v74 offset:528
	s_waitcnt vmcnt(28)
	ds_write_b32 v22, v75 offset:792
	s_waitcnt vmcnt(27)
	ds_write_b32 v22, v76 offset:1056
	s_waitcnt vmcnt(26)
	ds_write_b32 v22, v77 offset:1320
	s_waitcnt vmcnt(25)
	ds_write_b32 v22, v78 offset:1584
	s_waitcnt vmcnt(24)
	ds_write_b32 v22, v79 offset:1848
	s_waitcnt vmcnt(23)
	ds_write_b32 v22, v80 offset:2112
	s_waitcnt vmcnt(22)
	ds_write_b32 v22, v81 offset:2376
	s_waitcnt vmcnt(21)
	ds_write_b32 v22, v82 offset:2640
	s_waitcnt vmcnt(20)
	ds_write_b32 v22, v83 offset:2904
	s_waitcnt vmcnt(19)
	ds_write_b32 v22, v84 offset:3168
	s_waitcnt vmcnt(18)
	ds_write_b32 v22, v85 offset:3432
	s_waitcnt vmcnt(17)
	ds_write_b32 v22, v86 offset:3696
	s_waitcnt vmcnt(16)
	ds_write_b32 v22, v87 offset:3960
	s_waitcnt vmcnt(15)
	ds_write_b32 v22, v88 offset:4224
	s_waitcnt vmcnt(14)
	ds_write_b32 v22, v89 offset:4488
	s_waitcnt vmcnt(13)
	ds_write_b32 v22, v90 offset:4752
	s_waitcnt vmcnt(12)
	ds_write_b32 v22, v91 offset:5016
	s_waitcnt vmcnt(11)
	ds_write_b32 v22, v92 offset:5280
	s_waitcnt vmcnt(10)
	ds_write_b32 v22, v93 offset:5544
	s_waitcnt vmcnt(9)
	ds_write_b32 v22, v94 offset:5808
	s_waitcnt vmcnt(8)
	ds_write_b32 v22, v95 offset:6072
	s_waitcnt vmcnt(7)
	ds_write_b32 v22, v96 offset:6336
	s_waitcnt vmcnt(6)
	ds_write_b32 v22, v97 offset:6600
	s_waitcnt vmcnt(5)
	ds_write_b32 v22, v98 offset:6864
	s_waitcnt vmcnt(4)
	ds_write_b32 v22, v99 offset:7128
	s_waitcnt vmcnt(3)
	ds_write_b32 v22, v100 offset:7392
	s_waitcnt vmcnt(2)
	ds_write_b32 v22, v101 offset:7656
	s_waitcnt vmcnt(1)
	ds_write_b32 v22, v102 offset:7920
	s_waitcnt vmcnt(0)
	ds_write_b32 v22, v103 offset:8184
	v_add_u32_e32 v22, 0x2100, v22
	s_waitcnt lgkmcnt(0)
	ds_read2_b32 v[8:9], v16 offset0:33 offset1:41
	ds_read2_b32 v[10:11], v16 offset1:8
	ds_read2_b32 v[12:13], v16 offset0:66 offset1:74
	ds_read2_b32 v[22:23], v16 offset0:99 offset1:107
	ds_read2_b32 v[24:25], v16 offset0:132 offset1:140
	ds_read2_b32 v[26:27], v16 offset0:165 offset1:173
	ds_read2_b32 v[28:29], v16 offset0:198 offset1:206
	ds_read2_b32 v[30:31], v16 offset0:231 offset1:239
	v_lshl_add_u64 v[32:33], s[2:3], 1, v[2:3]
	v_add_u32_e32 v36, s12, v17
	s_waitcnt lgkmcnt(6)
	v_cvt_pk_bf16_f32 v4, v10, v8
	s_waitcnt lgkmcnt(4)
	v_cvt_pk_bf16_f32 v5, v12, v22
	s_waitcnt lgkmcnt(2)
	v_cvt_pk_bf16_f32 v6, v24, v26
	s_waitcnt lgkmcnt(0)
	v_cvt_pk_bf16_f32 v7, v28, v30
	v_mad_i64_i32 v[34:35], s[2:3], v36, s11, v[32:33]
	global_store_dwordx4 v[34:35], v[4:7], off
	v_add_u32_e32 v8, 8, v36
	s_add_i32 s13, s13, s10
	v_cvt_pk_bf16_f32 v4, v11, v9
	v_cvt_pk_bf16_f32 v5, v13, v23
	v_cvt_pk_bf16_f32 v6, v25, v27
	v_cvt_pk_bf16_f32 v7, v29, v31
	ds_read2_b32 v[10:11], v16 offset0:49 offset1:57
	ds_read2_b32 v[12:13], v16 offset0:16 offset1:24
	ds_read2_b32 v[22:23], v16 offset0:82 offset1:90
	ds_read2_b32 v[24:25], v16 offset0:115 offset1:123
	ds_read2_b32 v[26:27], v16 offset0:148 offset1:156
	ds_read2_b32 v[28:29], v16 offset0:181 offset1:189
	ds_read2_b32 v[30:31], v16 offset0:214 offset1:222
	ds_read2_b32 v[34:35], v16 offset0:247 offset1:255
	v_mad_i64_i32 v[8:9], s[2:3], v8, s11, v[32:33]
	global_store_dwordx4 v[8:9], v[4:7], off
	v_add_u32_e32 v8, 16, v36
	v_mad_i64_i32 v[8:9], s[2:3], v8, s11, v[32:33]
	s_waitcnt lgkmcnt(6)
	v_cvt_pk_bf16_f32 v4, v12, v10
	s_waitcnt lgkmcnt(4)
	v_cvt_pk_bf16_f32 v5, v22, v24
	s_waitcnt lgkmcnt(2)
	v_cvt_pk_bf16_f32 v6, v26, v28
	s_waitcnt lgkmcnt(0)
	v_cvt_pk_bf16_f32 v7, v30, v34
	global_store_dwordx4 v[8:9], v[4:7], off
	v_add_u32_e32 v8, 24, v36
	v_mad_i64_i32 v[8:9], s[2:3], v8, s11, v[32:33]
	v_cvt_pk_bf16_f32 v4, v13, v11
	v_cvt_pk_bf16_f32 v5, v23, v25
	v_cvt_pk_bf16_f32 v6, v27, v29
	v_cvt_pk_bf16_f32 v7, v31, v35
	global_store_dwordx4 v[8:9], v[4:7], off
	s_waitcnt lgkmcnt(0)
	s_cmpk_gt_i32 s13, 0x57f
	s_cbranch_scc0 .LBB0_1464
	v_mov_b32_e32 v16, v15

; #define LAS __attribute__((address_space(3)))
; template <class Fn>
; __device__ __forceinline__ void prep_mat(bf16_t* dst, int NR, int KC, int ldd, const Fn f, int& gw, int NGW, LAS float* scr, int lane) {
;     const int nnb = NR / 32, ntile = nnb * (KC / 64);
;     const int gw0 = gw; gw = (gw0 + NGW - ntile % NGW) % NGW;
;     for (int it = gw0; it < ntile; it += NGW) {
;         const int nb = it % nnb, kb = it / nnb, n0 = 32 * nb, k0 = 64 * kb;
; #pragma unroll 4
;         for (int i = 0; i < 32; ++i) { const int kk = 2 * i + (lane >> 5); scr[kk * 33 + (lane & 31)] = f(n0 + (lane & 31), k0 + kk); }
; __device__ __forceinline__ void prep_hybrid(const float* w_in, const float* w_out, const float* pool_w, const float* pool_scale, bf16_t* WIN, bf16_t* WOUT, int gw, int NGW, LAS float* scr, int lane) {
;     prep_mat(WIN, NPROJ, D, D, [=](int n, int k) -> float {
;         const int src = n < 1024 ? headperm(n) : (n < 2048 ? n : n + 8);
;         return w_in[(size_t)k * INC + src]; }, gw, NGW, scr, lane);
.LBB0_1667:
	v_lshl_add_u64 v[24:25], v[10:11], 0, s[8:9]
	global_load_dword v40, v[24:25], off
	v_lshl_add_u64 v[24:25], v[8:9], 0, s[8:9]
	global_load_dword v41, v[24:25], off
	v_lshl_add_u64 v[24:25], v[6:7], 0, s[8:9]
	s_add_u32 s8, s8, 0x14100
	s_addc_u32 s9, s9, 0
	s_cmp_eq_u32 s8, 0xa0800
	global_load_dword v42, v[24:25], off
	v_mad_i64_i32 v[24:25], s[38:39], v22, s30, v[4:5]
	v_add_u32_e32 v22, 8, v22
	global_load_dword v43, v[24:25], off
	v_lshl_add_u64 v[24:25], v[10:11], 0, s[8:9]
	global_load_dword v44, v[24:25], off
	v_lshl_add_u64 v[24:25], v[8:9], 0, s[8:9]
	global_load_dword v45, v[24:25], off
	v_lshl_add_u64 v[24:25], v[6:7], 0, s[8:9]
	s_add_u32 s8, s8, 0x14100
	s_addc_u32 s9, s9, 0
	s_cmp_eq_u32 s8, 0xa0800
	global_load_dword v46, v[24:25], off
	v_mad_i64_i32 v[24:25], s[38:39], v22, s30, v[4:5]
	v_add_u32_e32 v22, 8, v22
	global_load_dword v47, v[24:25], off
	v_lshl_add_u64 v[24:25], v[10:11], 0, s[8:9]
	global_load_dword v48, v[24:25], off
	v_lshl_add_u64 v[24:25], v[8:9], 0, s[8:9]
	global_load_dword v49, v[24:25], off
	v_lshl_add_u64 v[24:25], v[6:7], 0, s[8:9]
	s_add_u32 s8, s8, 0x14100
	s_addc_u32 s9, s9, 0
	s_cmp_eq_u32 s8, 0xa0800
	global_load_dword v50, v[24:25], off
	v_mad_i64_i32 v[24:25], s[38:39], v22, s30, v[4:5]
	v_add_u32_e32 v22, 8, v22
	global_load_dword v51, v[24:25], off
	v_lshl_add_u64 v[24:25], v[10:11], 0, s[8:9]
	global_load_dword v52, v[24:25], off
	v_lshl_add_u64 v[24:25], v[8:9], 0, s[8:9]
	global_load_dword v53, v[24:25], off
	v_lshl_add_u64 v[24:25], v[6:7], 0, s[8:9]
	s_add_u32 s8, s8, 0x14100
	s_addc_u32 s9, s9, 0
	s_cmp_eq_u32 s8, 0xa0800
	global_load_dword v54, v[24:25], off
	v_mad_i64_i32 v[24:25], s[38:39], v22, s30, v[4:5]
	v_add_u32_e32 v22, 8, v22
	global_load_dword v55, v[24:25], off
	v_lshl_add_u64 v[24:25], v[10:11], 0, s[8:9]
	global_load_dword v56, v[24:25], off
	v_lshl_add_u64 v[24:25], v[8:9], 0, s[8:9]
	global_load_dword v57, v[24:25], off
	v_lshl_add_u64 v[24:25], v[6:7], 0, s[8:9]
	s_add_u32 s8, s8, 0x14100
	s_addc_u32 s9, s9, 0
	s_cmp_eq_u32 s8, 0xa0800
	global_load_dword v58, v[24:25], off
	v_mad_i64_i32 v[24:25], s[38:39], v22, s30, v[4:5]
	v_add_u32_e32 v22, 8, v22
	global_load_dword v59, v[24:25], off
	v_lshl_add_u64 v[24:25], v[10:11], 0, s[8:9]
	global_load_dword v60, v[24:25], off
	v_lshl_add_u64 v[24:25], v[8:9], 0, s[8:9]
	global_load_dword v61, v[24:25], off
	v_lshl_add_u64 v[24:25], v[6:7], 0, s[8:9]
	s_add_u32 s8, s8, 0x14100
	s_addc_u32 s9, s9, 0
	s_cmp_eq_u32 s8, 0xa0800
	global_load_dword v62, v[24:25], off
	v_mad_i64_i32 v[24:25], s[38:39], v22, s30, v[4:5]
	v_add_u32_e32 v22, 8, v22
	global_load_dword v63, v[24:25], off
	v_lshl_add_u64 v[24:25], v[10:11], 0, s[8:9]
	global_load_dword v64, v[24:25], off
	v_lshl_add_u64 v[24:25], v[8:9], 0, s[8:9]
	global_load_dword v65, v[24:25], off
	v_lshl_add_u64 v[24:25], v[6:7], 0, s[8:9]
	s_add_u32 s8, s8, 0x14100
	s_addc_u32 s9, s9, 0
	s_cmp_eq_u32 s8, 0xa0800
	global_load_dword v66, v[24:25], off
	v_mad_i64_i32 v[24:25], s[38:39], v22, s30, v[4:5]
	v_add_u32_e32 v22, 8, v22
	global_load_dword v67, v[24:25], off
	v_lshl_add_u64 v[24:25], v[10:11], 0, s[8:9]
	global_load_dword v68, v[24:25], off
	v_lshl_add_u64 v[24:25], v[8:9], 0, s[8:9]
	global_load_dword v69, v[24:25], off
	v_lshl_add_u64 v[24:25], v[6:7], 0, s[8:9]
	s_add_u32 s8, s8, 0x14100
	s_addc_u32 s9, s9, 0
	s_cmp_eq_u32 s8, 0xa0800
	global_load_dword v70, v[24:25], off
	v_mad_i64_i32 v[24:25], s[38:39], v22, s30, v[4:5]
	v_add_u32_e32 v22, 8, v22
	global_load_dword v71, v[24:25], off
	s_waitcnt vmcnt(31)
	ds_write_b32 v23, v40
	s_waitcnt vmcnt(30)
	ds_write_b32 v23, v41 offset:264
	s_waitcnt vmcnt(29)
	ds_write_b32 v23, v42 offset:528
	s_waitcnt vmcnt(28)
	ds_write_b32 v23, v43 offset:792
	s_waitcnt vmcnt(27)
	ds_write_b32 v23, v44 offset:1056
	s_waitcnt vmcnt(26)
	ds_write_b32 v23, v45 offset:1320
	s_waitcnt vmcnt(25)
; #define LAS __attribute__((address_space(3)))
; #define GAS __attribute__((address_space(1)))
; __device__ __forceinline__ unsigned cvt_pk_bf16(float lo, float hi) { const f32x2 v = {lo, hi}; return __builtin_bit_cast(unsigned, __builtin_convertvector(v, b16x2_t)); }
; #define LDS_WAIT() asm volatile("s_waitcnt lgkmcnt(0)" ::: "memory")
; template <class Fn>
; __device__ __forceinline__ void prep_mat(bf16_t* dst, int NR, int KC, int ldd, const Fn f, int& gw, int NGW, LAS float* scr, int lane) {
;     ...
;         for (int i = 0; i < 32; ++i) { const int kk = 2 * i + (lane >> 5); scr[kk * 33 + (lane & 31)] = f(n0 + (lane & 31), k0 + kk); }
;         LDS_WAIT(); asm volatile("" ::: "memory");
;         const int c = lane & 7;
; #pragma unroll
;         for (int j = 0; j < 4; ++j) { const int n = (lane >> 3) + 8 * j; const LAS float* s = scr + (8 * c) * 33 + n;
;             u32x4 o; o.x = cvt_pk_bf16(s[0 * 33], s[1 * 33]); o.y = cvt_pk_bf16(s[2 * 33], s[3 * 33]); o.z = cvt_pk_bf16(s[4 * 33], s[5 * 33]); o.w = cvt_pk_bf16(s[6 * 33], s[7 * 33]);
;             *(GAS u32x4*)(dst + (size_t)(n0 + n) * ldd + k0 + 8 * c) = o; }
;         LDS_WAIT(); asm volatile("" ::: "memory");
;     }
	ds_write_b32 v23, v46 offset:1584
	s_waitcnt vmcnt(24)
	ds_write_b32 v23, v47 offset:1848
	s_waitcnt vmcnt(23)
	ds_write_b32 v23, v48 offset:2112
	s_waitcnt vmcnt(22)
	ds_write_b32 v23, v49 offset:2376
	s_waitcnt vmcnt(21)
	ds_write_b32 v23, v50 offset:2640
	s_waitcnt vmcnt(20)
	ds_write_b32 v23, v51 offset:2904
	s_waitcnt vmcnt(19)
	ds_write_b32 v23, v52 offset:3168
	s_waitcnt vmcnt(18)
	ds_write_b32 v23, v53 offset:3432
	s_waitcnt vmcnt(17)
	ds_write_b32 v23, v54 offset:3696
	s_waitcnt vmcnt(16)
	ds_write_b32 v23, v55 offset:3960
	s_waitcnt vmcnt(15)
	ds_write_b32 v23, v56 offset:4224
	s_waitcnt vmcnt(14)
	ds_write_b32 v23, v57 offset:4488
	s_waitcnt vmcnt(13)
	ds_write_b32 v23, v58 offset:4752
	s_waitcnt vmcnt(12)
	ds_write_b32 v23, v59 offset:5016
	s_waitcnt vmcnt(11)
	ds_write_b32 v23, v60 offset:5280
	s_waitcnt vmcnt(10)
	ds_write_b32 v23, v61 offset:5544
	s_waitcnt vmcnt(9)
	ds_write_b32 v23, v62 offset:5808
	s_waitcnt vmcnt(8)
	ds_write_b32 v23, v63 offset:6072
	s_waitcnt vmcnt(7)
	ds_write_b32 v23, v64 offset:6336
	s_waitcnt vmcnt(6)
	ds_write_b32 v23, v65 offset:6600
	s_waitcnt vmcnt(5)
	ds_write_b32 v23, v66 offset:6864
	s_waitcnt vmcnt(4)
	ds_write_b32 v23, v67 offset:7128
	s_waitcnt vmcnt(3)
	ds_write_b32 v23, v68 offset:7392
	s_waitcnt vmcnt(2)
	ds_write_b32 v23, v69 offset:7656
	s_waitcnt vmcnt(1)
	ds_write_b32 v23, v70 offset:7920
	s_waitcnt vmcnt(0)
	ds_write_b32 v23, v71 offset:8184
	v_add_u32_e32 v23, 0x2100, v23
	s_waitcnt lgkmcnt(0)
	ds_read2_b32 v[8:9], v12 offset0:33 offset1:41
	ds_read2_b32 v[10:11], v12 offset1:8
	ds_read2_b32 v[22:23], v12 offset0:66 offset1:74
	ds_read2_b32 v[24:25], v12 offset0:99 offset1:107
	ds_read2_b32 v[26:27], v12 offset0:132 offset1:140
	ds_read2_b32 v[28:29], v12 offset0:165 offset1:173
	ds_read2_b32 v[30:31], v12 offset0:198 offset1:206
	ds_read2_b32 v[32:33], v12 offset0:231 offset1:239
	v_add_u32_e32 v36, s34, v15
	v_ashrrev_i32_e32 v37, 31, v36
	v_lshl_add_u64 v[34:35], s[6:7], 1, v[2:3]
	v_lshlrev_b64 v[38:39], 11, v[36:37]
	s_waitcnt lgkmcnt(6)
	v_cvt_pk_bf16_f32 v4, v10, v8
	s_waitcnt lgkmcnt(4)
	v_cvt_pk_bf16_f32 v5, v22, v24
	s_waitcnt lgkmcnt(2)
	v_cvt_pk_bf16_f32 v6, v26, v28
	s_waitcnt lgkmcnt(0)
	v_cvt_pk_bf16_f32 v7, v30, v32
	v_lshl_add_u64 v[38:39], v[34:35], 0, v[38:39]
	v_add_u32_e32 v8, 8, v36
	global_store_dwordx4 v[38:39], v[4:7], off
	s_add_i32 s31, s31, s16
	s_cmpk_gt_i32 s31, 0x4ff
	v_cvt_pk_bf16_f32 v4, v11, v9
	v_ashrrev_i32_e32 v9, 31, v8
	v_cvt_pk_bf16_f32 v5, v23, v25
	v_cvt_pk_bf16_f32 v6, v27, v29
	v_cvt_pk_bf16_f32 v7, v31, v33
	v_lshlrev_b64 v[8:9], 11, v[8:9]
	ds_read2_b32 v[10:11], v12 offset0:49 offset1:57
	ds_read2_b32 v[22:23], v12 offset0:16 offset1:24
	ds_read2_b32 v[24:25], v12 offset0:82 offset1:90
	ds_read2_b32 v[26:27], v12 offset0:115 offset1:123
	ds_read2_b32 v[28:29], v12 offset0:148 offset1:156
	ds_read2_b32 v[30:31], v12 offset0:181 offset1:189
	ds_read2_b32 v[32:33], v12 offset0:214 offset1:222
	ds_read2_b32 v[38:39], v12 offset0:247 offset1:255
	v_lshl_add_u64 v[8:9], v[34:35], 0, v[8:9]
	global_store_dwordx4 v[8:9], v[4:7], off
	v_add_u32_e32 v8, 16, v36
	v_ashrrev_i32_e32 v9, 31, v8
	v_lshlrev_b64 v[8:9], 11, v[8:9]
	s_waitcnt lgkmcnt(6)
	v_cvt_pk_bf16_f32 v4, v22, v10
	s_waitcnt lgkmcnt(4)
	v_cvt_pk_bf16_f32 v5, v24, v26
	s_waitcnt lgkmcnt(2)
	v_cvt_pk_bf16_f32 v6, v28, v30
	s_waitcnt lgkmcnt(0)
	v_cvt_pk_bf16_f32 v7, v32, v38
	v_lshl_add_u64 v[8:9], v[34:35], 0, v[8:9]
	global_store_dwordx4 v[8:9], v[4:7], off
	v_add_u32_e32 v8, 24, v36
	v_ashrrev_i32_e32 v9, 31, v8
	v_lshlrev_b64 v[8:9], 11, v[8:9]
	v_cvt_pk_bf16_f32 v4, v23, v11
	v_cvt_pk_bf16_f32 v5, v25, v27
	v_cvt_pk_bf16_f32 v6, v29, v31
	v_cvt_pk_bf16_f32 v7, v33, v39
	v_lshl_add_u64 v[8:9], v[34:35], 0, v[8:9]
	global_store_dwordx4 v[8:9], v[4:7], off
	s_waitcnt lgkmcnt(0)
	s_cbranch_scc0 .LBB0_1666

; #define LAS __attribute__((address_space(3)))
; template <class Fn>
; __device__ __forceinline__ void prep_mat(bf16_t* dst, int NR, int KC, int ldd, const Fn f, int& gw, int NGW, LAS float* scr, int lane) {
;     const int nnb = NR / 32, ntile = nnb * (KC / 64);
;     const int gw0 = gw; gw = (gw0 + NGW - ntile % NGW) % NGW;
;     for (int it = gw0; it < ntile; it += NGW) {
;         const int nb = it % nnb, kb = it / nnb, n0 = 32 * nb, k0 = 64 * kb;
; #pragma unroll 4
;         for (int i = 0; i < 32; ++i) { const int kk = 2 * i + (lane >> 5); scr[kk * 33 + (lane & 31)] = f(n0 + (lane & 31), k0 + kk); }
; __device__ __forceinline__ void prep_hybrid(const float* w_in, const float* w_out, const float* pool_w, const float* pool_scale, bf16_t* WIN, bf16_t* WOUT, int gw, int NGW, LAS float* scr, int lane) {
;     ...
;     prep_mat(WOUT, D, 512, D, [=](int n, int k) -> float { return w_out[(size_t)k * D + n]; }, gw, NGW, scr, lane);
.LBB0_1672:
	v_lshl_add_u64 v[24:25], v[12:13], 0, s[12:13]
	global_load_dword v72, v[24:25], off
	v_lshl_add_u64 v[24:25], v[10:11], 0, s[12:13]
	global_load_dword v73, v[24:25], off
	v_lshl_add_u64 v[24:25], v[8:9], 0, s[12:13]
	s_add_u32 s12, s12, 0x8000
	s_addc_u32 s13, s13, 0
	s_cmp_eq_u32 s12, 0x40000
	global_load_dword v74, v[24:25], off
	v_ashrrev_i32_e32 v7, 31, v6
	v_lshlrev_b64 v[24:25], 12, v[6:7]
	v_lshl_add_u64 v[24:25], v[4:5], 0, v[24:25]
	v_add_u32_e32 v6, 8, v6
	global_load_dword v75, v[24:25], off
	v_lshl_add_u64 v[24:25], v[12:13], 0, s[12:13]
	global_load_dword v76, v[24:25], off
	v_lshl_add_u64 v[24:25], v[10:11], 0, s[12:13]
	global_load_dword v77, v[24:25], off
	v_lshl_add_u64 v[24:25], v[8:9], 0, s[12:13]
	s_add_u32 s12, s12, 0x8000
	s_addc_u32 s13, s13, 0
	s_cmp_eq_u32 s12, 0x40000
	global_load_dword v78, v[24:25], off
	v_ashrrev_i32_e32 v7, 31, v6
	v_lshlrev_b64 v[24:25], 12, v[6:7]
	v_lshl_add_u64 v[24:25], v[4:5], 0, v[24:25]
	v_add_u32_e32 v6, 8, v6
	global_load_dword v79, v[24:25], off
	v_lshl_add_u64 v[24:25], v[12:13], 0, s[12:13]
	global_load_dword v80, v[24:25], off
	v_lshl_add_u64 v[24:25], v[10:11], 0, s[12:13]
	global_load_dword v81, v[24:25], off
	v_lshl_add_u64 v[24:25], v[8:9], 0, s[12:13]
	s_add_u32 s12, s12, 0x8000
	s_addc_u32 s13, s13, 0
	s_cmp_eq_u32 s12, 0x40000
	global_load_dword v82, v[24:25], off
	v_ashrrev_i32_e32 v7, 31, v6
	v_lshlrev_b64 v[24:25], 12, v[6:7]
	v_lshl_add_u64 v[24:25], v[4:5], 0, v[24:25]
	v_add_u32_e32 v6, 8, v6
	global_load_dword v83, v[24:25], off
	v_lshl_add_u64 v[24:25], v[12:13], 0, s[12:13]
	global_load_dword v84, v[24:25], off
	v_lshl_add_u64 v[24:25], v[10:11], 0, s[12:13]
	global_load_dword v85, v[24:25], off
	v_lshl_add_u64 v[24:25], v[8:9], 0, s[12:13]
	s_add_u32 s12, s12, 0x8000
	s_addc_u32 s13, s13, 0
	s_cmp_eq_u32 s12, 0x40000
	global_load_dword v86, v[24:25], off
	v_ashrrev_i32_e32 v7, 31, v6
	v_lshlrev_b64 v[24:25], 12, v[6:7]
	v_lshl_add_u64 v[24:25], v[4:5], 0, v[24:25]
	v_add_u32_e32 v6, 8, v6
	global_load_dword v87, v[24:25], off
	v_lshl_add_u64 v[24:25], v[12:13], 0, s[12:13]
	global_load_dword v88, v[24:25], off
	v_lshl_add_u64 v[24:25], v[10:11], 0, s[12:13]
	global_load_dword v89, v[24:25], off
	v_lshl_add_u64 v[24:25], v[8:9], 0, s[12:13]
	s_add_u32 s12, s12, 0x8000
	s_addc_u32 s13, s13, 0
	s_cmp_eq_u32 s12, 0x40000
	global_load_dword v90, v[24:25], off
	v_ashrrev_i32_e32 v7, 31, v6
	v_lshlrev_b64 v[24:25], 12, v[6:7]
	v_lshl_add_u64 v[24:25], v[4:5], 0, v[24:25]
	v_add_u32_e32 v6, 8, v6
	global_load_dword v91, v[24:25], off
	v_lshl_add_u64 v[24:25], v[12:13], 0, s[12:13]
	global_load_dword v92, v[24:25], off
	v_lshl_add_u64 v[24:25], v[10:11], 0, s[12:13]
	global_load_dword v93, v[24:25], off
	v_lshl_add_u64 v[24:25], v[8:9], 0, s[12:13]
	s_add_u32 s12, s12, 0x8000
	s_addc_u32 s13, s13, 0
	s_cmp_eq_u32 s12, 0x40000
	global_load_dword v96, v[24:25], off
	v_ashrrev_i32_e32 v7, 31, v6
	v_lshlrev_b64 v[24:25], 12, v[6:7]
	v_lshl_add_u64 v[24:25], v[4:5], 0, v[24:25]
	v_add_u32_e32 v6, 8, v6
	global_load_dword v97, v[24:25], off
	v_lshl_add_u64 v[24:25], v[12:13], 0, s[12:13]
	global_load_dword v98, v[24:25], off
	v_lshl_add_u64 v[24:25], v[10:11], 0, s[12:13]
	global_load_dword v100, v[24:25], off
	v_lshl_add_u64 v[24:25], v[8:9], 0, s[12:13]
	s_add_u32 s12, s12, 0x8000
	s_addc_u32 s13, s13, 0
	s_cmp_eq_u32 s12, 0x40000
	global_load_dword v101, v[24:25], off
	v_ashrrev_i32_e32 v7, 31, v6
	v_lshlrev_b64 v[24:25], 12, v[6:7]
	v_lshl_add_u64 v[24:25], v[4:5], 0, v[24:25]
	v_add_u32_e32 v6, 8, v6
	global_load_dword v102, v[24:25], off
	v_lshl_add_u64 v[24:25], v[12:13], 0, s[12:13]
	global_load_dword v103, v[24:25], off
	v_lshl_add_u64 v[24:25], v[10:11], 0, s[12:13]
	global_load_dword v104, v[24:25], off
	v_lshl_add_u64 v[24:25], v[8:9], 0, s[12:13]
	s_add_u32 s12, s12, 0x8000
	s_addc_u32 s13, s13, 0
	s_cmp_eq_u32 s12, 0x40000
	global_load_dword v105, v[24:25], off
	v_ashrrev_i32_e32 v7, 31, v6
	v_lshlrev_b64 v[24:25], 12, v[6:7]
	v_lshl_add_u64 v[24:25], v[4:5], 0, v[24:25]
	v_add_u32_e32 v6, 8, v6
	global_load_dword v106, v[24:25], off
	s_waitcnt vmcnt(31)
; #define LAS __attribute__((address_space(3)))
; #define GAS __attribute__((address_space(1)))
; __device__ __forceinline__ unsigned cvt_pk_bf16(float lo, float hi) { const f32x2 v = {lo, hi}; return __builtin_bit_cast(unsigned, __builtin_convertvector(v, b16x2_t)); }
; #define LDS_WAIT() asm volatile("s_waitcnt lgkmcnt(0)" ::: "memory")
; template <class Fn>
; __device__ __forceinline__ void prep_mat(bf16_t* dst, int NR, int KC, int ldd, const Fn f, int& gw, int NGW, LAS float* scr, int lane) {
;     ...
;         for (int i = 0; i < 32; ++i) { const int kk = 2 * i + (lane >> 5); scr[kk * 33 + (lane & 31)] = f(n0 + (lane & 31), k0 + kk); }
;         LDS_WAIT(); asm volatile("" ::: "memory");
;         const int c = lane & 7;
; #pragma unroll
;         for (int j = 0; j < 4; ++j) { const int n = (lane >> 3) + 8 * j; const LAS float* s = scr + (8 * c) * 33 + n;
;             u32x4 o; o.x = cvt_pk_bf16(s[0 * 33], s[1 * 33]); o.y = cvt_pk_bf16(s[2 * 33], s[3 * 33]); o.z = cvt_pk_bf16(s[4 * 33], s[5 * 33]); o.w = cvt_pk_bf16(s[6 * 33], s[7 * 33]);
;             *(GAS u32x4*)(dst + (size_t)(n0 + n) * ldd + k0 + 8 * c) = o; }
;         LDS_WAIT(); asm volatile("" ::: "memory");
;     }
	ds_write_b32 v23, v72
	s_waitcnt vmcnt(30)
	ds_write_b32 v23, v73 offset:264
	s_waitcnt vmcnt(29)
	ds_write_b32 v23, v74 offset:528
	s_waitcnt vmcnt(28)
	ds_write_b32 v23, v75 offset:792
	s_waitcnt vmcnt(27)
	ds_write_b32 v23, v76 offset:1056
	s_waitcnt vmcnt(26)
	ds_write_b32 v23, v77 offset:1320
	s_waitcnt vmcnt(25)
	ds_write_b32 v23, v78 offset:1584
	s_waitcnt vmcnt(24)
	ds_write_b32 v23, v79 offset:1848
	s_waitcnt vmcnt(23)
	ds_write_b32 v23, v80 offset:2112
	s_waitcnt vmcnt(22)
	ds_write_b32 v23, v81 offset:2376
	s_waitcnt vmcnt(21)
	ds_write_b32 v23, v82 offset:2640
	s_waitcnt vmcnt(20)
	ds_write_b32 v23, v83 offset:2904
	s_waitcnt vmcnt(19)
	ds_write_b32 v23, v84 offset:3168
	s_waitcnt vmcnt(18)
	ds_write_b32 v23, v85 offset:3432
	s_waitcnt vmcnt(17)
	ds_write_b32 v23, v86 offset:3696
	s_waitcnt vmcnt(16)
	ds_write_b32 v23, v87 offset:3960
	s_waitcnt vmcnt(15)
	ds_write_b32 v23, v88 offset:4224
	s_waitcnt vmcnt(14)
	ds_write_b32 v23, v89 offset:4488
	s_waitcnt vmcnt(13)
	ds_write_b32 v23, v90 offset:4752
	s_waitcnt vmcnt(12)
	ds_write_b32 v23, v91 offset:5016
	s_waitcnt vmcnt(11)
	ds_write_b32 v23, v92 offset:5280
	s_waitcnt vmcnt(10)
	ds_write_b32 v23, v93 offset:5544
	s_waitcnt vmcnt(9)
	ds_write_b32 v23, v96 offset:5808
	s_waitcnt vmcnt(8)
	ds_write_b32 v23, v97 offset:6072
	s_waitcnt vmcnt(7)
	ds_write_b32 v23, v98 offset:6336
	s_waitcnt vmcnt(6)
	ds_write_b32 v23, v100 offset:6600
	s_waitcnt vmcnt(5)
	ds_write_b32 v23, v101 offset:6864
	s_waitcnt vmcnt(4)
	ds_write_b32 v23, v102 offset:7128
	s_waitcnt vmcnt(3)
	ds_write_b32 v23, v103 offset:7392
	s_waitcnt vmcnt(2)
	ds_write_b32 v23, v104 offset:7656
	s_waitcnt vmcnt(1)
	ds_write_b32 v23, v105 offset:7920
	s_waitcnt vmcnt(0)
	ds_write_b32 v23, v106 offset:8184
	v_add_u32_e32 v23, 0x2100, v23
	s_waitcnt lgkmcnt(0)
	ds_read2_b32 v[8:9], v17 offset0:33 offset1:41
	ds_read2_b32 v[10:11], v17 offset1:8
	ds_read2_b32 v[12:13], v17 offset0:66 offset1:74
	ds_read2_b32 v[24:25], v17 offset0:99 offset1:107
	ds_read2_b32 v[26:27], v17 offset0:132 offset1:140
	ds_read2_b32 v[28:29], v17 offset0:165 offset1:173
	ds_read2_b32 v[30:31], v17 offset0:198 offset1:206
	ds_read2_b32 v[32:33], v17 offset0:231 offset1:239
	v_add_u32_e32 v36, s27, v15
	v_ashrrev_i32_e32 v37, 31, v36
	v_lshl_add_u64 v[34:35], s[8:9], 1, v[2:3]
	v_lshlrev_b64 v[38:39], 11, v[36:37]
	s_waitcnt lgkmcnt(6)
	v_cvt_pk_bf16_f32 v4, v10, v8
	s_waitcnt lgkmcnt(4)
	v_cvt_pk_bf16_f32 v5, v12, v24
	s_waitcnt lgkmcnt(2)
	v_cvt_pk_bf16_f32 v6, v26, v28
	s_waitcnt lgkmcnt(0)
	v_cvt_pk_bf16_f32 v7, v30, v32
	v_lshl_add_u64 v[38:39], v[34:35], 0, v[38:39]
	v_add_u32_e32 v8, 8, v36
	global_store_dwordx4 v[38:39], v[4:7], off
	s_add_i32 s24, s24, s16
	s_cmpk_gt_i32 s24, 0xff
	v_cvt_pk_bf16_f32 v4, v11, v9
	v_ashrrev_i32_e32 v9, 31, v8
	v_cvt_pk_bf16_f32 v5, v13, v25
	v_cvt_pk_bf16_f32 v6, v27, v29
	v_cvt_pk_bf16_f32 v7, v31, v33
	v_lshlrev_b64 v[8:9], 11, v[8:9]
	ds_read2_b32 v[10:11], v17 offset0:49 offset1:57
	ds_read2_b32 v[12:13], v17 offset0:16 offset1:24
	ds_read2_b32 v[24:25], v17 offset0:82 offset1:90
	ds_read2_b32 v[26:27], v17 offset0:115 offset1:123
	ds_read2_b32 v[28:29], v17 offset0:148 offset1:156
	ds_read2_b32 v[30:31], v17 offset0:181 offset1:189
	ds_read2_b32 v[32:33], v17 offset0:214 offset1:222
	ds_read2_b32 v[38:39], v17 offset0:247 offset1:255
	v_lshl_add_u64 v[8:9], v[34:35], 0, v[8:9]
	global_store_dwordx4 v[8:9], v[4:7], off
	v_add_u32_e32 v8, 16, v36
	v_ashrrev_i32_e32 v9, 31, v8
	v_lshlrev_b64 v[8:9], 11, v[8:9]
	s_waitcnt lgkmcnt(6)
	v_cvt_pk_bf16_f32 v4, v12, v10
	s_waitcnt lgkmcnt(4)
	v_cvt_pk_bf16_f32 v5, v24, v26
	s_waitcnt lgkmcnt(2)
	v_cvt_pk_bf16_f32 v6, v28, v30
	s_waitcnt lgkmcnt(0)
	v_cvt_pk_bf16_f32 v7, v32, v38
	v_lshl_add_u64 v[8:9], v[34:35], 0, v[8:9]
	global_store_dwordx4 v[8:9], v[4:7], off
	v_add_u32_e32 v8, 24, v36
	v_ashrrev_i32_e32 v9, 31, v8
	v_lshlrev_b64 v[8:9], 11, v[8:9]
	v_cvt_pk_bf16_f32 v4, v13, v11
	v_cvt_pk_bf16_f32 v5, v25, v27
	v_cvt_pk_bf16_f32 v6, v29, v31
	v_cvt_pk_bf16_f32 v7, v33, v39
	v_lshl_add_u64 v[8:9], v[34:35], 0, v[8:9]
	global_store_dwordx4 v[8:9], v[4:7], off
	s_waitcnt lgkmcnt(0)
	s_cbranch_scc0 .LBB0_1671

; #define LAS __attribute__((address_space(3)))
; template <class Fn>
; __device__ __forceinline__ void prep_mat(bf16_t* dst, int NR, int KC, int ldd, const Fn f, int& gw, int NGW, LAS float* scr, int lane) {
;     const int nnb = NR / 32, ntile = nnb * (KC / 64);
;     const int gw0 = gw; gw = (gw0 + NGW - ntile % NGW) % NGW;
;     for (int it = gw0; it < ntile; it += NGW) {
;         const int nb = it % nnb, kb = it / nnb, n0 = 32 * nb, k0 = 64 * kb;
; #pragma unroll 4
;         for (int i = 0; i < 32; ++i) { const int kk = 2 * i + (lane >> 5); scr[kk * 33 + (lane & 31)] = f(n0 + (lane & 31), k0 + kk); }
; __device__ __forceinline__ void prep_rwkv(const LAS unsigned* PL, int idx, bf16_t* WR2, bf16_t* WR3, bf16_t* WG, bf16_t* WO, int gw, int NGW, LAS float* scr, int lane) {
;     ...
;             prep_mat(WR2, 2048, 1024, 1024, [=](int n, int k) -> float { const float* W = (n >> 10) ? w_k : w_r; return W[(size_t)k * D + (n & 1023)]; }, gw, NGW, scr, lane);
.LBB0_2247:
	v_lshl_add_u64 v[26:27], v[14:15], 0, s[14:15]
	global_load_dword v40, v[26:27], off
	v_lshl_add_u64 v[26:27], v[12:13], 0, s[14:15]
	global_load_dword v41, v[26:27], off
	v_lshl_add_u64 v[26:27], v[10:11], 0, s[14:15]
	s_add_u32 s14, s14, 0x8000
	s_addc_u32 s15, s15, 0
	s_cmp_eq_u32 s14, 0x40000
	global_load_dword v42, v[26:27], off
	v_ashrrev_i32_e32 v9, 31, v8
	v_lshlrev_b64 v[26:27], 12, v[8:9]
	v_lshl_add_u64 v[26:27], v[6:7], 0, v[26:27]
	v_add_u32_e32 v8, 8, v8
	global_load_dword v43, v[26:27], off
	v_lshl_add_u64 v[26:27], v[14:15], 0, s[14:15]
	global_load_dword v44, v[26:27], off
	v_lshl_add_u64 v[26:27], v[12:13], 0, s[14:15]
	global_load_dword v45, v[26:27], off
	v_lshl_add_u64 v[26:27], v[10:11], 0, s[14:15]
	s_add_u32 s14, s14, 0x8000
	s_addc_u32 s15, s15, 0
	s_cmp_eq_u32 s14, 0x40000
	global_load_dword v46, v[26:27], off
	v_ashrrev_i32_e32 v9, 31, v8
	v_lshlrev_b64 v[26:27], 12, v[8:9]
	v_lshl_add_u64 v[26:27], v[6:7], 0, v[26:27]
	v_add_u32_e32 v8, 8, v8
	global_load_dword v47, v[26:27], off
	v_lshl_add_u64 v[26:27], v[14:15], 0, s[14:15]
	global_load_dword v48, v[26:27], off
	v_lshl_add_u64 v[26:27], v[12:13], 0, s[14:15]
	global_load_dword v49, v[26:27], off
	v_lshl_add_u64 v[26:27], v[10:11], 0, s[14:15]
	s_add_u32 s14, s14, 0x8000
	s_addc_u32 s15, s15, 0
	s_cmp_eq_u32 s14, 0x40000
	global_load_dword v50, v[26:27], off
	v_ashrrev_i32_e32 v9, 31, v8
	v_lshlrev_b64 v[26:27], 12, v[8:9]
	v_lshl_add_u64 v[26:27], v[6:7], 0, v[26:27]
	v_add_u32_e32 v8, 8, v8
	global_load_dword v51, v[26:27], off
	v_lshl_add_u64 v[26:27], v[14:15], 0, s[14:15]
	global_load_dword v52, v[26:27], off
	v_lshl_add_u64 v[26:27], v[12:13], 0, s[14:15]
	global_load_dword v53, v[26:27], off
	v_lshl_add_u64 v[26:27], v[10:11], 0, s[14:15]
	s_add_u32 s14, s14, 0x8000
	s_addc_u32 s15, s15, 0
	s_cmp_eq_u32 s14, 0x40000
	global_load_dword v54, v[26:27], off
	v_ashrrev_i32_e32 v9, 31, v8
	v_lshlrev_b64 v[26:27], 12, v[8:9]
	v_lshl_add_u64 v[26:27], v[6:7], 0, v[26:27]
	v_add_u32_e32 v8, 8, v8
	global_load_dword v55, v[26:27], off
	v_lshl_add_u64 v[26:27], v[14:15], 0, s[14:15]
	global_load_dword v56, v[26:27], off
	v_lshl_add_u64 v[26:27], v[12:13], 0, s[14:15]
	global_load_dword v57, v[26:27], off
	v_lshl_add_u64 v[26:27], v[10:11], 0, s[14:15]
	s_add_u32 s14, s14, 0x8000
	s_addc_u32 s15, s15, 0
	s_cmp_eq_u32 s14, 0x40000
	global_load_dword v58, v[26:27], off
	v_ashrrev_i32_e32 v9, 31, v8
	v_lshlrev_b64 v[26:27], 12, v[8:9]
	v_lshl_add_u64 v[26:27], v[6:7], 0, v[26:27]
	v_add_u32_e32 v8, 8, v8
	global_load_dword v59, v[26:27], off
	v_lshl_add_u64 v[26:27], v[14:15], 0, s[14:15]
	global_load_dword v60, v[26:27], off
	v_lshl_add_u64 v[26:27], v[12:13], 0, s[14:15]
	global_load_dword v61, v[26:27], off
	v_lshl_add_u64 v[26:27], v[10:11], 0, s[14:15]
	s_add_u32 s14, s14, 0x8000
	s_addc_u32 s15, s15, 0
	s_cmp_eq_u32 s14, 0x40000
	global_load_dword v62, v[26:27], off
	v_ashrrev_i32_e32 v9, 31, v8
	v_lshlrev_b64 v[26:27], 12, v[8:9]
	v_lshl_add_u64 v[26:27], v[6:7], 0, v[26:27]
	v_add_u32_e32 v8, 8, v8
	global_load_dword v113, v[26:27], off
	v_lshl_add_u64 v[26:27], v[14:15], 0, s[14:15]
	global_load_dword v130, v[26:27], off
	v_lshl_add_u64 v[26:27], v[12:13], 0, s[14:15]
	global_load_dword v132, v[26:27], off
	v_lshl_add_u64 v[26:27], v[10:11], 0, s[14:15]
	s_add_u32 s14, s14, 0x8000
	s_addc_u32 s15, s15, 0
	s_cmp_eq_u32 s14, 0x40000
	global_load_dword v134, v[26:27], off
	v_ashrrev_i32_e32 v9, 31, v8
	v_lshlrev_b64 v[26:27], 12, v[8:9]
	v_lshl_add_u64 v[26:27], v[6:7], 0, v[26:27]
	v_add_u32_e32 v8, 8, v8
	global_load_dword v136, v[26:27], off
	v_lshl_add_u64 v[26:27], v[14:15], 0, s[14:15]
	global_load_dword v138, v[26:27], off
	v_lshl_add_u64 v[26:27], v[12:13], 0, s[14:15]
	global_load_dword v140, v[26:27], off
	v_lshl_add_u64 v[26:27], v[10:11], 0, s[14:15]
	s_add_u32 s14, s14, 0x8000
	s_addc_u32 s15, s15, 0
	s_cmp_eq_u32 s14, 0x40000
	global_load_dword v142, v[26:27], off
	v_ashrrev_i32_e32 v9, 31, v8
	v_lshlrev_b64 v[26:27], 12, v[8:9]
	v_lshl_add_u64 v[26:27], v[6:7], 0, v[26:27]
	v_add_u32_e32 v8, 8, v8
	global_load_dword v144, v[26:27], off
	s_waitcnt vmcnt(31)
; #define LAS __attribute__((address_space(3)))
; #define GAS __attribute__((address_space(1)))
; __device__ __forceinline__ unsigned cvt_pk_bf16(float lo, float hi) { const f32x2 v = {lo, hi}; return __builtin_bit_cast(unsigned, __builtin_convertvector(v, b16x2_t)); }
; #define LDS_WAIT() asm volatile("s_waitcnt lgkmcnt(0)" ::: "memory")
; template <class Fn>
; __device__ __forceinline__ void prep_mat(bf16_t* dst, int NR, int KC, int ldd, const Fn f, int& gw, int NGW, LAS float* scr, int lane) {
;     ...
;         for (int i = 0; i < 32; ++i) { const int kk = 2 * i + (lane >> 5); scr[kk * 33 + (lane & 31)] = f(n0 + (lane & 31), k0 + kk); }
;         LDS_WAIT(); asm volatile("" ::: "memory");
;         const int c = lane & 7;
; #pragma unroll
;         for (int j = 0; j < 4; ++j) { const int n = (lane >> 3) + 8 * j; const LAS float* s = scr + (8 * c) * 33 + n;
;             u32x4 o; o.x = cvt_pk_bf16(s[0 * 33], s[1 * 33]); o.y = cvt_pk_bf16(s[2 * 33], s[3 * 33]); o.z = cvt_pk_bf16(s[4 * 33], s[5 * 33]); o.w = cvt_pk_bf16(s[6 * 33], s[7 * 33]);
;             *(GAS u32x4*)(dst + (size_t)(n0 + n) * ldd + k0 + 8 * c) = o; }
;         LDS_WAIT(); asm volatile("" ::: "memory");
;     }
	ds_write_b32 v2, v40
	s_waitcnt vmcnt(30)
	ds_write_b32 v2, v41 offset:264
	s_waitcnt vmcnt(29)
	ds_write_b32 v2, v42 offset:528
	s_waitcnt vmcnt(28)
	ds_write_b32 v2, v43 offset:792
	s_waitcnt vmcnt(27)
	ds_write_b32 v2, v44 offset:1056
	s_waitcnt vmcnt(26)
	ds_write_b32 v2, v45 offset:1320
	s_waitcnt vmcnt(25)
	ds_write_b32 v2, v46 offset:1584
	s_waitcnt vmcnt(24)
	ds_write_b32 v2, v47 offset:1848
	s_waitcnt vmcnt(23)
	ds_write_b32 v2, v48 offset:2112
	s_waitcnt vmcnt(22)
	ds_write_b32 v2, v49 offset:2376
	s_waitcnt vmcnt(21)
	ds_write_b32 v2, v50 offset:2640
	s_waitcnt vmcnt(20)
	ds_write_b32 v2, v51 offset:2904
	s_waitcnt vmcnt(19)
	ds_write_b32 v2, v52 offset:3168
	s_waitcnt vmcnt(18)
	ds_write_b32 v2, v53 offset:3432
	s_waitcnt vmcnt(17)
	ds_write_b32 v2, v54 offset:3696
	s_waitcnt vmcnt(16)
	ds_write_b32 v2, v55 offset:3960
	s_waitcnt vmcnt(15)
	ds_write_b32 v2, v56 offset:4224
	s_waitcnt vmcnt(14)
	ds_write_b32 v2, v57 offset:4488
	s_waitcnt vmcnt(13)
	ds_write_b32 v2, v58 offset:4752
	s_waitcnt vmcnt(12)
	ds_write_b32 v2, v59 offset:5016
	s_waitcnt vmcnt(11)
	ds_write_b32 v2, v60 offset:5280
	s_waitcnt vmcnt(10)
	ds_write_b32 v2, v61 offset:5544
	s_waitcnt vmcnt(9)
	ds_write_b32 v2, v62 offset:5808
	s_waitcnt vmcnt(8)
	ds_write_b32 v2, v113 offset:6072
	s_waitcnt vmcnt(7)
	ds_write_b32 v2, v130 offset:6336
	s_waitcnt vmcnt(6)
	ds_write_b32 v2, v132 offset:6600
	s_waitcnt vmcnt(5)
	ds_write_b32 v2, v134 offset:6864
	s_waitcnt vmcnt(4)
	ds_write_b32 v2, v136 offset:7128
	s_waitcnt vmcnt(3)
	ds_write_b32 v2, v138 offset:7392
	s_waitcnt vmcnt(2)
	ds_write_b32 v2, v140 offset:7656
	s_waitcnt vmcnt(1)
	ds_write_b32 v2, v142 offset:7920
	s_waitcnt vmcnt(0)
	ds_write_b32 v2, v144 offset:8184
	v_add_u32_e32 v2, 0x2100, v2
	s_waitcnt lgkmcnt(0)
	ds_read2_b32 v[10:11], v20 offset0:33 offset1:41
	ds_read2_b32 v[12:13], v20 offset1:8
	ds_read2_b32 v[14:15], v20 offset0:66 offset1:74
	ds_read2_b32 v[26:27], v20 offset0:99 offset1:107
	ds_read2_b32 v[28:29], v20 offset0:132 offset1:140
	ds_read2_b32 v[30:31], v20 offset0:165 offset1:173
	ds_read2_b32 v[32:33], v20 offset0:198 offset1:206
	ds_read2_b32 v[34:35], v20 offset0:231 offset1:239
	v_add_u32_e32 v38, s29, v18
	v_ashrrev_i32_e32 v39, 31, v38
	v_lshl_add_u64 v[36:37], s[12:13], 1, v[4:5]
	v_lshlrev_b64 v[40:41], 11, v[38:39]
	s_waitcnt lgkmcnt(6)
	v_cvt_pk_bf16_f32 v6, v12, v10
	s_waitcnt lgkmcnt(4)
	v_cvt_pk_bf16_f32 v7, v14, v26
	s_waitcnt lgkmcnt(2)
	v_cvt_pk_bf16_f32 v8, v28, v30
	s_waitcnt lgkmcnt(0)
	v_cvt_pk_bf16_f32 v9, v32, v34
	v_lshl_add_u64 v[40:41], v[36:37], 0, v[40:41]
	v_add_u32_e32 v10, 8, v38
	global_store_dwordx4 v[40:41], v[6:9], off
	s_add_i32 s28, s28, s49
	s_cmpk_gt_i32 s28, 0x3ff
	v_cvt_pk_bf16_f32 v6, v13, v11
	v_ashrrev_i32_e32 v11, 31, v10
	v_cvt_pk_bf16_f32 v7, v15, v27
	v_cvt_pk_bf16_f32 v8, v29, v31
	v_cvt_pk_bf16_f32 v9, v33, v35
	v_lshlrev_b64 v[10:11], 11, v[10:11]
	ds_read2_b32 v[12:13], v20 offset0:49 offset1:57
	ds_read2_b32 v[14:15], v20 offset0:16 offset1:24
	ds_read2_b32 v[26:27], v20 offset0:82 offset1:90
	ds_read2_b32 v[28:29], v20 offset0:115 offset1:123
	ds_read2_b32 v[30:31], v20 offset0:148 offset1:156
	ds_read2_b32 v[32:33], v20 offset0:181 offset1:189
	ds_read2_b32 v[34:35], v20 offset0:214 offset1:222
	ds_read2_b32 v[40:41], v20 offset0:247 offset1:255
	v_lshl_add_u64 v[10:11], v[36:37], 0, v[10:11]
	global_store_dwordx4 v[10:11], v[6:9], off
	v_add_u32_e32 v10, 16, v38
	v_ashrrev_i32_e32 v11, 31, v10
	v_lshlrev_b64 v[10:11], 11, v[10:11]
	s_waitcnt lgkmcnt(6)
	v_cvt_pk_bf16_f32 v6, v14, v12
	s_waitcnt lgkmcnt(4)
	v_cvt_pk_bf16_f32 v7, v26, v28
	s_waitcnt lgkmcnt(2)
	v_cvt_pk_bf16_f32 v8, v30, v32
	s_waitcnt lgkmcnt(0)
	v_cvt_pk_bf16_f32 v9, v34, v40
	v_lshl_add_u64 v[10:11], v[36:37], 0, v[10:11]
	global_store_dwordx4 v[10:11], v[6:9], off
	v_add_u32_e32 v10, 24, v38
	v_ashrrev_i32_e32 v11, 31, v10
	v_lshlrev_b64 v[10:11], 11, v[10:11]
	v_cvt_pk_bf16_f32 v6, v15, v13
	v_cvt_pk_bf16_f32 v7, v27, v29
	v_cvt_pk_bf16_f32 v8, v31, v33
	v_cvt_pk_bf16_f32 v9, v35, v41
	v_lshl_add_u64 v[10:11], v[36:37], 0, v[10:11]
	global_store_dwordx4 v[10:11], v[6:9], off
	s_waitcnt lgkmcnt(0)
	s_cbranch_scc0 .LBB0_2246

; #define LAS __attribute__((address_space(3)))
; template <class Fn>
; __device__ __forceinline__ void prep_mat(bf16_t* dst, int NR, int KC, int ldd, const Fn f, int& gw, int NGW, LAS float* scr, int lane) {
;     const int nnb = NR / 32, ntile = nnb * (KC / 64);
;     const int gw0 = gw; gw = (gw0 + NGW - ntile % NGW) % NGW;
;     for (int it = gw0; it < ntile; it += NGW) {
;         const int nb = it % nnb, kb = it / nnb, n0 = 32 * nb, k0 = 64 * kb;
; #pragma unroll 4
;         for (int i = 0; i < 32; ++i) { const int kk = 2 * i + (lane >> 5); scr[kk * 33 + (lane & 31)] = f(n0 + (lane & 31), k0 + kk); }
; __device__ __forceinline__ void prep_rwkv(const LAS unsigned* PL, int idx, bf16_t* WR2, bf16_t* WR3, bf16_t* WG, bf16_t* WO, int gw, int NGW, LAS float* scr, int lane) {
;     ...
;         prep_mat(WO, D, D, D, [=](int n, int k) -> float { return w_o[(size_t)k * D + n]; }, gw, NGW, scr, lane);
.LBB0_2402:
	v_lshl_add_u64 v[24:25], v[12:13], 0, s[6:7]
	global_load_dword v156, v[24:25], off
	v_lshl_add_u64 v[24:25], v[10:11], 0, s[6:7]
	global_load_dword v157, v[24:25], off
	v_lshl_add_u64 v[24:25], v[8:9], 0, s[6:7]
	s_add_u32 s6, s6, 0x8000
	s_addc_u32 s7, s7, 0
	s_cmp_eq_u32 s6, 0x40000
	global_load_dword v158, v[24:25], off
	v_ashrrev_i32_e32 v7, 31, v6
	v_lshlrev_b64 v[24:25], 12, v[6:7]
	v_lshl_add_u64 v[24:25], v[4:5], 0, v[24:25]
	v_add_u32_e32 v6, 8, v6
	global_load_dword v159, v[24:25], off
	v_lshl_add_u64 v[24:25], v[12:13], 0, s[6:7]
	global_load_dword v160, v[24:25], off
	v_lshl_add_u64 v[24:25], v[10:11], 0, s[6:7]
	global_load_dword v161, v[24:25], off
	v_lshl_add_u64 v[24:25], v[8:9], 0, s[6:7]
	s_add_u32 s6, s6, 0x8000
	s_addc_u32 s7, s7, 0
	s_cmp_eq_u32 s6, 0x40000
	global_load_dword v162, v[24:25], off
	v_ashrrev_i32_e32 v7, 31, v6
	v_lshlrev_b64 v[24:25], 12, v[6:7]
	v_lshl_add_u64 v[24:25], v[4:5], 0, v[24:25]
	v_add_u32_e32 v6, 8, v6
	global_load_dword v163, v[24:25], off
	v_lshl_add_u64 v[24:25], v[12:13], 0, s[6:7]
	global_load_dword v164, v[24:25], off
	v_lshl_add_u64 v[24:25], v[10:11], 0, s[6:7]
	global_load_dword v165, v[24:25], off
	v_lshl_add_u64 v[24:25], v[8:9], 0, s[6:7]
	s_add_u32 s6, s6, 0x8000
	s_addc_u32 s7, s7, 0
	s_cmp_eq_u32 s6, 0x40000
	global_load_dword v166, v[24:25], off
	v_ashrrev_i32_e32 v7, 31, v6
	v_lshlrev_b64 v[24:25], 12, v[6:7]
	v_lshl_add_u64 v[24:25], v[4:5], 0, v[24:25]
	v_add_u32_e32 v6, 8, v6
	global_load_dword v167, v[24:25], off
	v_lshl_add_u64 v[24:25], v[12:13], 0, s[6:7]
	global_load_dword v168, v[24:25], off
	v_lshl_add_u64 v[24:25], v[10:11], 0, s[6:7]
	global_load_dword v169, v[24:25], off
	v_lshl_add_u64 v[24:25], v[8:9], 0, s[6:7]
	s_add_u32 s6, s6, 0x8000
	s_addc_u32 s7, s7, 0
	s_cmp_eq_u32 s6, 0x40000
	global_load_dword v170, v[24:25], off
	v_ashrrev_i32_e32 v7, 31, v6
	v_lshlrev_b64 v[24:25], 12, v[6:7]
	v_lshl_add_u64 v[24:25], v[4:5], 0, v[24:25]
	v_add_u32_e32 v6, 8, v6
	global_load_dword v171, v[24:25], off
	v_lshl_add_u64 v[24:25], v[12:13], 0, s[6:7]
	global_load_dword v172, v[24:25], off
	v_lshl_add_u64 v[24:25], v[10:11], 0, s[6:7]
	global_load_dword v173, v[24:25], off
	v_lshl_add_u64 v[24:25], v[8:9], 0, s[6:7]
	s_add_u32 s6, s6, 0x8000
	s_addc_u32 s7, s7, 0
	s_cmp_eq_u32 s6, 0x40000
	global_load_dword v174, v[24:25], off
	v_ashrrev_i32_e32 v7, 31, v6
	v_lshlrev_b64 v[24:25], 12, v[6:7]
	v_lshl_add_u64 v[24:25], v[4:5], 0, v[24:25]
	v_add_u32_e32 v6, 8, v6
	global_load_dword v175, v[24:25], off
	v_lshl_add_u64 v[24:25], v[12:13], 0, s[6:7]
	global_load_dword v182, v[24:25], off
	v_lshl_add_u64 v[24:25], v[10:11], 0, s[6:7]
	global_load_dword v183, v[24:25], off
	v_lshl_add_u64 v[24:25], v[8:9], 0, s[6:7]
	s_add_u32 s6, s6, 0x8000
	s_addc_u32 s7, s7, 0
	s_cmp_eq_u32 s6, 0x40000
	global_load_dword v184, v[24:25], off
	v_ashrrev_i32_e32 v7, 31, v6
	v_lshlrev_b64 v[24:25], 12, v[6:7]
	v_lshl_add_u64 v[24:25], v[4:5], 0, v[24:25]
	v_add_u32_e32 v6, 8, v6
	global_load_dword v185, v[24:25], off
	v_lshl_add_u64 v[24:25], v[12:13], 0, s[6:7]
	global_load_dword v186, v[24:25], off
	v_lshl_add_u64 v[24:25], v[10:11], 0, s[6:7]
	global_load_dword v187, v[24:25], off
	v_lshl_add_u64 v[24:25], v[8:9], 0, s[6:7]
	s_add_u32 s6, s6, 0x8000
	s_addc_u32 s7, s7, 0
	s_cmp_eq_u32 s6, 0x40000
	global_load_dword v188, v[24:25], off
	v_ashrrev_i32_e32 v7, 31, v6
	v_lshlrev_b64 v[24:25], 12, v[6:7]
	v_lshl_add_u64 v[24:25], v[4:5], 0, v[24:25]
	v_add_u32_e32 v6, 8, v6
	global_load_dword v189, v[24:25], off
	v_lshl_add_u64 v[24:25], v[12:13], 0, s[6:7]
	global_load_dword v190, v[24:25], off
	v_lshl_add_u64 v[24:25], v[10:11], 0, s[6:7]
	global_load_dword v191, v[24:25], off
	v_lshl_add_u64 v[24:25], v[8:9], 0, s[6:7]
	s_add_u32 s6, s6, 0x8000
	s_addc_u32 s7, s7, 0
	s_cmp_eq_u32 s6, 0x40000
	global_load_dword v192, v[24:25], off
	v_ashrrev_i32_e32 v7, 31, v6
	v_lshlrev_b64 v[24:25], 12, v[6:7]
	v_lshl_add_u64 v[24:25], v[4:5], 0, v[24:25]
	v_add_u32_e32 v6, 8, v6
	global_load_dword v193, v[24:25], off
	s_waitcnt vmcnt(31)
	ds_write_b32 v22, v156
	s_waitcnt vmcnt(30)
	ds_write_b32 v22, v157 offset:264
	s_waitcnt vmcnt(29)
; #define LAS __attribute__((address_space(3)))
; #define GAS __attribute__((address_space(1)))
; __device__ __forceinline__ unsigned cvt_pk_bf16(float lo, float hi) { const f32x2 v = {lo, hi}; return __builtin_bit_cast(unsigned, __builtin_convertvector(v, b16x2_t)); }
; #define LDS_WAIT() asm volatile("s_waitcnt lgkmcnt(0)" ::: "memory")
; template <class Fn>
; __device__ __forceinline__ void prep_mat(bf16_t* dst, int NR, int KC, int ldd, const Fn f, int& gw, int NGW, LAS float* scr, int lane) {
;     ...
;         for (int i = 0; i < 32; ++i) { const int kk = 2 * i + (lane >> 5); scr[kk * 33 + (lane & 31)] = f(n0 + (lane & 31), k0 + kk); }
;         LDS_WAIT(); asm volatile("" ::: "memory");
;         const int c = lane & 7;
; #pragma unroll
;         for (int j = 0; j < 4; ++j) { const int n = (lane >> 3) + 8 * j; const LAS float* s = scr + (8 * c) * 33 + n;
;             u32x4 o; o.x = cvt_pk_bf16(s[0 * 33], s[1 * 33]); o.y = cvt_pk_bf16(s[2 * 33], s[3 * 33]); o.z = cvt_pk_bf16(s[4 * 33], s[5 * 33]); o.w = cvt_pk_bf16(s[6 * 33], s[7 * 33]);
;             *(GAS u32x4*)(dst + (size_t)(n0 + n) * ldd + k0 + 8 * c) = o; }
;         LDS_WAIT(); asm volatile("" ::: "memory");
;     }
	ds_write_b32 v22, v158 offset:528
	s_waitcnt vmcnt(28)
	ds_write_b32 v22, v159 offset:792
	s_waitcnt vmcnt(27)
	ds_write_b32 v22, v160 offset:1056
	s_waitcnt vmcnt(26)
	ds_write_b32 v22, v161 offset:1320
	s_waitcnt vmcnt(25)
	ds_write_b32 v22, v162 offset:1584
	s_waitcnt vmcnt(24)
	ds_write_b32 v22, v163 offset:1848
	s_waitcnt vmcnt(23)
	ds_write_b32 v22, v164 offset:2112
	s_waitcnt vmcnt(22)
	ds_write_b32 v22, v165 offset:2376
	s_waitcnt vmcnt(21)
	ds_write_b32 v22, v166 offset:2640
	s_waitcnt vmcnt(20)
	ds_write_b32 v22, v167 offset:2904
	s_waitcnt vmcnt(19)
	ds_write_b32 v22, v168 offset:3168
	s_waitcnt vmcnt(18)
	ds_write_b32 v22, v169 offset:3432
	s_waitcnt vmcnt(17)
	ds_write_b32 v22, v170 offset:3696
	s_waitcnt vmcnt(16)
	ds_write_b32 v22, v171 offset:3960
	s_waitcnt vmcnt(15)
	ds_write_b32 v22, v172 offset:4224
	s_waitcnt vmcnt(14)
	ds_write_b32 v22, v173 offset:4488
	s_waitcnt vmcnt(13)
	ds_write_b32 v22, v174 offset:4752
	s_waitcnt vmcnt(12)
	ds_write_b32 v22, v175 offset:5016
	s_waitcnt vmcnt(11)
	ds_write_b32 v22, v182 offset:5280
	s_waitcnt vmcnt(10)
	ds_write_b32 v22, v183 offset:5544
	s_waitcnt vmcnt(9)
	ds_write_b32 v22, v184 offset:5808
	s_waitcnt vmcnt(8)
	ds_write_b32 v22, v185 offset:6072
	s_waitcnt vmcnt(7)
	ds_write_b32 v22, v186 offset:6336
	s_waitcnt vmcnt(6)
	ds_write_b32 v22, v187 offset:6600
	s_waitcnt vmcnt(5)
	ds_write_b32 v22, v188 offset:6864
	s_waitcnt vmcnt(4)
	ds_write_b32 v22, v189 offset:7128
	s_waitcnt vmcnt(3)
	ds_write_b32 v22, v190 offset:7392
	s_waitcnt vmcnt(2)
	ds_write_b32 v22, v191 offset:7656
	s_waitcnt vmcnt(1)
	ds_write_b32 v22, v192 offset:7920
	s_waitcnt vmcnt(0)
	ds_write_b32 v22, v193 offset:8184
	v_add_u32_e32 v22, 0x2100, v22
	s_waitcnt lgkmcnt(0)
	ds_read2_b32 v[8:9], v14 offset0:33 offset1:41
	ds_read2_b32 v[10:11], v14 offset1:8
	ds_read2_b32 v[12:13], v14 offset0:66 offset1:74
	ds_read2_b32 v[22:23], v14 offset0:99 offset1:107
	ds_read2_b32 v[24:25], v14 offset0:132 offset1:140
	ds_read2_b32 v[26:27], v14 offset0:165 offset1:173
	ds_read2_b32 v[28:29], v14 offset0:198 offset1:206
	ds_read2_b32 v[30:31], v14 offset0:231 offset1:239
	v_add_u32_e32 v34, s11, v18
	v_ashrrev_i32_e32 v35, 31, v34
	v_lshl_add_u64 v[32:33], s[4:5], 1, v[2:3]
	v_lshlrev_b64 v[36:37], 11, v[34:35]
	s_waitcnt lgkmcnt(6)
	v_cvt_pk_bf16_f32 v4, v10, v8
	s_waitcnt lgkmcnt(4)
	v_cvt_pk_bf16_f32 v5, v12, v22
	s_waitcnt lgkmcnt(2)
	v_cvt_pk_bf16_f32 v6, v24, v26
	s_waitcnt lgkmcnt(0)
	v_cvt_pk_bf16_f32 v7, v28, v30
	v_lshl_add_u64 v[36:37], v[32:33], 0, v[36:37]
	v_add_u32_e32 v8, 8, v34
	global_store_dwordx4 v[36:37], v[4:7], off
	s_add_i32 s10, s10, s49
	s_cmpk_gt_i32 s10, 0x1ff
	v_cvt_pk_bf16_f32 v4, v11, v9
	v_ashrrev_i32_e32 v9, 31, v8
	v_cvt_pk_bf16_f32 v5, v13, v23
	v_cvt_pk_bf16_f32 v6, v25, v27
	v_cvt_pk_bf16_f32 v7, v29, v31
	v_lshlrev_b64 v[8:9], 11, v[8:9]
	ds_read2_b32 v[10:11], v14 offset0:49 offset1:57
	ds_read2_b32 v[12:13], v14 offset0:16 offset1:24
	ds_read2_b32 v[22:23], v14 offset0:82 offset1:90
	ds_read2_b32 v[24:25], v14 offset0:115 offset1:123
	ds_read2_b32 v[26:27], v14 offset0:148 offset1:156
	ds_read2_b32 v[28:29], v14 offset0:181 offset1:189
	ds_read2_b32 v[30:31], v14 offset0:214 offset1:222
	ds_read2_b32 v[36:37], v14 offset0:247 offset1:255
	v_lshl_add_u64 v[8:9], v[32:33], 0, v[8:9]
	global_store_dwordx4 v[8:9], v[4:7], off
	v_add_u32_e32 v8, 16, v34
	v_ashrrev_i32_e32 v9, 31, v8
	v_lshlrev_b64 v[8:9], 11, v[8:9]
	s_waitcnt lgkmcnt(6)
	v_cvt_pk_bf16_f32 v4, v12, v10
	s_waitcnt lgkmcnt(4)
	v_cvt_pk_bf16_f32 v5, v22, v24
	s_waitcnt lgkmcnt(2)
	v_cvt_pk_bf16_f32 v6, v26, v28
	s_waitcnt lgkmcnt(0)
	v_cvt_pk_bf16_f32 v7, v30, v36
	v_lshl_add_u64 v[8:9], v[32:33], 0, v[8:9]
	global_store_dwordx4 v[8:9], v[4:7], off
	v_add_u32_e32 v8, 24, v34
	v_ashrrev_i32_e32 v9, 31, v8
	v_lshlrev_b64 v[8:9], 11, v[8:9]
	v_cvt_pk_bf16_f32 v4, v13, v11
	v_cvt_pk_bf16_f32 v5, v23, v25
	v_cvt_pk_bf16_f32 v6, v27, v29
	v_cvt_pk_bf16_f32 v7, v31, v37
	v_lshl_add_u64 v[8:9], v[32:33], 0, v[8:9]
	global_store_dwordx4 v[8:9], v[4:7], off
	s_waitcnt lgkmcnt(0)
	s_cbranch_scc0 .LBB0_2401
	v_mov_b32_e32 v48, v17

; #define GAS __attribute__((address_space(1)))
; __device__ __forceinline__ void scan_phase2(LAS unsigned char* lds, const int wid, const bf16_t* R, const bf16_t* K, const bf16_t* V, const bf16_t* W, const bf16_t* A,
;                                             const float* k_k, const float* k_a, const float* r_k, bf16_t* Y, float* BON) {
;     ...
;             const int j = lane >> 2, v8 = (lane & 3) * 8;
;             const size_t gv = (tokb + j) * D + h * 64 + half * 32 + v8;
;             u32x4 vr = *(const GAS u32x4*)(V + gv);
;             const bf16_t* Wl = W + tokb * D + h * 64 + lane;
;             bf16_t ewl[16];
; #pragma unroll
;             for (int i = 0; i < 16; ++i) ewl[i] = Wl[(size_t)(CL + i) * D];
.LBB0_2888:
	s_andn2_b64 vcc, exec, s[54:55]
	s_cbranch_vccnz .LBB0_2897
	s_waitcnt vmcnt(0)
	v_lshl_add_u64 v[0:1], s[20:21], 0, v[36:37]
	v_lshlrev_b64 v[0:1], 11, v[0:1]
	v_lshl_add_u64 v[0:1], s[40:41], 0, v[0:1]
	s_lshl_b32 s28, s86, 6
	v_lshl_add_u64 v[0:1], v[0:1], 0, s[28:29]
	s_lshl_b32 s28, s85, 7
	s_lshl_b64 s[20:21], s[24:25], 23
	s_add_u32 s0, s42, s20
	s_addc_u32 s1, s43, s21
	s_add_u32 s54, s0, s28
	s_addc_u32 s55, s1, 0
	v_lshl_add_u64 v[4:5], v[16:17], 1, s[54:55]
	v_add_co_u32_e32 v6, vcc, s76, v4
	v_mov_b32_e32 v45, v25
	s_nop 0
	v_addc_co_u32_e32 v7, vcc, 0, v5, vcc
	v_add_co_u32_e32 v12, vcc, s77, v4
	v_lshl_add_u64 v[0:1], v[0:1], 0, v[44:45]
	s_nop 0
	v_addc_co_u32_e32 v13, vcc, 0, v5, vcc
	v_add_co_u32_e32 v14, vcc, s78, v4
	v_lshl_add_u64 v[0:1], v[0:1], 0, s[28:29]
	s_nop 0
	v_addc_co_u32_e32 v15, vcc, 0, v5, vcc
	v_add_co_u32_e32 v46, vcc, s79, v4
	global_load_dwordx4 v[0:3], v[0:1], off
	s_nop 0
	v_addc_co_u32_e32 v47, vcc, 0, v5, vcc
	global_load_ushort v8, v[6:7], off
	global_load_ushort v9, v[6:7], off offset:2048
	global_load_ushort v10, v[12:13], off
	global_load_ushort v11, v[12:13], off offset:2048
	s_nop 0
	global_load_ushort v12, v[14:15], off
	global_load_ushort v13, v[14:15], off offset:2048
	s_nop 0
	global_load_ushort v14, v[46:47], off
	global_load_ushort v15, v[46:47], off offset:2048
	v_add_co_u32_e32 v6, vcc, s80, v4
	s_or_b64 s[20:21], s[20:21], s[52:53]
	s_nop 0
	v_addc_co_u32_e32 v7, vcc, 0, v5, vcc
	v_add_co_u32_e32 v48, vcc, s81, v4
	s_mov_b32 s28, 0
	s_nop 0
	v_addc_co_u32_e32 v49, vcc, 0, v5, vcc
	v_add_co_u32_e32 v50, vcc, s82, v4
	s_movk_i32 s54, 0x1000
	s_nop 0
	v_addc_co_u32_e32 v51, vcc, 0, v5, vcc
	v_add_co_u32_e32 v4, vcc, 0xf000, v4
	s_nop 1
	v_addc_co_u32_e32 v5, vcc, 0, v5, vcc
	global_load_ushort v45, v[6:7], off
	global_load_ushort v46, v[6:7], off offset:2048
	global_load_ushort v47, v[48:49], off
	s_nop 0
	global_load_ushort v48, v[48:49], off offset:2048
	s_nop 0
	global_load_ushort v49, v[50:51], off
	s_nop 0
	global_load_ushort v50, v[50:51], off offset:2048
	s_nop 0
	global_load_ushort v51, v[4:5], off
	global_load_ushort v52, v[4:5], off offset:2048
	v_cndmask_b32_e64 v4, 0, 1, s[44:45]
	v_lshlrev_b32_e32 v24, 6, v4
	v_lshl_add_u64 v[6:7], s[20:21], 0, v[24:25]
	v_lshl_add_u64 v[4:5], v[40:41], 0, s[20:21]
	v_lshl_add_u64 v[6:7], v[42:43], 0, v[6:7]
	s_nop 0
	v_readfirstlane_b32 s88, v4
	v_readfirstlane_b32 s89, v5
	s_nop 3
	v_subrev_u32_e32 v149, s88, v4
	s_add_u32 s88, s88, 0x15800000
	s_addc_u32 s89, s89, 0
	s_add_u32 s56, s88, 0x10000
	s_addc_u32 s57, s89, 0
	global_load_ushort v150, v149, s[56:57]
	global_load_ushort v151, v149, s[56:57] offset:2048
	s_add_u32 s56, s56, 0x1000
	s_addc_u32 s57, s57, 0
	global_load_ushort v152, v149, s[56:57]
	global_load_ushort v153, v149, s[56:57] offset:2048
	s_add_u32 s56, s56, 0x1000
	s_addc_u32 s57, s57, 0
	global_load_ushort v154, v149, s[56:57]
	global_load_ushort v155, v149, s[56:57] offset:2048
	s_add_u32 s56, s56, 0x1000
	s_addc_u32 s57, s57, 0
	global_load_ushort v156, v149, s[56:57]
	global_load_ushort v157, v149, s[56:57] offset:2048
	s_add_u32 s56, s56, 0x1000
	s_addc_u32 s57, s57, 0
	global_load_ushort v158, v149, s[56:57]
	global_load_ushort v159, v149, s[56:57] offset:2048
	s_add_u32 s56, s56, 0x1000
	s_addc_u32 s57, s57, 0
	global_load_ushort v160, v149, s[56:57]
	global_load_ushort v161, v149, s[56:57] offset:2048
	s_add_u32 s56, s56, 0x1000
	s_addc_u32 s57, s57, 0
	global_load_ushort v162, v149, s[56:57]
	global_load_ushort v163, v149, s[56:57] offset:2048
	s_add_u32 s56, s56, 0x1000
	s_addc_u32 s57, s57, 0
	global_load_ushort v164, v149, s[56:57]
	global_load_ushort v165, v149, s[56:57] offset:2048
	s_mov_b64 s[20:21], 0
	s_branch .LBB0_2891

; #define LAS __attribute__((address_space(3)))
; __device__ __forceinline__ void scan_phase2(LAS unsigned char* lds, const int wid, const bf16_t* R, const bf16_t* K, const bf16_t* V, const bf16_t* W, const bf16_t* A,
;                                             const float* k_k, const float* k_a, const float* r_k, bf16_t* Y, float* BON) {
;     ...
;             for (int it = 0; it < NCH + 2; ++it) {
;                 if (it < NCH) {
;                     LAS unsigned char* vt = lds + L_P + (it % 3) * P_SIZE + P_VT + (v8 * 20 + j) * 2;
.LBB0_2891:
	s_cmpk_gt_u32 s28, 0xff
	s_cbranch_scc1 .LBB0_2890
	s_mul_i32 s0, s28, 0xab
	s_bfe_u32 s0, s0, 0x70009
	s_mul_i32 s0, s0, 3
	s_sub_i32 s0, s28, s0
	s_and_b32 s0, s0, 0xff
	s_mulk_i32 s0, 0x3e00
	v_add_u32_e32 v24, s0, v115
	s_cmpk_gt_u32 s28, 0xfd
	s_cbranch_scc1 .Lw7b_w0
	s_waitcnt vmcnt(16)
	s_branch .Lw7b_vt

; #define LAS __attribute__((address_space(3)))
; #define GAS __attribute__((address_space(1)))
; __device__ __forceinline__ void scan_phase2(LAS unsigned char* lds, const int wid, const bf16_t* R, const bf16_t* K, const bf16_t* V, const bf16_t* W, const bf16_t* A,
;                                             const float* k_k, const float* k_a, const float* r_k, bf16_t* Y, float* BON) {
;     ...
;                 if (it < NCH) {
;                     LAS unsigned char* vt = lds + L_P + (it % 3) * P_SIZE + P_VT + (v8 * 20 + j) * 2;
;                     *(LAS bf16_t*)(vt + 0 * 40) = (bf16_t)(vr.x & 0xffff); *(LAS bf16_t*)(vt + 1 * 40) = (bf16_t)(vr.x >> 16);
;                     *(LAS bf16_t*)(vt + 2 * 40) = (bf16_t)(vr.y & 0xffff); *(LAS bf16_t*)(vt + 3 * 40) = (bf16_t)(vr.y >> 16);
;                     *(LAS bf16_t*)(vt + 4 * 40) = (bf16_t)(vr.z & 0xffff); *(LAS bf16_t*)(vt + 5 * 40) = (bf16_t)(vr.z >> 16);
;                     *(LAS bf16_t*)(vt + 6 * 40) = (bf16_t)(vr.w & 0xffff); *(LAS bf16_t*)(vt + 7 * 40) = (bf16_t)(vr.w >> 16);
;                 }
;                 if (it + 1 < NCH) {
;                     LAS float* CEn = (LAS float*)(lds + L_CE + ((it + 1) & 1) * 4096);
;                     float c = 0.f;
; #pragma unroll
;                     for (int i = 0; i < 16; ++i) { c += __uint_as_float((unsigned)ewl[i] << 16); CEn[i * 64 + lane] = c; }
;                     vr = *(const GAS u32x4*)(V + gv + (size_t)(it + 1) * CL * D);
;                 }
;                 if (it + 2 < NCH) {
; #pragma unroll
;                     for (int i = 0; i < 16; ++i) ewl[i] = Wl[(size_t)((it + 2) * CL + i) * D];
;                 }
.Lw7b_vt:
	ds_write_b16 v24, v0 offset:14336
	ds_write_b16_d16_hi v24, v0 offset:14376
	ds_write_b16 v24, v1 offset:14416
	ds_write_b16_d16_hi v24, v1 offset:14456
	ds_write_b16 v24, v2 offset:14496
	ds_write_b16_d16_hi v24, v2 offset:14536
	ds_write_b16 v24, v3 offset:14576
	ds_write_b16_d16_hi v24, v3 offset:14616
	s_cmpk_gt_u32 s28, 0xfe
	s_cbranch_scc1 .LBB0_2890
	v_lshl_add_u64 v[0:1], v[6:7], 0, s[20:21]
	global_load_dwordx4 v[0:3], v[0:1], off
	s_and_b32 s0, s54, 0x1000
	v_add_u32_e32 v24, s0, v68
	s_add_u32 s56, s88, s20
	s_addc_u32 s57, s89, s21
	s_add_u32 s56, s56, 0x18000
	s_addc_u32 s57, s57, 0
	s_bitcmp1_b32 s28, 0
	s_cbranch_scc1 .Lw7b_odd
	v_lshlrev_b32_e32 v53, 16, v8
	v_add_f32_e32 v53, 0, v53
	v_lshlrev_b32_e32 v54, 16, v9
	v_add_f32_e32 v54, v53, v54
	ds_write2st64_b32 v24, v53, v54 offset0:229 offset1:230
	v_lshlrev_b32_e32 v53, 16, v10
	v_add_f32_e32 v53, v54, v53
	v_lshlrev_b32_e32 v54, 16, v11
	v_add_f32_e32 v54, v53, v54
	ds_write2st64_b32 v24, v53, v54 offset0:231 offset1:232
	v_lshlrev_b32_e32 v53, 16, v12
	v_add_f32_e32 v53, v54, v53
	v_lshlrev_b32_e32 v54, 16, v13
	v_add_f32_e32 v54, v53, v54
	ds_write2st64_b32 v24, v53, v54 offset0:233 offset1:234
	v_lshlrev_b32_e32 v53, 16, v14
	v_add_f32_e32 v53, v54, v53
	v_lshlrev_b32_e32 v54, 16, v15
	v_add_f32_e32 v54, v53, v54
	ds_write2st64_b32 v24, v53, v54 offset0:235 offset1:236
	v_lshlrev_b32_e32 v53, 16, v45
	v_add_f32_e32 v53, v54, v53
	v_lshlrev_b32_e32 v54, 16, v46
	v_add_f32_e32 v54, v53, v54
	ds_write2st64_b32 v24, v53, v54 offset0:237 offset1:238
	v_lshlrev_b32_e32 v53, 16, v47
	v_add_f32_e32 v53, v54, v53
	v_lshlrev_b32_e32 v54, 16, v48
	v_add_f32_e32 v54, v53, v54
	ds_write2st64_b32 v24, v53, v54 offset0:239 offset1:240
	v_lshlrev_b32_e32 v53, 16, v49
	v_add_f32_e32 v53, v54, v53
	v_lshlrev_b32_e32 v54, 16, v50
	v_add_f32_e32 v54, v53, v54
	ds_write2st64_b32 v24, v53, v54 offset0:241 offset1:242
	v_lshlrev_b32_e32 v53, 16, v51
	v_add_f32_e32 v53, v54, v53
	v_lshlrev_b32_e32 v54, 16, v52
	v_add_f32_e32 v54, v53, v54
	ds_write2st64_b32 v24, v53, v54 offset0:243 offset1:244
	s_cmpk_gt_u32 s28, 0xfc
	s_cbranch_scc1 .LBB0_2890
	global_load_ushort v8, v149, s[56:57]
	global_load_ushort v9, v149, s[56:57] offset:2048
	s_add_u32 s56, s56, 0x1000
	s_addc_u32 s57, s57, 0
	global_load_ushort v10, v149, s[56:57]
	global_load_ushort v11, v149, s[56:57] offset:2048
	s_add_u32 s56, s56, 0x1000
	s_addc_u32 s57, s57, 0
	global_load_ushort v12, v149, s[56:57]
	global_load_ushort v13, v149, s[56:57] offset:2048
	s_add_u32 s56, s56, 0x1000
	s_addc_u32 s57, s57, 0
	global_load_ushort v14, v149, s[56:57]
	global_load_ushort v15, v149, s[56:57] offset:2048
	s_add_u32 s56, s56, 0x1000
	s_addc_u32 s57, s57, 0
	global_load_ushort v45, v149, s[56:57]
	global_load_ushort v46, v149, s[56:57] offset:2048
	s_add_u32 s56, s56, 0x1000
	s_addc_u32 s57, s57, 0
	global_load_ushort v47, v149, s[56:57]
	global_load_ushort v48, v149, s[56:57] offset:2048
	s_add_u32 s56, s56, 0x1000
	s_addc_u32 s57, s57, 0
	global_load_ushort v49, v149, s[56:57]
	global_load_ushort v50, v149, s[56:57] offset:2048
	s_add_u32 s56, s56, 0x1000
	s_addc_u32 s57, s57, 0
	global_load_ushort v51, v149, s[56:57]
	global_load_ushort v52, v149, s[56:57] offset:2048
	s_branch .LBB0_2890
.Lw7b_odd:
	v_lshlrev_b32_e32 v53, 16, v150
	v_add_f32_e32 v53, 0, v53
	v_lshlrev_b32_e32 v54, 16, v151
	v_add_f32_e32 v54, v53, v54
	ds_write2st64_b32 v24, v53, v54 offset0:229 offset1:230
	v_lshlrev_b32_e32 v53, 16, v152
	v_add_f32_e32 v53, v54, v53
	v_lshlrev_b32_e32 v54, 16, v153
	v_add_f32_e32 v54, v53, v54
	ds_write2st64_b32 v24, v53, v54 offset0:231 offset1:232
	v_lshlrev_b32_e32 v53, 16, v154
	v_add_f32_e32 v53, v54, v53
	v_lshlrev_b32_e32 v54, 16, v155
	v_add_f32_e32 v54, v53, v54
	ds_write2st64_b32 v24, v53, v54 offset0:233 offset1:234
	v_lshlrev_b32_e32 v53, 16, v156
	v_add_f32_e32 v53, v54, v53
	v_lshlrev_b32_e32 v54, 16, v157
	v_add_f32_e32 v54, v53, v54
	ds_write2st64_b32 v24, v53, v54 offset0:235 offset1:236
	v_lshlrev_b32_e32 v53, 16, v158
	v_add_f32_e32 v53, v54, v53
	v_lshlrev_b32_e32 v54, 16, v159
	v_add_f32_e32 v54, v53, v54
	ds_write2st64_b32 v24, v53, v54 offset0:237 offset1:238
	v_lshlrev_b32_e32 v53, 16, v160
	v_add_f32_e32 v53, v54, v53
	v_lshlrev_b32_e32 v54, 16, v161
	v_add_f32_e32 v54, v53, v54
	ds_write2st64_b32 v24, v53, v54 offset0:239 offset1:240
	v_lshlrev_b32_e32 v53, 16, v162
	v_add_f32_e32 v53, v54, v53
	v_lshlrev_b32_e32 v54, 16, v163
	v_add_f32_e32 v54, v53, v54
	ds_write2st64_b32 v24, v53, v54 offset0:241 offset1:242
	v_lshlrev_b32_e32 v53, 16, v164
	v_add_f32_e32 v53, v54, v53
	v_lshlrev_b32_e32 v54, 16, v165
	v_add_f32_e32 v54, v53, v54
	ds_write2st64_b32 v24, v53, v54 offset0:243 offset1:244
	s_cmpk_gt_u32 s28, 0xfc
	s_cbranch_scc1 .LBB0_2890
	global_load_ushort v150, v149, s[56:57]
	global_load_ushort v151, v149, s[56:57] offset:2048
	s_add_u32 s56, s56, 0x1000
	s_addc_u32 s57, s57, 0
	global_load_ushort v152, v149, s[56:57]
	global_load_ushort v153, v149, s[56:57] offset:2048
	s_add_u32 s56, s56, 0x1000
	s_addc_u32 s57, s57, 0
	global_load_ushort v154, v149, s[56:57]
	global_load_ushort v155, v149, s[56:57] offset:2048
	s_add_u32 s56, s56, 0x1000
	s_addc_u32 s57, s57, 0
	global_load_ushort v156, v149, s[56:57]
	global_load_ushort v157, v149, s[56:57] offset:2048
	s_add_u32 s56, s56, 0x1000
	s_addc_u32 s57, s57, 0
	global_load_ushort v158, v149, s[56:57]
	global_load_ushort v159, v149, s[56:57] offset:2048
	s_add_u32 s56, s56, 0x1000
	s_addc_u32 s57, s57, 0
	global_load_ushort v160, v149, s[56:57]
	global_load_ushort v161, v149, s[56:57] offset:2048
	s_add_u32 s56, s56, 0x1000
	s_addc_u32 s57, s57, 0
	global_load_ushort v162, v149, s[56:57]
	global_load_ushort v163, v149, s[56:57] offset:2048
	s_add_u32 s56, s56, 0x1000
	s_addc_u32 s57, s57, 0
	global_load_ushort v164, v149, s[56:57]
	global_load_ushort v165, v149, s[56:57] offset:2048
	s_branch .LBB0_2890
